# NSA tile loops: first PV V-fragment reads hoisted above the P permlane block; redundant post-barrier lgkmcnt(0) waits dropped in GEMM K-loops
# speedup vs baseline: 1.0050x; 1.0020x over previous
; #define PG8_STAGE(bufoff, gbase, voff) do { _Pragma("unroll") for (int _i = 0; _i < 2; ++_i) \
;         __builtin_amdgcn_global_load_lds((const unsigned*)((const char*)(gbase) + (voff)[_i]), (LAS unsigned*)(lds + (bufoff) + ldsw + _i * 8192), 16, 0, 0); } while (0)
; #define PG8_LDA(dst, b, h) do { _Pragma("unroll") for (int m = 0; m < 4; ++m) _Pragma("unroll") for (int k = 0; k < 2; ++k) dst[m][k] = *(const LAS bf16x8*)(lds + PG8_SA(b, h) + aoff + m * 2048 + k * 1024); } while (0)
; #define PG8_LDB(dst, b, h) do { _Pragma("unroll") for (int n = 0; n < 2; ++n) _Pragma("unroll") for (int k = 0; k < 2; ++k) dst[n][k] = *(const LAS bf16x8*)(lds + PG8_SB(b, h) + boff + n * 2048 + k * 1024); } while (0)
; #define PG8_WAIT_V(n) asm volatile("s_waitcnt vmcnt(" #n ")" ::: "memory")
; #define PG8_WAIT_L(n) asm volatile("s_waitcnt lgkmcnt(" #n ")" ::: "memory")
; #define PG8_BAR __builtin_amdgcn_s_barrier()
; #define PG8_SCHED __builtin_amdgcn_sched_barrier(0)
; template <class Epi, class Sched, int KC, bool ALIGN_EPI = false, bool SP2 = false, bool ATILED = false>
; __device__ __forceinline__ void gemm_phase(LAS unsigned char* lds, const Gemm g, const Sched& S, const Epi& E, int wave_s) {
;     ...
;         const bool has_next = S.next(ui + 1, nxt);
;         const char* nA = has_next ? (const char*)g.A + (size_t)nxt.pm * tstepA : cA; const char* nB = has_next ? (const char*)g.Bt + (size_t)nxt.pn * tstep : cB;
;         for (int t = 0; t < nt; t += 2) {
;             const bool last = (t == nt - 2);
;             const char* a1 = cA + PG8_AOFF(t + 1);
;             const char* a2 = last ? nA : cA + PG8_AOFF(t + 2); const char* b2 = last ? nB : cB + (size_t)(t + 2) * kstep;
;             const char* a3 = a2 + kstep; const char* b3 = b2 + kstep;
;             if (last && has_next) S.a_ready(nxt);
;             if constexpr (SP2) {
;             PG8_LDB(B0, 0, 0); PG8_LDB(B1, 0, 1); PG8_SCHED; PG8_LDA(At, 0, 0); PG8_STAGE(PG8_SA(1, 1), a1 + hstepA, voffA);
;             PG8_WAIT_V(8); PG8_WAIT_L(0); PG8_BAR; PG8_MMA(0, 0, At, B0); PG8_MMA(0, 1, At, B1); PG8_BAR; PG8_SCHED;
;     ...
; #pragma unroll
;         for (int a = 0; a < 2; ++a)
; #pragma unroll
;             for (int b = 0; b < 2; ++b)
; #pragma unroll
;                 for (int m = 0; m < 4; ++m)
; #pragma unroll
;                     for (int n = 0; n < 2; ++n) acc[a][b][m][n] = (f32x4){0.f, 0.f, 0.f, 0.f};
.LBB0_232:
	s_ashr_i32 s19, s18, 31
	s_lshl_b64 s[20:21], s[18:19], 17
	s_add_u32 s20, s39, s20
	s_addc_u32 s21, s40, s21
	s_and_b64 s[22:23], s[6:7], exec
	s_cselect_b32 s19, s21, s27
	s_cselect_b32 s53, s20, s26
	s_ashr_i32 s17, s16, 31
	s_lshl_b64 s[22:23], s[16:17], 20
	s_add_u32 s22, s41, s22
	s_addc_u32 s23, s42, s23
	s_and_b64 s[30:31], s[6:7], exec
	s_cselect_b32 s17, s23, s29
	s_cselect_b32 s54, s22, s28
	s_add_u32 s55, s28, 0x100
	v_mov_b32_e32 v2, 0
	s_addc_u32 s56, s29, 0
	s_mov_b32 s57, -2
	s_mov_b64 s[28:29], 0
	s_mov_b32 s58, 0x400000
	v_mov_b32_e32 v3, v2
	v_mov_b32_e32 v4, v2
	v_mov_b32_e32 v5, v2
	v_mov_b32_e32 v14, v2
	v_mov_b32_e32 v15, v2
	v_mov_b32_e32 v16, v2
	v_mov_b32_e32 v17, v2
	v_mov_b32_e32 v22, v2
	v_mov_b32_e32 v23, v2
	v_mov_b32_e32 v24, v2
	v_mov_b32_e32 v25, v2
	v_mov_b32_e32 v30, v2
	v_mov_b32_e32 v31, v2
	v_mov_b32_e32 v32, v2
	v_mov_b32_e32 v33, v2
	v_mov_b32_e32 v38, v2
	v_mov_b32_e32 v39, v2
	v_mov_b32_e32 v40, v2
	v_mov_b32_e32 v41, v2
	v_mov_b32_e32 v46, v2
	v_mov_b32_e32 v47, v2
	v_mov_b32_e32 v48, v2
	v_mov_b32_e32 v49, v2
	v_mov_b32_e32 v54, v2
	v_mov_b32_e32 v55, v2
	v_mov_b32_e32 v56, v2
	v_mov_b32_e32 v57, v2
	v_mov_b32_e32 v62, v2
	v_mov_b32_e32 v63, v2
	v_mov_b32_e32 v64, v2
	v_mov_b32_e32 v65, v2
	v_mov_b32_e32 v6, v2
	v_mov_b32_e32 v7, v2
	v_mov_b32_e32 v8, v2
	v_mov_b32_e32 v9, v2
	v_mov_b32_e32 v10, v2
	v_mov_b32_e32 v11, v2
	v_mov_b32_e32 v12, v2
	v_mov_b32_e32 v13, v2
	v_mov_b32_e32 v18, v2
	v_mov_b32_e32 v19, v2
	v_mov_b32_e32 v20, v2
	v_mov_b32_e32 v21, v2
	v_mov_b32_e32 v26, v2
	v_mov_b32_e32 v27, v2
	v_mov_b32_e32 v28, v2
	v_mov_b32_e32 v29, v2
	v_mov_b32_e32 v34, v2
	v_mov_b32_e32 v35, v2
	v_mov_b32_e32 v36, v2
	v_mov_b32_e32 v37, v2
	v_mov_b32_e32 v42, v2
	v_mov_b32_e32 v43, v2
	v_mov_b32_e32 v44, v2
	v_mov_b32_e32 v45, v2
	v_mov_b32_e32 v50, v2
	v_mov_b32_e32 v51, v2
	v_mov_b32_e32 v52, v2
	v_mov_b32_e32 v53, v2
	v_mov_b32_e32 v58, v2
	v_mov_b32_e32 v59, v2
	v_mov_b32_e32 v60, v2
	v_mov_b32_e32 v61, v2
	v_mov_b32_e32 v70, v2
	v_mov_b32_e32 v71, v2
	v_mov_b32_e32 v72, v2
	v_mov_b32_e32 v73, v2
	v_mov_b32_e32 v78, v2
	v_mov_b32_e32 v79, v2
	v_mov_b32_e32 v80, v2
	v_mov_b32_e32 v81, v2
	v_mov_b32_e32 v86, v2
	v_mov_b32_e32 v87, v2
	v_mov_b32_e32 v88, v2
	v_mov_b32_e32 v89, v2
	v_mov_b32_e32 v94, v2
	v_mov_b32_e32 v95, v2
	v_mov_b32_e32 v96, v2
	v_mov_b32_e32 v97, v2
	v_mov_b32_e32 v102, v2
	v_mov_b32_e32 v103, v2
	v_mov_b32_e32 v104, v2
	v_mov_b32_e32 v105, v2
	v_mov_b32_e32 v110, v2
	v_mov_b32_e32 v111, v2
	v_mov_b32_e32 v112, v2
	v_mov_b32_e32 v113, v2
	v_mov_b32_e32 v118, v2
	v_mov_b32_e32 v119, v2
	v_mov_b32_e32 v120, v2
	v_mov_b32_e32 v121, v2
	v_mov_b32_e32 v126, v2
	v_mov_b32_e32 v127, v2
	v_mov_b32_e32 v128, v2
	v_mov_b32_e32 v129, v2
	v_mov_b32_e32 v66, v2
	v_mov_b32_e32 v67, v2
	v_mov_b32_e32 v68, v2
	v_mov_b32_e32 v69, v2
	v_mov_b32_e32 v74, v2
	v_mov_b32_e32 v75, v2
	v_mov_b32_e32 v76, v2
	v_mov_b32_e32 v77, v2
	v_mov_b32_e32 v82, v2
	v_mov_b32_e32 v83, v2
	v_mov_b32_e32 v84, v2
	v_mov_b32_e32 v85, v2
	v_mov_b32_e32 v90, v2
	v_mov_b32_e32 v91, v2
	v_mov_b32_e32 v92, v2
	v_mov_b32_e32 v93, v2
	v_mov_b32_e32 v98, v2
	v_mov_b32_e32 v99, v2
	v_mov_b32_e32 v100, v2
	v_mov_b32_e32 v101, v2
	v_mov_b32_e32 v106, v2
	v_mov_b32_e32 v107, v2
	v_mov_b32_e32 v108, v2
	v_mov_b32_e32 v109, v2
	v_mov_b32_e32 v114, v2
	v_mov_b32_e32 v115, v2
	v_mov_b32_e32 v116, v2
	v_mov_b32_e32 v117, v2
	v_mov_b32_e32 v122, v2
	v_mov_b32_e32 v123, v2
	v_mov_b32_e32 v124, v2
	v_mov_b32_e32 v125, v2
	s_add_i32 s30, s58, 0xffc00000
	s_and_b32 s30, s30, 0x3800000
	s_and_b32 s31, s28, 0x100
	s_or_b32 s59, s31, s30
	s_and_b32 s34, s58, 0x7800000
	s_add_u32 s30, s28, 0x100
	s_addc_u32 s31, s29, 0
	s_and_b32 s35, s30, 0x100
	s_or_b32 s34, s34, s35
	s_add_u32 s34, s26, s34
	s_addc_u32 s35, s27, 0
	s_add_u32 s28, s55, s28
	s_addc_u32 s29, s56, s29
	s_add_i32 s62, 0, 0x10000
	s_cmp_eq_u32 s57, 28
	s_cselect_b32 s35, s19, s35
	s_cselect_b32 s34, s53, s34
	v_add_u32_e32 v139, s62, v163
	s_cselect_b32 s29, s17, s29
	s_cselect_b32 s28, s54, s28
	s_add_i32 s63, 0, 0x14000
	ds_read_b128 v[152:155], v139
	ds_read_b128 v[156:159], v139 offset:1024
	ds_read_b128 v[168:171], v139 offset:2048
	ds_read_b128 v[172:175], v139 offset:3072
	v_add_u32_e32 v139, s63, v163
	ds_read_b128 v[176:179], v139
	ds_read_b128 v[180:183], v139 offset:1024
	ds_read_b128 v[184:187], v139 offset:2048
	ds_read_b128 v[188:191], v139 offset:3072
	s_add_u32 s59, s26, s59
	s_addc_u32 s61, s27, 0
	s_add_u32 s60, s59, 0x10080
	s_addc_u32 s61, s61, 0
	s_add_i32 m0, s44, 0xc000
	ds_read_b128 v[198:201], v166
	ds_read_b128 v[202:205], v166 offset:1024
	ds_read_b128 v[206:209], v166 offset:2048
	ds_read_b128 v[210:213], v166 offset:3072
	ds_read_b128 v[214:217], v166 offset:4096
	ds_read_b128 v[218:221], v166 offset:5120
	ds_read_b128 v[222:225], v166 offset:6144
	ds_read_b128 v[226:229], v166 offset:7168
	global_load_lds_dwordx4 v136, s[60:61]
	s_add_i32 m0, s44, 0xe000
	s_nop 0
	global_load_lds_dwordx4 v132, s[60:61]
	s_waitcnt vmcnt(16)
	s_waitcnt lgkmcnt(0)
	s_barrier
; #define PG8_STAGE(bufoff, gbase, voff) do { _Pragma("unroll") for (int _i = 0; _i < 2; ++_i) \
;         __builtin_amdgcn_global_load_lds((const unsigned*)((const char*)(gbase) + (voff)[_i]), (LAS unsigned*)(lds + (bufoff) + ldsw + _i * 8192), 16, 0, 0); } while (0)
; #define PG8_LDA(dst, b, h) do { _Pragma("unroll") for (int m = 0; m < 4; ++m) _Pragma("unroll") for (int k = 0; k < 2; ++k) dst[m][k] = *(const LAS bf16x8*)(lds + PG8_SA(b, h) + aoff + m * 2048 + k * 1024); } while (0)
; #define PG8_MMA(ai, bj, At, Bt) do { __builtin_amdgcn_s_setprio(1); _Pragma("unroll") for (int m = 0; m < 4; ++m) _Pragma("unroll") for (int n = 0; n < 2; ++n) _Pragma("unroll") for (int k = 0; k < 2; ++k) \
;         acc[ai][bj][m][n] = __builtin_amdgcn_mfma_f32_16x16x32_bf16(Bt[n][k], At[m][k], acc[ai][bj][m][n], 0, 0, 0); __builtin_amdgcn_s_setprio(0); } while (0)
; #define PG8_WAIT_V(n) asm volatile("s_waitcnt vmcnt(" #n ")" ::: "memory")
; #define PG8_WAIT_L(n) asm volatile("s_waitcnt lgkmcnt(" #n ")" ::: "memory")
; #define PG8_BAR __builtin_amdgcn_s_barrier()
; #define PG8_SCHED __builtin_amdgcn_sched_barrier(0)
; template <class Epi, class Sched, int KC, bool ALIGN_EPI = false, bool SP2 = false, bool ATILED = false>
; __device__ __forceinline__ void gemm_phase(LAS unsigned char* lds, const Gemm g, const Sched& S, const Epi& E, int wave_s) {
;     ...
;             PG8_WAIT_V(8); PG8_WAIT_L(0); PG8_BAR; PG8_MMA(0, 0, At, B0); PG8_MMA(0, 1, At, B1); PG8_BAR; PG8_SCHED;
;             PG8_LDA(At, 0, 1); PG8_STAGE(PG8_SB(0, 0), b2, voffB); PG8_STAGE(PG8_SB(0, 1), b2 + hstepB, voffB); PG8_STAGE(PG8_SA(0, 0), a2, voffA);
;             PG8_WAIT_V(8); PG8_WAIT_L(0); PG8_BAR; PG8_MMA(1, 0, At, B0); PG8_MMA(1, 1, At, B1); PG8_BAR; PG8_SCHED;
	v_mfma_f32_16x16x32_bf16 v[122:125], v[152:155], v[198:201], v[122:125]
	v_mfma_f32_16x16x32_bf16 v[114:117], v[168:171], v[198:201], v[114:117]
	v_mfma_f32_16x16x32_bf16 v[106:109], v[152:155], v[206:209], v[106:109]
	v_mfma_f32_16x16x32_bf16 v[98:101], v[168:171], v[206:209], v[98:101]
	v_mfma_f32_16x16x32_bf16 v[90:93], v[152:155], v[214:217], v[90:93]
	v_mfma_f32_16x16x32_bf16 v[82:85], v[168:171], v[214:217], v[82:85]
	v_mfma_f32_16x16x32_bf16 v[74:77], v[152:155], v[222:225], v[74:77]
	v_mfma_f32_16x16x32_bf16 v[66:69], v[168:171], v[222:225], v[66:69]
	v_mfma_f32_16x16x32_bf16 v[122:125], v[156:159], v[202:205], v[122:125]
	v_mfma_f32_16x16x32_bf16 v[114:117], v[172:175], v[202:205], v[114:117]
	v_mfma_f32_16x16x32_bf16 v[106:109], v[156:159], v[210:213], v[106:109]
	v_mfma_f32_16x16x32_bf16 v[98:101], v[172:175], v[210:213], v[98:101]
	v_mfma_f32_16x16x32_bf16 v[90:93], v[156:159], v[218:221], v[90:93]
	v_mfma_f32_16x16x32_bf16 v[82:85], v[172:175], v[218:221], v[82:85]
	v_mfma_f32_16x16x32_bf16 v[74:77], v[156:159], v[226:229], v[74:77]
	v_mfma_f32_16x16x32_bf16 v[66:69], v[172:175], v[226:229], v[66:69]
	v_mfma_f32_16x16x32_bf16 v[126:129], v[176:179], v[198:201], v[126:129]
	v_mfma_f32_16x16x32_bf16 v[118:121], v[184:187], v[198:201], v[118:121]
	v_mfma_f32_16x16x32_bf16 v[110:113], v[176:179], v[206:209], v[110:113]
	v_mfma_f32_16x16x32_bf16 v[102:105], v[184:187], v[206:209], v[102:105]
	v_mfma_f32_16x16x32_bf16 v[94:97], v[176:179], v[214:217], v[94:97]
	v_mfma_f32_16x16x32_bf16 v[86:89], v[184:187], v[214:217], v[86:89]
	v_mfma_f32_16x16x32_bf16 v[78:81], v[176:179], v[222:225], v[78:81]
	v_mfma_f32_16x16x32_bf16 v[70:73], v[184:187], v[222:225], v[70:73]
	v_mfma_f32_16x16x32_bf16 v[126:129], v[180:183], v[202:205], v[126:129]
	v_mfma_f32_16x16x32_bf16 v[118:121], v[188:191], v[202:205], v[118:121]
	v_mfma_f32_16x16x32_bf16 v[110:113], v[180:183], v[210:213], v[110:113]
	v_mfma_f32_16x16x32_bf16 v[102:105], v[188:191], v[210:213], v[102:105]
	v_mfma_f32_16x16x32_bf16 v[94:97], v[180:183], v[218:221], v[94:97]
	v_mfma_f32_16x16x32_bf16 v[86:89], v[188:191], v[218:221], v[86:89]
	v_mfma_f32_16x16x32_bf16 v[78:81], v[180:183], v[226:229], v[78:81]
	v_mfma_f32_16x16x32_bf16 v[70:73], v[188:191], v[226:229], v[70:73]
	s_barrier
	s_add_u32 s100, s34, 0x80
	s_addc_u32 s101, s35, 0
	s_add_i32 s59, s62, s38
	s_mov_b32 m0, s59
	ds_read_b128 v[198:201], v166 offset:16384
	ds_read_b128 v[202:205], v166 offset:17408
	ds_read_b128 v[206:209], v166 offset:18432
	ds_read_b128 v[210:213], v166 offset:19456
	ds_read_b128 v[214:217], v166 offset:20480
	ds_read_b128 v[218:221], v166 offset:21504
	ds_read_b128 v[222:225], v166 offset:22528
	ds_read_b128 v[226:229], v166 offset:23552
	global_load_lds_dwordx4 v134, s[28:29]
	s_add_i32 m0, s59, 0x2000
	s_add_u32 s60, s28, 0x80000
	s_addc_u32 s61, s29, 0
	s_add_i32 s59, s63, s38
	global_load_lds_dwordx4 v130, s[28:29]
	s_mov_b32 m0, s59
	s_nop 0
	global_load_lds_dwordx4 v134, s[60:61]
	s_add_i32 m0, s59, 0x2000
	s_nop 0
	global_load_lds_dwordx4 v130, s[60:61]
	s_mov_b32 m0, s44
	s_nop 0
	global_load_lds_dwordx4 v136, s[34:35]
	s_mov_b32 m0, s45
	s_nop 0
	global_load_lds_dwordx4 v132, s[34:35]
	s_waitcnt vmcnt(16)
	s_waitcnt lgkmcnt(0)
	s_barrier
	v_mfma_f32_16x16x32_bf16 v[58:61], v[152:155], v[198:201], v[58:61]
	v_mfma_f32_16x16x32_bf16 v[50:53], v[168:171], v[198:201], v[50:53]
	v_mfma_f32_16x16x32_bf16 v[42:45], v[152:155], v[206:209], v[42:45]
	v_mfma_f32_16x16x32_bf16 v[34:37], v[168:171], v[206:209], v[34:37]
	v_mfma_f32_16x16x32_bf16 v[26:29], v[152:155], v[214:217], v[26:29]
	v_mfma_f32_16x16x32_bf16 v[18:21], v[168:171], v[214:217], v[18:21]
	v_mfma_f32_16x16x32_bf16 v[10:13], v[152:155], v[222:225], v[10:13]
	v_mfma_f32_16x16x32_bf16 v[6:9], v[168:171], v[222:225], v[6:9]
	v_mfma_f32_16x16x32_bf16 v[58:61], v[156:159], v[202:205], v[58:61]
	v_mfma_f32_16x16x32_bf16 v[50:53], v[172:175], v[202:205], v[50:53]
	v_mfma_f32_16x16x32_bf16 v[42:45], v[156:159], v[210:213], v[42:45]
	v_mfma_f32_16x16x32_bf16 v[34:37], v[172:175], v[210:213], v[34:37]
	v_mfma_f32_16x16x32_bf16 v[26:29], v[156:159], v[218:221], v[26:29]
	v_mfma_f32_16x16x32_bf16 v[18:21], v[172:175], v[218:221], v[18:21]
	v_mfma_f32_16x16x32_bf16 v[10:13], v[156:159], v[226:229], v[10:13]
	v_mfma_f32_16x16x32_bf16 v[6:9], v[172:175], v[226:229], v[6:9]
	v_mfma_f32_16x16x32_bf16 v[62:65], v[176:179], v[198:201], v[62:65]
	v_mfma_f32_16x16x32_bf16 v[54:57], v[184:187], v[198:201], v[54:57]
	v_mfma_f32_16x16x32_bf16 v[46:49], v[176:179], v[206:209], v[46:49]
	v_mfma_f32_16x16x32_bf16 v[38:41], v[184:187], v[206:209], v[38:41]
	v_mfma_f32_16x16x32_bf16 v[30:33], v[176:179], v[214:217], v[30:33]
	v_mfma_f32_16x16x32_bf16 v[22:25], v[184:187], v[214:217], v[22:25]
	v_mfma_f32_16x16x32_bf16 v[14:17], v[176:179], v[222:225], v[14:17]
	v_mfma_f32_16x16x32_bf16 v[2:5], v[184:187], v[222:225], v[2:5]
	v_mfma_f32_16x16x32_bf16 v[62:65], v[180:183], v[202:205], v[62:65]
	v_mfma_f32_16x16x32_bf16 v[54:57], v[188:191], v[202:205], v[54:57]
	v_mfma_f32_16x16x32_bf16 v[46:49], v[180:183], v[210:213], v[46:49]
	v_mfma_f32_16x16x32_bf16 v[38:41], v[188:191], v[210:213], v[38:41]
	v_mfma_f32_16x16x32_bf16 v[30:33], v[180:183], v[218:221], v[30:33]
	v_mfma_f32_16x16x32_bf16 v[22:25], v[188:191], v[218:221], v[22:25]
	v_mfma_f32_16x16x32_bf16 v[14:17], v[180:183], v[226:229], v[14:17]
	v_mfma_f32_16x16x32_bf16 v[2:5], v[188:191], v[226:229], v[2:5]
	s_barrier
; #define PG8_STAGE(bufoff, gbase, voff) do { _Pragma("unroll") for (int _i = 0; _i < 2; ++_i) \
;         __builtin_amdgcn_global_load_lds((const unsigned*)((const char*)(gbase) + (voff)[_i]), (LAS unsigned*)(lds + (bufoff) + ldsw + _i * 8192), 16, 0, 0); } while (0)
; #define PG8_LDA(dst, b, h) do { _Pragma("unroll") for (int m = 0; m < 4; ++m) _Pragma("unroll") for (int k = 0; k < 2; ++k) dst[m][k] = *(const LAS bf16x8*)(lds + PG8_SA(b, h) + aoff + m * 2048 + k * 1024); } while (0)
; #define PG8_LDB(dst, b, h) do { _Pragma("unroll") for (int n = 0; n < 2; ++n) _Pragma("unroll") for (int k = 0; k < 2; ++k) dst[n][k] = *(const LAS bf16x8*)(lds + PG8_SB(b, h) + boff + n * 2048 + k * 1024); } while (0)
; #define PG8_MMA(ai, bj, At, Bt) do { __builtin_amdgcn_s_setprio(1); _Pragma("unroll") for (int m = 0; m < 4; ++m) _Pragma("unroll") for (int n = 0; n < 2; ++n) _Pragma("unroll") for (int k = 0; k < 2; ++k) \
;         acc[ai][bj][m][n] = __builtin_amdgcn_mfma_f32_16x16x32_bf16(Bt[n][k], At[m][k], acc[ai][bj][m][n], 0, 0, 0); __builtin_amdgcn_s_setprio(0); } while (0)
; #define PG8_WAIT_V(n) asm volatile("s_waitcnt vmcnt(" #n ")" ::: "memory")
; #define PG8_WAIT_L(n) asm volatile("s_waitcnt lgkmcnt(" #n ")" ::: "memory")
; #define PG8_BAR __builtin_amdgcn_s_barrier()
; #define PG8_SCHED __builtin_amdgcn_sched_barrier(0)
; template <class Epi, class Sched, int KC, bool ALIGN_EPI = false, bool SP2 = false, bool ATILED = false>
; __device__ __forceinline__ void gemm_phase(LAS unsigned char* lds, const Gemm g, const Sched& S, const Epi& E, int wave_s) {
;     ...
;             PG8_LDB(B0, 1, 0); PG8_LDB(B1, 1, 1); PG8_SCHED; PG8_LDA(At, 1, 0); PG8_STAGE(PG8_SA(0, 1), a2 + hstepA, voffA);
;             PG8_WAIT_V(8); PG8_WAIT_L(0); PG8_BAR; PG8_MMA(0, 0, At, B0); PG8_MMA(0, 1, At, B1); PG8_BAR; PG8_SCHED;
;             PG8_LDA(At, 1, 1); PG8_STAGE(PG8_SB(1, 0), b3, voffB); PG8_STAGE(PG8_SB(1, 1), b3 + hstepB, voffB); PG8_STAGE(PG8_SA(1, 0), a3, voffA);
;             PG8_WAIT_V(8); PG8_WAIT_L(0); PG8_BAR; PG8_MMA(1, 0, At, B0); PG8_MMA(1, 1, At, B1); PG8_BAR; PG8_SCHED;
	s_add_i32 s59, 0, 0x18000
	v_add_u32_e32 v139, s59, v163
	s_add_i32 s60, 0, 0x1c000
	ds_read_b128 v[152:155], v139
	ds_read_b128 v[156:159], v139 offset:1024
	ds_read_b128 v[168:171], v139 offset:2048
	ds_read_b128 v[172:175], v139 offset:3072
	v_add_u32_e32 v139, s60, v163
	ds_read_b128 v[176:179], v139
	ds_read_b128 v[180:183], v139 offset:1024
	ds_read_b128 v[184:187], v139 offset:2048
	ds_read_b128 v[188:191], v139 offset:3072
	s_add_u32 s34, s34, 0x10000
	s_addc_u32 s35, s35, 0
	s_mov_b32 m0, s46
	ds_read_b128 v[198:201], v166 offset:32768
	ds_read_b128 v[202:205], v166 offset:33792
	ds_read_b128 v[206:209], v166 offset:34816
	ds_read_b128 v[210:213], v166 offset:35840
	ds_read_b128 v[214:217], v166 offset:36864
	ds_read_b128 v[218:221], v166 offset:37888
	ds_read_b128 v[222:225], v166 offset:38912
	ds_read_b128 v[226:229], v166 offset:39936
	global_load_lds_dwordx4 v136, s[34:35]
	s_mov_b32 m0, s47
	s_nop 0
	global_load_lds_dwordx4 v132, s[34:35]
	s_waitcnt vmcnt(8)
	s_waitcnt lgkmcnt(0)
	s_barrier
	v_mfma_f32_16x16x32_bf16 v[122:125], v[152:155], v[198:201], v[122:125]
	v_mfma_f32_16x16x32_bf16 v[114:117], v[168:171], v[198:201], v[114:117]
	v_mfma_f32_16x16x32_bf16 v[106:109], v[152:155], v[206:209], v[106:109]
	v_mfma_f32_16x16x32_bf16 v[98:101], v[168:171], v[206:209], v[98:101]
	v_mfma_f32_16x16x32_bf16 v[90:93], v[152:155], v[214:217], v[90:93]
	v_mfma_f32_16x16x32_bf16 v[82:85], v[168:171], v[214:217], v[82:85]
	v_mfma_f32_16x16x32_bf16 v[74:77], v[152:155], v[222:225], v[74:77]
	v_mfma_f32_16x16x32_bf16 v[66:69], v[168:171], v[222:225], v[66:69]
	v_mfma_f32_16x16x32_bf16 v[122:125], v[156:159], v[202:205], v[122:125]
	v_mfma_f32_16x16x32_bf16 v[114:117], v[172:175], v[202:205], v[114:117]
	v_mfma_f32_16x16x32_bf16 v[106:109], v[156:159], v[210:213], v[106:109]
	v_mfma_f32_16x16x32_bf16 v[98:101], v[172:175], v[210:213], v[98:101]
	v_mfma_f32_16x16x32_bf16 v[90:93], v[156:159], v[218:221], v[90:93]
	v_mfma_f32_16x16x32_bf16 v[82:85], v[172:175], v[218:221], v[82:85]
	v_mfma_f32_16x16x32_bf16 v[74:77], v[156:159], v[226:229], v[74:77]
	v_mfma_f32_16x16x32_bf16 v[66:69], v[172:175], v[226:229], v[66:69]
	v_mfma_f32_16x16x32_bf16 v[126:129], v[176:179], v[198:201], v[126:129]
	v_mfma_f32_16x16x32_bf16 v[118:121], v[184:187], v[198:201], v[118:121]
	v_mfma_f32_16x16x32_bf16 v[110:113], v[176:179], v[206:209], v[110:113]
	v_mfma_f32_16x16x32_bf16 v[102:105], v[184:187], v[206:209], v[102:105]
	v_mfma_f32_16x16x32_bf16 v[94:97], v[176:179], v[214:217], v[94:97]
	v_mfma_f32_16x16x32_bf16 v[86:89], v[184:187], v[214:217], v[86:89]
	v_mfma_f32_16x16x32_bf16 v[78:81], v[176:179], v[222:225], v[78:81]
	v_mfma_f32_16x16x32_bf16 v[70:73], v[184:187], v[222:225], v[70:73]
	v_mfma_f32_16x16x32_bf16 v[126:129], v[180:183], v[202:205], v[126:129]
	v_mfma_f32_16x16x32_bf16 v[118:121], v[188:191], v[202:205], v[118:121]
	v_mfma_f32_16x16x32_bf16 v[110:113], v[180:183], v[210:213], v[110:113]
	v_mfma_f32_16x16x32_bf16 v[102:105], v[188:191], v[210:213], v[102:105]
	v_mfma_f32_16x16x32_bf16 v[94:97], v[180:183], v[218:221], v[94:97]
	v_mfma_f32_16x16x32_bf16 v[86:89], v[188:191], v[218:221], v[86:89]
	v_mfma_f32_16x16x32_bf16 v[78:81], v[180:183], v[226:229], v[78:81]
	v_mfma_f32_16x16x32_bf16 v[70:73], v[188:191], v[226:229], v[70:73]
	s_barrier
	s_add_u32 s98, s28, 0x80
	s_addc_u32 s99, s29, 0
	s_add_i32 s34, s59, s38
	s_mov_b32 m0, s34
	ds_read_b128 v[198:201], v166 offset:49152
	ds_read_b128 v[202:205], v166 offset:50176
	ds_read_b128 v[206:209], v166 offset:51200
	ds_read_b128 v[210:213], v166 offset:52224
	ds_read_b128 v[214:217], v166 offset:53248
	ds_read_b128 v[218:221], v166 offset:54272
	ds_read_b128 v[222:225], v166 offset:55296
	ds_read_b128 v[226:229], v166 offset:56320
	global_load_lds_dwordx4 v134, s[98:99]
	s_add_i32 m0, s34, 0x2000
	s_add_u32 s28, s28, 0x80080
	s_addc_u32 s29, s29, 0
	s_add_i32 s34, s60, s38
	global_load_lds_dwordx4 v130, s[98:99]
	s_mov_b32 m0, s34
	s_nop 0
	global_load_lds_dwordx4 v134, s[28:29]
	s_add_i32 m0, s34, 0x2000
	s_nop 0
	global_load_lds_dwordx4 v130, s[28:29]
	s_mov_b32 m0, s48
	s_nop 0
	global_load_lds_dwordx4 v136, s[100:101]
	s_mov_b32 m0, s49
	s_nop 0
	global_load_lds_dwordx4 v132, s[100:101]
	s_waitcnt vmcnt(8)
	s_waitcnt lgkmcnt(0)
	s_barrier
	v_mfma_f32_16x16x32_bf16 v[58:61], v[152:155], v[198:201], v[58:61]
	v_mfma_f32_16x16x32_bf16 v[50:53], v[168:171], v[198:201], v[50:53]
	v_mfma_f32_16x16x32_bf16 v[42:45], v[152:155], v[206:209], v[42:45]
	v_mfma_f32_16x16x32_bf16 v[34:37], v[168:171], v[206:209], v[34:37]
	v_mfma_f32_16x16x32_bf16 v[26:29], v[152:155], v[214:217], v[26:29]
	v_mfma_f32_16x16x32_bf16 v[18:21], v[168:171], v[214:217], v[18:21]
	v_mfma_f32_16x16x32_bf16 v[10:13], v[152:155], v[222:225], v[10:13]
	v_mfma_f32_16x16x32_bf16 v[6:9], v[168:171], v[222:225], v[6:9]
	v_mfma_f32_16x16x32_bf16 v[58:61], v[156:159], v[202:205], v[58:61]
	v_mfma_f32_16x16x32_bf16 v[50:53], v[172:175], v[202:205], v[50:53]
	v_mfma_f32_16x16x32_bf16 v[42:45], v[156:159], v[210:213], v[42:45]
	v_mfma_f32_16x16x32_bf16 v[34:37], v[172:175], v[210:213], v[34:37]
	v_mfma_f32_16x16x32_bf16 v[26:29], v[156:159], v[218:221], v[26:29]
	v_mfma_f32_16x16x32_bf16 v[18:21], v[172:175], v[218:221], v[18:21]
	v_mfma_f32_16x16x32_bf16 v[10:13], v[156:159], v[226:229], v[10:13]
	v_mfma_f32_16x16x32_bf16 v[6:9], v[172:175], v[226:229], v[6:9]
	v_mfma_f32_16x16x32_bf16 v[62:65], v[176:179], v[198:201], v[62:65]
	v_mfma_f32_16x16x32_bf16 v[54:57], v[184:187], v[198:201], v[54:57]
	v_mfma_f32_16x16x32_bf16 v[46:49], v[176:179], v[206:209], v[46:49]
	v_mfma_f32_16x16x32_bf16 v[38:41], v[184:187], v[206:209], v[38:41]
	v_mfma_f32_16x16x32_bf16 v[30:33], v[176:179], v[214:217], v[30:33]
	v_mfma_f32_16x16x32_bf16 v[22:25], v[184:187], v[214:217], v[22:25]
	v_mfma_f32_16x16x32_bf16 v[14:17], v[176:179], v[222:225], v[14:17]
	v_mfma_f32_16x16x32_bf16 v[2:5], v[184:187], v[222:225], v[2:5]
	v_mfma_f32_16x16x32_bf16 v[62:65], v[180:183], v[202:205], v[62:65]
	v_mfma_f32_16x16x32_bf16 v[54:57], v[188:191], v[202:205], v[54:57]
	v_mfma_f32_16x16x32_bf16 v[46:49], v[180:183], v[210:213], v[46:49]
	v_mfma_f32_16x16x32_bf16 v[38:41], v[188:191], v[210:213], v[38:41]
	v_mfma_f32_16x16x32_bf16 v[30:33], v[180:183], v[218:221], v[30:33]
	v_mfma_f32_16x16x32_bf16 v[22:25], v[188:191], v[218:221], v[22:25]
	v_mfma_f32_16x16x32_bf16 v[14:17], v[180:183], v[226:229], v[14:17]
	v_mfma_f32_16x16x32_bf16 v[2:5], v[188:191], v[226:229], v[2:5]
	s_barrier
	s_add_i32 s57, s57, 2
	s_add_i32 s58, s58, 0x400000
	s_cmp_gt_u32 s57, 29
	s_mov_b64 s[28:29], s[30:31]
; #define PG8_STAGE(bufoff, gbase, voff) do { _Pragma("unroll") for (int _i = 0; _i < 2; ++_i) \
;         __builtin_amdgcn_global_load_lds((const unsigned*)((const char*)(gbase) + (voff)[_i]), (LAS unsigned*)(lds + (bufoff) + ldsw + _i * 8192), 16, 0, 0); } while (0)
; #define PG8_LDA(dst, b, h) do { _Pragma("unroll") for (int m = 0; m < 4; ++m) _Pragma("unroll") for (int k = 0; k < 2; ++k) dst[m][k] = *(const LAS bf16x8*)(lds + PG8_SA(b, h) + aoff + m * 2048 + k * 1024); } while (0)
; #define PG8_LDB(dst, b, h) do { _Pragma("unroll") for (int n = 0; n < 2; ++n) _Pragma("unroll") for (int k = 0; k < 2; ++k) dst[n][k] = *(const LAS bf16x8*)(lds + PG8_SB(b, h) + boff + n * 2048 + k * 1024); } while (0)
; #define PG8_MMA(ai, bj, At, Bt) do { __builtin_amdgcn_s_setprio(1); _Pragma("unroll") for (int m = 0; m < 4; ++m) _Pragma("unroll") for (int n = 0; n < 2; ++n) _Pragma("unroll") for (int k = 0; k < 2; ++k) \
;         acc[ai][bj][m][n] = __builtin_amdgcn_mfma_f32_16x16x32_bf16(Bt[n][k], At[m][k], acc[ai][bj][m][n], 0, 0, 0); __builtin_amdgcn_s_setprio(0); } while (0)
; #define PG8_WAIT_V(n) asm volatile("s_waitcnt vmcnt(" #n ")" ::: "memory")
; #define PG8_WAIT_L(n) asm volatile("s_waitcnt lgkmcnt(" #n ")" ::: "memory")
; #define PG8_BAR __builtin_amdgcn_s_barrier()
; #define PG8_SCHED __builtin_amdgcn_sched_barrier(0)
; template <class Epi, class Sched, int KC, bool ALIGN_EPI = false, bool SP2 = false, bool ATILED = false>
; __device__ __forceinline__ void gemm_phase(LAS unsigned char* lds, const Gemm g, const Sched& S, const Epi& E, int wave_s) {
;     ...
;             const bool last = (t == nt - 2);
;             const char* a1 = cA + PG8_AOFF(t + 1);
;             const char* a2 = last ? nA : cA + PG8_AOFF(t + 2); const char* b2 = last ? nB : cB + (size_t)(t + 2) * kstep;
;             const char* a3 = a2 + kstep; const char* b3 = b2 + kstep;
;             if (last && has_next) S.a_ready(nxt);
;             if constexpr (SP2) {
;             PG8_LDB(B0, 0, 0); PG8_LDB(B1, 0, 1); PG8_SCHED; PG8_LDA(At, 0, 0); PG8_STAGE(PG8_SA(1, 1), a1 + hstepA, voffA);
;             PG8_WAIT_V(8); PG8_WAIT_L(0); PG8_BAR; PG8_MMA(0, 0, At, B0); PG8_MMA(0, 1, At, B1); PG8_BAR; PG8_SCHED;
.LBB0_233:
	s_add_i32 s30, s58, 0xffc00000
	s_and_b32 s30, s30, 0x3800000
	s_and_b32 s31, s28, 0x100
	s_or_b32 s59, s31, s30
	s_and_b32 s34, s58, 0x7800000
	s_add_u32 s30, s28, 0x100
	s_addc_u32 s31, s29, 0
	s_and_b32 s35, s30, 0x100
	s_or_b32 s34, s34, s35
	s_add_u32 s34, s26, s34
	s_addc_u32 s35, s27, 0
	s_add_u32 s28, s55, s28
	s_addc_u32 s29, s56, s29
	s_add_i32 s62, 0, 0x10000
	s_cmp_eq_u32 s57, 28
	s_cselect_b32 s35, s19, s35
	s_cselect_b32 s34, s53, s34
	v_add_u32_e32 v139, s62, v163
	s_cselect_b32 s29, s17, s29
	s_cselect_b32 s28, s54, s28
	s_add_i32 s63, 0, 0x14000
	ds_read_b128 v[152:155], v139
	ds_read_b128 v[156:159], v139 offset:1024
	ds_read_b128 v[168:171], v139 offset:2048
	ds_read_b128 v[172:175], v139 offset:3072
	v_add_u32_e32 v139, s63, v163
	ds_read_b128 v[176:179], v139
	ds_read_b128 v[180:183], v139 offset:1024
	ds_read_b128 v[184:187], v139 offset:2048
	ds_read_b128 v[188:191], v139 offset:3072
	s_add_u32 s59, s26, s59
	s_addc_u32 s61, s27, 0
	s_add_u32 s60, s59, 0x10080
	s_addc_u32 s61, s61, 0
	s_add_i32 m0, s44, 0xc000
	ds_read_b128 v[198:201], v166
	ds_read_b128 v[202:205], v166 offset:1024
	ds_read_b128 v[206:209], v166 offset:2048
	ds_read_b128 v[210:213], v166 offset:3072
	ds_read_b128 v[214:217], v166 offset:4096
	ds_read_b128 v[218:221], v166 offset:5120
	ds_read_b128 v[222:225], v166 offset:6144
	ds_read_b128 v[226:229], v166 offset:7168
	global_load_lds_dwordx4 v136, s[60:61]
	s_add_i32 m0, s44, 0xe000
	s_nop 0
	global_load_lds_dwordx4 v132, s[60:61]
	s_waitcnt vmcnt(8)
	s_waitcnt lgkmcnt(0)
	s_barrier
	v_mfma_f32_16x16x32_bf16 v[122:125], v[152:155], v[198:201], v[122:125]
	v_mfma_f32_16x16x32_bf16 v[114:117], v[168:171], v[198:201], v[114:117]
	v_mfma_f32_16x16x32_bf16 v[106:109], v[152:155], v[206:209], v[106:109]
	v_mfma_f32_16x16x32_bf16 v[98:101], v[168:171], v[206:209], v[98:101]
	v_mfma_f32_16x16x32_bf16 v[90:93], v[152:155], v[214:217], v[90:93]
	v_mfma_f32_16x16x32_bf16 v[82:85], v[168:171], v[214:217], v[82:85]
	v_mfma_f32_16x16x32_bf16 v[74:77], v[152:155], v[222:225], v[74:77]
	v_mfma_f32_16x16x32_bf16 v[66:69], v[168:171], v[222:225], v[66:69]
	v_mfma_f32_16x16x32_bf16 v[122:125], v[156:159], v[202:205], v[122:125]
	v_mfma_f32_16x16x32_bf16 v[114:117], v[172:175], v[202:205], v[114:117]
	v_mfma_f32_16x16x32_bf16 v[106:109], v[156:159], v[210:213], v[106:109]
	v_mfma_f32_16x16x32_bf16 v[98:101], v[172:175], v[210:213], v[98:101]
	v_mfma_f32_16x16x32_bf16 v[90:93], v[156:159], v[218:221], v[90:93]
	v_mfma_f32_16x16x32_bf16 v[82:85], v[172:175], v[218:221], v[82:85]
	v_mfma_f32_16x16x32_bf16 v[74:77], v[156:159], v[226:229], v[74:77]
	v_mfma_f32_16x16x32_bf16 v[66:69], v[172:175], v[226:229], v[66:69]
	v_mfma_f32_16x16x32_bf16 v[126:129], v[176:179], v[198:201], v[126:129]
	v_mfma_f32_16x16x32_bf16 v[118:121], v[184:187], v[198:201], v[118:121]
	v_mfma_f32_16x16x32_bf16 v[110:113], v[176:179], v[206:209], v[110:113]
	v_mfma_f32_16x16x32_bf16 v[102:105], v[184:187], v[206:209], v[102:105]
	v_mfma_f32_16x16x32_bf16 v[94:97], v[176:179], v[214:217], v[94:97]
	v_mfma_f32_16x16x32_bf16 v[86:89], v[184:187], v[214:217], v[86:89]
	v_mfma_f32_16x16x32_bf16 v[78:81], v[176:179], v[222:225], v[78:81]
	v_mfma_f32_16x16x32_bf16 v[70:73], v[184:187], v[222:225], v[70:73]
	v_mfma_f32_16x16x32_bf16 v[126:129], v[180:183], v[202:205], v[126:129]
	v_mfma_f32_16x16x32_bf16 v[118:121], v[188:191], v[202:205], v[118:121]
	v_mfma_f32_16x16x32_bf16 v[110:113], v[180:183], v[210:213], v[110:113]
	v_mfma_f32_16x16x32_bf16 v[102:105], v[188:191], v[210:213], v[102:105]
	v_mfma_f32_16x16x32_bf16 v[94:97], v[180:183], v[218:221], v[94:97]
	v_mfma_f32_16x16x32_bf16 v[86:89], v[188:191], v[218:221], v[86:89]
	v_mfma_f32_16x16x32_bf16 v[78:81], v[180:183], v[226:229], v[78:81]
	v_mfma_f32_16x16x32_bf16 v[70:73], v[188:191], v[226:229], v[70:73]
	s_barrier
	s_add_u32 s100, s34, 0x80
	s_addc_u32 s101, s35, 0
	s_add_i32 s59, s62, s38
	s_mov_b32 m0, s59
	ds_read_b128 v[198:201], v166 offset:16384
	ds_read_b128 v[202:205], v166 offset:17408
	ds_read_b128 v[206:209], v166 offset:18432
	ds_read_b128 v[210:213], v166 offset:19456
	ds_read_b128 v[214:217], v166 offset:20480
	ds_read_b128 v[218:221], v166 offset:21504
	ds_read_b128 v[222:225], v166 offset:22528
	ds_read_b128 v[226:229], v166 offset:23552
	global_load_lds_dwordx4 v134, s[28:29]
	s_add_i32 m0, s59, 0x2000
	s_add_u32 s60, s28, 0x80000
	s_addc_u32 s61, s29, 0
	s_add_i32 s59, s63, s38
	global_load_lds_dwordx4 v130, s[28:29]
	s_mov_b32 m0, s59
	s_nop 0
	global_load_lds_dwordx4 v134, s[60:61]
	s_add_i32 m0, s59, 0x2000
	s_nop 0
	global_load_lds_dwordx4 v130, s[60:61]
	s_mov_b32 m0, s44
	s_nop 0
	global_load_lds_dwordx4 v136, s[34:35]
	s_mov_b32 m0, s45
	s_nop 0
	global_load_lds_dwordx4 v132, s[34:35]
	s_waitcnt vmcnt(8)
	s_waitcnt lgkmcnt(0)
	s_barrier
; #define PG8_STAGE(bufoff, gbase, voff) do { _Pragma("unroll") for (int _i = 0; _i < 2; ++_i) \
;         __builtin_amdgcn_global_load_lds((const unsigned*)((const char*)(gbase) + (voff)[_i]), (LAS unsigned*)(lds + (bufoff) + ldsw + _i * 8192), 16, 0, 0); } while (0)
; #define PG8_LDA(dst, b, h) do { _Pragma("unroll") for (int m = 0; m < 4; ++m) _Pragma("unroll") for (int k = 0; k < 2; ++k) dst[m][k] = *(const LAS bf16x8*)(lds + PG8_SA(b, h) + aoff + m * 2048 + k * 1024); } while (0)
; #define PG8_LDB(dst, b, h) do { _Pragma("unroll") for (int n = 0; n < 2; ++n) _Pragma("unroll") for (int k = 0; k < 2; ++k) dst[n][k] = *(const LAS bf16x8*)(lds + PG8_SB(b, h) + boff + n * 2048 + k * 1024); } while (0)
; #define PG8_MMA(ai, bj, At, Bt) do { __builtin_amdgcn_s_setprio(1); _Pragma("unroll") for (int m = 0; m < 4; ++m) _Pragma("unroll") for (int n = 0; n < 2; ++n) _Pragma("unroll") for (int k = 0; k < 2; ++k) \
;         acc[ai][bj][m][n] = __builtin_amdgcn_mfma_f32_16x16x32_bf16(Bt[n][k], At[m][k], acc[ai][bj][m][n], 0, 0, 0); __builtin_amdgcn_s_setprio(0); } while (0)
; #define PG8_WAIT_V(n) asm volatile("s_waitcnt vmcnt(" #n ")" ::: "memory")
; #define PG8_WAIT_L(n) asm volatile("s_waitcnt lgkmcnt(" #n ")" ::: "memory")
; #define PG8_BAR __builtin_amdgcn_s_barrier()
; #define PG8_SCHED __builtin_amdgcn_sched_barrier(0)
; template <class Epi, class Sched, int KC, bool ALIGN_EPI = false, bool SP2 = false, bool ATILED = false>
; __device__ __forceinline__ void gemm_phase(LAS unsigned char* lds, const Gemm g, const Sched& S, const Epi& E, int wave_s) {
;     ...
;             PG8_WAIT_V(8); PG8_WAIT_L(0); PG8_BAR; PG8_MMA(0, 0, At, B0); PG8_MMA(0, 1, At, B1); PG8_BAR; PG8_SCHED;
;             PG8_LDA(At, 0, 1); PG8_STAGE(PG8_SB(0, 0), b2, voffB); PG8_STAGE(PG8_SB(0, 1), b2 + hstepB, voffB); PG8_STAGE(PG8_SA(0, 0), a2, voffA);
;             PG8_WAIT_V(8); PG8_WAIT_L(0); PG8_BAR; PG8_MMA(1, 0, At, B0); PG8_MMA(1, 1, At, B1); PG8_BAR; PG8_SCHED;
;             PG8_LDB(B0, 1, 0); PG8_LDB(B1, 1, 1); PG8_SCHED; PG8_LDA(At, 1, 0); PG8_STAGE(PG8_SA(0, 1), a2 + hstepA, voffA);
;             PG8_WAIT_V(8); PG8_WAIT_L(0); PG8_BAR; PG8_MMA(0, 0, At, B0); PG8_MMA(0, 1, At, B1); PG8_BAR; PG8_SCHED;
	v_mfma_f32_16x16x32_bf16 v[58:61], v[152:155], v[198:201], v[58:61]
	v_mfma_f32_16x16x32_bf16 v[50:53], v[168:171], v[198:201], v[50:53]
	v_mfma_f32_16x16x32_bf16 v[42:45], v[152:155], v[206:209], v[42:45]
	v_mfma_f32_16x16x32_bf16 v[34:37], v[168:171], v[206:209], v[34:37]
	v_mfma_f32_16x16x32_bf16 v[26:29], v[152:155], v[214:217], v[26:29]
	v_mfma_f32_16x16x32_bf16 v[18:21], v[168:171], v[214:217], v[18:21]
	v_mfma_f32_16x16x32_bf16 v[10:13], v[152:155], v[222:225], v[10:13]
	v_mfma_f32_16x16x32_bf16 v[6:9], v[168:171], v[222:225], v[6:9]
	v_mfma_f32_16x16x32_bf16 v[58:61], v[156:159], v[202:205], v[58:61]
	v_mfma_f32_16x16x32_bf16 v[50:53], v[172:175], v[202:205], v[50:53]
	v_mfma_f32_16x16x32_bf16 v[42:45], v[156:159], v[210:213], v[42:45]
	v_mfma_f32_16x16x32_bf16 v[34:37], v[172:175], v[210:213], v[34:37]
	v_mfma_f32_16x16x32_bf16 v[26:29], v[156:159], v[218:221], v[26:29]
	v_mfma_f32_16x16x32_bf16 v[18:21], v[172:175], v[218:221], v[18:21]
	v_mfma_f32_16x16x32_bf16 v[10:13], v[156:159], v[226:229], v[10:13]
	v_mfma_f32_16x16x32_bf16 v[6:9], v[172:175], v[226:229], v[6:9]
	v_mfma_f32_16x16x32_bf16 v[62:65], v[176:179], v[198:201], v[62:65]
	v_mfma_f32_16x16x32_bf16 v[54:57], v[184:187], v[198:201], v[54:57]
	v_mfma_f32_16x16x32_bf16 v[46:49], v[176:179], v[206:209], v[46:49]
	v_mfma_f32_16x16x32_bf16 v[38:41], v[184:187], v[206:209], v[38:41]
	v_mfma_f32_16x16x32_bf16 v[30:33], v[176:179], v[214:217], v[30:33]
	v_mfma_f32_16x16x32_bf16 v[22:25], v[184:187], v[214:217], v[22:25]
	v_mfma_f32_16x16x32_bf16 v[14:17], v[176:179], v[222:225], v[14:17]
	v_mfma_f32_16x16x32_bf16 v[2:5], v[184:187], v[222:225], v[2:5]
	v_mfma_f32_16x16x32_bf16 v[62:65], v[180:183], v[202:205], v[62:65]
	v_mfma_f32_16x16x32_bf16 v[54:57], v[188:191], v[202:205], v[54:57]
	v_mfma_f32_16x16x32_bf16 v[46:49], v[180:183], v[210:213], v[46:49]
	v_mfma_f32_16x16x32_bf16 v[38:41], v[188:191], v[210:213], v[38:41]
	v_mfma_f32_16x16x32_bf16 v[30:33], v[180:183], v[218:221], v[30:33]
	v_mfma_f32_16x16x32_bf16 v[22:25], v[188:191], v[218:221], v[22:25]
	v_mfma_f32_16x16x32_bf16 v[14:17], v[180:183], v[226:229], v[14:17]
	v_mfma_f32_16x16x32_bf16 v[2:5], v[188:191], v[226:229], v[2:5]
	s_barrier
	s_add_i32 s59, 0, 0x18000
	v_add_u32_e32 v139, s59, v163
	s_add_i32 s60, 0, 0x1c000
	ds_read_b128 v[152:155], v139
	ds_read_b128 v[156:159], v139 offset:1024
	ds_read_b128 v[168:171], v139 offset:2048
	ds_read_b128 v[172:175], v139 offset:3072
	v_add_u32_e32 v139, s60, v163
	ds_read_b128 v[176:179], v139
	ds_read_b128 v[180:183], v139 offset:1024
	ds_read_b128 v[184:187], v139 offset:2048
	ds_read_b128 v[188:191], v139 offset:3072
	s_add_u32 s34, s34, 0x10000
	s_addc_u32 s35, s35, 0
	s_mov_b32 m0, s46
	ds_read_b128 v[198:201], v166 offset:32768
	ds_read_b128 v[202:205], v166 offset:33792
	ds_read_b128 v[206:209], v166 offset:34816
	ds_read_b128 v[210:213], v166 offset:35840
	ds_read_b128 v[214:217], v166 offset:36864
	ds_read_b128 v[218:221], v166 offset:37888
	ds_read_b128 v[222:225], v166 offset:38912
	ds_read_b128 v[226:229], v166 offset:39936
	global_load_lds_dwordx4 v136, s[34:35]
	s_mov_b32 m0, s47
	s_nop 0
	global_load_lds_dwordx4 v132, s[34:35]
	s_waitcnt vmcnt(8)
	s_waitcnt lgkmcnt(0)
	s_barrier
	v_mfma_f32_16x16x32_bf16 v[122:125], v[152:155], v[198:201], v[122:125]
	v_mfma_f32_16x16x32_bf16 v[114:117], v[168:171], v[198:201], v[114:117]
	v_mfma_f32_16x16x32_bf16 v[106:109], v[152:155], v[206:209], v[106:109]
	v_mfma_f32_16x16x32_bf16 v[98:101], v[168:171], v[206:209], v[98:101]
	v_mfma_f32_16x16x32_bf16 v[90:93], v[152:155], v[214:217], v[90:93]
	v_mfma_f32_16x16x32_bf16 v[82:85], v[168:171], v[214:217], v[82:85]
	v_mfma_f32_16x16x32_bf16 v[74:77], v[152:155], v[222:225], v[74:77]
	v_mfma_f32_16x16x32_bf16 v[66:69], v[168:171], v[222:225], v[66:69]
	v_mfma_f32_16x16x32_bf16 v[122:125], v[156:159], v[202:205], v[122:125]
	v_mfma_f32_16x16x32_bf16 v[114:117], v[172:175], v[202:205], v[114:117]
	v_mfma_f32_16x16x32_bf16 v[106:109], v[156:159], v[210:213], v[106:109]
	v_mfma_f32_16x16x32_bf16 v[98:101], v[172:175], v[210:213], v[98:101]
	v_mfma_f32_16x16x32_bf16 v[90:93], v[156:159], v[218:221], v[90:93]
	v_mfma_f32_16x16x32_bf16 v[82:85], v[172:175], v[218:221], v[82:85]
	v_mfma_f32_16x16x32_bf16 v[74:77], v[156:159], v[226:229], v[74:77]
	v_mfma_f32_16x16x32_bf16 v[66:69], v[172:175], v[226:229], v[66:69]
	v_mfma_f32_16x16x32_bf16 v[126:129], v[176:179], v[198:201], v[126:129]
	v_mfma_f32_16x16x32_bf16 v[118:121], v[184:187], v[198:201], v[118:121]
	v_mfma_f32_16x16x32_bf16 v[110:113], v[176:179], v[206:209], v[110:113]
	v_mfma_f32_16x16x32_bf16 v[102:105], v[184:187], v[206:209], v[102:105]
	v_mfma_f32_16x16x32_bf16 v[94:97], v[176:179], v[214:217], v[94:97]
	v_mfma_f32_16x16x32_bf16 v[86:89], v[184:187], v[214:217], v[86:89]
	v_mfma_f32_16x16x32_bf16 v[78:81], v[176:179], v[222:225], v[78:81]
	v_mfma_f32_16x16x32_bf16 v[70:73], v[184:187], v[222:225], v[70:73]
	v_mfma_f32_16x16x32_bf16 v[126:129], v[180:183], v[202:205], v[126:129]
	v_mfma_f32_16x16x32_bf16 v[118:121], v[188:191], v[202:205], v[118:121]
	v_mfma_f32_16x16x32_bf16 v[110:113], v[180:183], v[210:213], v[110:113]
	v_mfma_f32_16x16x32_bf16 v[102:105], v[188:191], v[210:213], v[102:105]
	v_mfma_f32_16x16x32_bf16 v[94:97], v[180:183], v[218:221], v[94:97]
	v_mfma_f32_16x16x32_bf16 v[86:89], v[188:191], v[218:221], v[86:89]
	v_mfma_f32_16x16x32_bf16 v[78:81], v[180:183], v[226:229], v[78:81]
	v_mfma_f32_16x16x32_bf16 v[70:73], v[188:191], v[226:229], v[70:73]
	s_barrier
; #define PG8_STAGE(bufoff, gbase, voff) do { _Pragma("unroll") for (int _i = 0; _i < 2; ++_i) \
;         __builtin_amdgcn_global_load_lds((const unsigned*)((const char*)(gbase) + (voff)[_i]), (LAS unsigned*)(lds + (bufoff) + ldsw + _i * 8192), 16, 0, 0); } while (0)
; #define PG8_LDA(dst, b, h) do { _Pragma("unroll") for (int m = 0; m < 4; ++m) _Pragma("unroll") for (int k = 0; k < 2; ++k) dst[m][k] = *(const LAS bf16x8*)(lds + PG8_SA(b, h) + aoff + m * 2048 + k * 1024); } while (0)
; #define PG8_MMA(ai, bj, At, Bt) do { __builtin_amdgcn_s_setprio(1); _Pragma("unroll") for (int m = 0; m < 4; ++m) _Pragma("unroll") for (int n = 0; n < 2; ++n) _Pragma("unroll") for (int k = 0; k < 2; ++k) \
;         acc[ai][bj][m][n] = __builtin_amdgcn_mfma_f32_16x16x32_bf16(Bt[n][k], At[m][k], acc[ai][bj][m][n], 0, 0, 0); __builtin_amdgcn_s_setprio(0); } while (0)
; #define PG8_WAIT_V(n) asm volatile("s_waitcnt vmcnt(" #n ")" ::: "memory")
; #define PG8_WAIT_L(n) asm volatile("s_waitcnt lgkmcnt(" #n ")" ::: "memory")
; #define PG8_BAR __builtin_amdgcn_s_barrier()
; #define PG8_SCHED __builtin_amdgcn_sched_barrier(0)
; template <class Epi, class Sched, int KC, bool ALIGN_EPI = false, bool SP2 = false, bool ATILED = false>
; __device__ __forceinline__ void gemm_phase(LAS unsigned char* lds, const Gemm g, const Sched& S, const Epi& E, int wave_s) {
;     ...
;             PG8_LDA(At, 1, 1); PG8_STAGE(PG8_SB(1, 0), b3, voffB); PG8_STAGE(PG8_SB(1, 1), b3 + hstepB, voffB); PG8_STAGE(PG8_SA(1, 0), a3, voffA);
;             PG8_WAIT_V(8); PG8_WAIT_L(0); PG8_BAR; PG8_MMA(1, 0, At, B0); PG8_MMA(1, 1, At, B1); PG8_BAR; PG8_SCHED;
;     ...
;         if constexpr (ALIGN_EPI) { if (wr == 0) PG8_BAR; }
	s_add_u32 s98, s28, 0x80
	s_addc_u32 s99, s29, 0
	s_add_i32 s34, s59, s38
	s_mov_b32 m0, s34
	ds_read_b128 v[198:201], v166 offset:49152
	ds_read_b128 v[202:205], v166 offset:50176
	ds_read_b128 v[206:209], v166 offset:51200
	ds_read_b128 v[210:213], v166 offset:52224
	ds_read_b128 v[214:217], v166 offset:53248
	ds_read_b128 v[218:221], v166 offset:54272
	ds_read_b128 v[222:225], v166 offset:55296
	ds_read_b128 v[226:229], v166 offset:56320
	global_load_lds_dwordx4 v134, s[98:99]
	s_add_i32 m0, s34, 0x2000
	s_add_u32 s28, s28, 0x80080
	s_addc_u32 s29, s29, 0
	s_add_i32 s34, s60, s38
	global_load_lds_dwordx4 v130, s[98:99]
	s_mov_b32 m0, s34
	s_nop 0
	global_load_lds_dwordx4 v134, s[28:29]
	s_add_i32 m0, s34, 0x2000
	s_nop 0
	global_load_lds_dwordx4 v130, s[28:29]
	s_mov_b32 m0, s48
	s_nop 0
	global_load_lds_dwordx4 v136, s[100:101]
	s_mov_b32 m0, s49
	s_nop 0
	global_load_lds_dwordx4 v132, s[100:101]
	s_waitcnt vmcnt(8)
	s_waitcnt lgkmcnt(0)
	s_barrier
	v_mfma_f32_16x16x32_bf16 v[58:61], v[152:155], v[198:201], v[58:61]
	v_mfma_f32_16x16x32_bf16 v[50:53], v[168:171], v[198:201], v[50:53]
	v_mfma_f32_16x16x32_bf16 v[42:45], v[152:155], v[206:209], v[42:45]
	v_mfma_f32_16x16x32_bf16 v[34:37], v[168:171], v[206:209], v[34:37]
	v_mfma_f32_16x16x32_bf16 v[26:29], v[152:155], v[214:217], v[26:29]
	v_mfma_f32_16x16x32_bf16 v[18:21], v[168:171], v[214:217], v[18:21]
	v_mfma_f32_16x16x32_bf16 v[10:13], v[152:155], v[222:225], v[10:13]
	v_mfma_f32_16x16x32_bf16 v[6:9], v[168:171], v[222:225], v[6:9]
	v_mfma_f32_16x16x32_bf16 v[58:61], v[156:159], v[202:205], v[58:61]
	v_mfma_f32_16x16x32_bf16 v[50:53], v[172:175], v[202:205], v[50:53]
	v_mfma_f32_16x16x32_bf16 v[42:45], v[156:159], v[210:213], v[42:45]
	v_mfma_f32_16x16x32_bf16 v[34:37], v[172:175], v[210:213], v[34:37]
	v_mfma_f32_16x16x32_bf16 v[26:29], v[156:159], v[218:221], v[26:29]
	v_mfma_f32_16x16x32_bf16 v[18:21], v[172:175], v[218:221], v[18:21]
	v_mfma_f32_16x16x32_bf16 v[10:13], v[156:159], v[226:229], v[10:13]
	v_mfma_f32_16x16x32_bf16 v[6:9], v[172:175], v[226:229], v[6:9]
	v_mfma_f32_16x16x32_bf16 v[62:65], v[176:179], v[198:201], v[62:65]
	v_mfma_f32_16x16x32_bf16 v[54:57], v[184:187], v[198:201], v[54:57]
	v_mfma_f32_16x16x32_bf16 v[46:49], v[176:179], v[206:209], v[46:49]
	v_mfma_f32_16x16x32_bf16 v[38:41], v[184:187], v[206:209], v[38:41]
	v_mfma_f32_16x16x32_bf16 v[30:33], v[176:179], v[214:217], v[30:33]
	v_mfma_f32_16x16x32_bf16 v[22:25], v[184:187], v[214:217], v[22:25]
	v_mfma_f32_16x16x32_bf16 v[14:17], v[176:179], v[222:225], v[14:17]
	v_mfma_f32_16x16x32_bf16 v[2:5], v[184:187], v[222:225], v[2:5]
	v_mfma_f32_16x16x32_bf16 v[62:65], v[180:183], v[202:205], v[62:65]
	v_mfma_f32_16x16x32_bf16 v[54:57], v[188:191], v[202:205], v[54:57]
	v_mfma_f32_16x16x32_bf16 v[46:49], v[180:183], v[210:213], v[46:49]
	v_mfma_f32_16x16x32_bf16 v[38:41], v[188:191], v[210:213], v[38:41]
	v_mfma_f32_16x16x32_bf16 v[30:33], v[180:183], v[218:221], v[30:33]
	v_mfma_f32_16x16x32_bf16 v[22:25], v[188:191], v[218:221], v[22:25]
	v_mfma_f32_16x16x32_bf16 v[14:17], v[180:183], v[226:229], v[14:17]
	v_mfma_f32_16x16x32_bf16 v[2:5], v[188:191], v[226:229], v[2:5]
	s_barrier
	s_add_i32 s57, s57, 2
	s_add_i32 s58, s58, 0x400000
	s_cmp_gt_u32 s57, 29
	s_mov_b64 s[28:29], s[30:31]
	s_cbranch_scc0 .LBB0_233
	s_and_b64 vcc, exec, s[14:15]
	s_cbranch_vccz .LBB0_236
	s_barrier

; #define PG8_STAGE(bufoff, gbase, voff) do { _Pragma("unroll") for (int _i = 0; _i < 2; ++_i) \
;         __builtin_amdgcn_global_load_lds((const unsigned*)((const char*)(gbase) + (voff)[_i]), (LAS unsigned*)(lds + (bufoff) + ldsw + _i * 8192), 16, 0, 0); } while (0)
; #define PG8_LDA(dst, b, h) do { _Pragma("unroll") for (int m = 0; m < 4; ++m) _Pragma("unroll") for (int k = 0; k < 2; ++k) dst[m][k] = *(const LAS bf16x8*)(lds + PG8_SA(b, h) + aoff + m * 2048 + k * 1024); } while (0)
; #define PG8_LDB(dst, b, h) do { _Pragma("unroll") for (int n = 0; n < 2; ++n) _Pragma("unroll") for (int k = 0; k < 2; ++k) dst[n][k] = *(const LAS bf16x8*)(lds + PG8_SB(b, h) + boff + n * 2048 + k * 1024); } while (0)
; #define PG8_MMA(ai, bj, At, Bt) do { __builtin_amdgcn_s_setprio(1); _Pragma("unroll") for (int m = 0; m < 4; ++m) _Pragma("unroll") for (int n = 0; n < 2; ++n) _Pragma("unroll") for (int k = 0; k < 2; ++k) \
;         acc[ai][bj][m][n] = __builtin_amdgcn_mfma_f32_16x16x32_bf16(Bt[n][k], At[m][k], acc[ai][bj][m][n], 0, 0, 0); __builtin_amdgcn_s_setprio(0); } while (0)
; #define PG8_WAIT_V(n) asm volatile("s_waitcnt vmcnt(" #n ")" ::: "memory")
; #define PG8_WAIT_L(n) asm volatile("s_waitcnt lgkmcnt(" #n ")" ::: "memory")
; template <class Epi, class Sched, int KC, bool ALIGN_EPI = false, bool SP2 = false, bool ATILED = false>
; __device__ __forceinline__ void gemm_phase(LAS unsigned char* lds, const Gemm g, const Sched& S, const Epi& E, int wave_s) {
;     ...
;             const bool last = (t == nt - 2);
;             const char* a1 = cA + PG8_AOFF(t + 1);
;             const char* a2 = last ? nA : cA + PG8_AOFF(t + 2); const char* b2 = last ? nB : cB + (size_t)(t + 2) * kstep;
;             const char* a3 = a2 + kstep; const char* b3 = b2 + kstep;
;             if (last && has_next) S.a_ready(nxt);
;             if constexpr (SP2) {
;             PG8_LDB(B0, 0, 0); PG8_LDB(B1, 0, 1); PG8_SCHED; PG8_LDA(At, 0, 0); PG8_STAGE(PG8_SA(1, 1), a1 + hstepA, voffA);
;             PG8_WAIT_V(8); PG8_WAIT_L(0); PG8_BAR; PG8_MMA(0, 0, At, B0); PG8_MMA(0, 1, At, B1); PG8_BAR; PG8_SCHED;
;     ...
; #pragma unroll
;         for (int a = 0; a < 2; ++a)
; #pragma unroll
;             for (int b = 0; b < 2; ++b)
; #pragma unroll
;                 for (int m = 0; m < 4; ++m)
; #pragma unroll
;                     for (int n = 0; n < 2; ++n) acc[a][b][m][n] = (f32x4){0.f, 0.f, 0.f, 0.f};
.LBB0_317:
	s_add_u32 s50, s22, 0x100
	v_mov_b32_e32 v2, 0
	s_addc_u32 s51, s23, 0
	s_mov_b32 s52, -2
	v_mov_b32_e32 v3, v2
	v_mov_b32_e32 v4, v2
	v_mov_b32_e32 v5, v2
	v_mov_b32_e32 v6, v2
	v_mov_b32_e32 v7, v2
	v_mov_b32_e32 v8, v2
	v_mov_b32_e32 v9, v2
	v_mov_b32_e32 v18, v2
	v_mov_b32_e32 v19, v2
	v_mov_b32_e32 v20, v2
	v_mov_b32_e32 v21, v2
	v_mov_b32_e32 v22, v2
	v_mov_b32_e32 v23, v2
	v_mov_b32_e32 v24, v2
	v_mov_b32_e32 v25, v2
	v_mov_b32_e32 v34, v2
	v_mov_b32_e32 v35, v2
	v_mov_b32_e32 v36, v2
	v_mov_b32_e32 v37, v2
	v_mov_b32_e32 v38, v2
	v_mov_b32_e32 v39, v2
	v_mov_b32_e32 v40, v2
	v_mov_b32_e32 v41, v2
	v_mov_b32_e32 v50, v2
	v_mov_b32_e32 v51, v2
	v_mov_b32_e32 v52, v2
	v_mov_b32_e32 v53, v2
	v_mov_b32_e32 v54, v2
	v_mov_b32_e32 v55, v2
	v_mov_b32_e32 v56, v2
	v_mov_b32_e32 v57, v2
	v_mov_b32_e32 v10, v2
	v_mov_b32_e32 v11, v2
	v_mov_b32_e32 v12, v2
	v_mov_b32_e32 v13, v2
	v_mov_b32_e32 v14, v2
	v_mov_b32_e32 v15, v2
	v_mov_b32_e32 v16, v2
	v_mov_b32_e32 v17, v2
	v_mov_b32_e32 v26, v2
	v_mov_b32_e32 v27, v2
	v_mov_b32_e32 v28, v2
	v_mov_b32_e32 v29, v2
	v_mov_b32_e32 v30, v2
	v_mov_b32_e32 v31, v2
	v_mov_b32_e32 v32, v2
	v_mov_b32_e32 v33, v2
	v_mov_b32_e32 v42, v2
	v_mov_b32_e32 v43, v2
	v_mov_b32_e32 v44, v2
	v_mov_b32_e32 v45, v2
	v_mov_b32_e32 v46, v2
	v_mov_b32_e32 v47, v2
	v_mov_b32_e32 v48, v2
	v_mov_b32_e32 v49, v2
	v_mov_b32_e32 v58, v2
	v_mov_b32_e32 v59, v2
	v_mov_b32_e32 v60, v2
	v_mov_b32_e32 v61, v2
	v_mov_b32_e32 v62, v2
	v_mov_b32_e32 v63, v2
	v_mov_b32_e32 v64, v2
	v_mov_b32_e32 v65, v2
	v_mov_b32_e32 v66, v2
	v_mov_b32_e32 v67, v2
	v_mov_b32_e32 v68, v2
	v_mov_b32_e32 v69, v2
	v_mov_b32_e32 v70, v2
	v_mov_b32_e32 v71, v2
	v_mov_b32_e32 v72, v2
	v_mov_b32_e32 v73, v2
	v_mov_b32_e32 v86, v2
	v_mov_b32_e32 v87, v2
	v_mov_b32_e32 v88, v2
	v_mov_b32_e32 v89, v2
	v_mov_b32_e32 v90, v2
	v_mov_b32_e32 v91, v2
	v_mov_b32_e32 v92, v2
	v_mov_b32_e32 v93, v2
	v_mov_b32_e32 v110, v2
	v_mov_b32_e32 v111, v2
	v_mov_b32_e32 v112, v2
	v_mov_b32_e32 v113, v2
	v_mov_b32_e32 v118, v2
	v_mov_b32_e32 v119, v2
	v_mov_b32_e32 v120, v2
	v_mov_b32_e32 v121, v2
	v_mov_b32_e32 v138, v2
	v_mov_b32_e32 v139, v2
	v_mov_b32_e32 v140, v2
	v_mov_b32_e32 v141, v2
	v_mov_b32_e32 v142, v2
	v_mov_b32_e32 v143, v2
	v_mov_b32_e32 v144, v2
	v_mov_b32_e32 v145, v2
	v_mov_b32_e32 v74, v2
	v_mov_b32_e32 v75, v2
	v_mov_b32_e32 v76, v2
	v_mov_b32_e32 v77, v2
	v_mov_b32_e32 v78, v2
	v_mov_b32_e32 v79, v2
	v_mov_b32_e32 v80, v2
	v_mov_b32_e32 v81, v2
	v_mov_b32_e32 v98, v2
	v_mov_b32_e32 v99, v2
	v_mov_b32_e32 v100, v2
	v_mov_b32_e32 v101, v2
	v_mov_b32_e32 v102, v2
	v_mov_b32_e32 v103, v2
	v_mov_b32_e32 v104, v2
	v_mov_b32_e32 v105, v2
	v_mov_b32_e32 v122, v2
	v_mov_b32_e32 v123, v2
	v_mov_b32_e32 v124, v2
	v_mov_b32_e32 v125, v2
	v_mov_b32_e32 v126, v2
	v_mov_b32_e32 v127, v2
	v_mov_b32_e32 v128, v2
	v_mov_b32_e32 v129, v2
	v_mov_b32_e32 v158, v2
	v_mov_b32_e32 v159, v2
	v_mov_b32_e32 v160, v2
	v_mov_b32_e32 v161, v2
	v_mov_b32_e32 v162, v2
	v_mov_b32_e32 v163, v2
	v_mov_b32_e32 v164, v2
	v_mov_b32_e32 v165, v2
	s_add_u32 s8, s20, 0x100
	s_addc_u32 s9, s21, 0
	s_add_i32 s53, 0, 0x10000
	s_cmpk_eq_i32 s52, 0x54
	s_cselect_b32 s25, s17, s9
	s_cselect_b32 s24, s16, s8
	s_cselect_b32 s23, s11, s51
	s_cselect_b32 s22, s10, s50
	s_add_i32 s54, 0, 0x14000
	v_add_u32_e32 v114, s53, v249
	v_add_u32_e32 v150, s54, v249
	ds_read_b128 v[82:85], v114
	ds_read_b128 v[94:97], v114 offset:1024
	ds_read_b128 v[106:109], v114 offset:2048
	ds_read_b128 v[114:117], v114 offset:3072
	ds_read_b128 v[130:133], v150
	ds_read_b128 v[134:137], v150 offset:1024
	ds_read_b128 v[146:149], v150 offset:2048
	ds_read_b128 v[150:153], v150 offset:3072
	s_add_i32 m0, s36, 0xc000
	ds_read_b128 v[154:157], v251
	ds_read_b128 v[166:169], v251 offset:1024
	ds_read_b128 v[170:173], v251 offset:2048
	ds_read_b128 v[174:177], v251 offset:3072
	ds_read_b128 v[178:181], v251 offset:4096
	ds_read_b128 v[182:185], v251 offset:5120
	ds_read_b128 v[186:189], v251 offset:6144
	ds_read_b128 v[194:197], v251 offset:7168
	global_load_lds_dwordx4 v204, s[20:21]
	s_add_i32 m0, s36, 0xe000
	s_nop 0
	global_load_lds_dwordx4 v202, s[20:21]
	s_waitcnt vmcnt(32)
	s_waitcnt lgkmcnt(0)
	s_barrier
	v_mfma_f32_16x16x32_bf16 v[162:165], v[82:85], v[154:157], v[162:165]
	v_mfma_f32_16x16x32_bf16 v[158:161], v[106:109], v[154:157], v[158:161]
	v_mfma_f32_16x16x32_bf16 v[126:129], v[82:85], v[170:173], v[126:129]
	v_mfma_f32_16x16x32_bf16 v[122:125], v[106:109], v[170:173], v[122:125]
	v_mfma_f32_16x16x32_bf16 v[102:105], v[82:85], v[178:181], v[102:105]
	v_mfma_f32_16x16x32_bf16 v[98:101], v[106:109], v[178:181], v[98:101]
	v_mfma_f32_16x16x32_bf16 v[78:81], v[82:85], v[186:189], v[78:81]
	v_mfma_f32_16x16x32_bf16 v[74:77], v[106:109], v[186:189], v[74:77]
	v_mfma_f32_16x16x32_bf16 v[162:165], v[94:97], v[166:169], v[162:165]
	v_mfma_f32_16x16x32_bf16 v[158:161], v[114:117], v[166:169], v[158:161]
	v_mfma_f32_16x16x32_bf16 v[126:129], v[94:97], v[174:177], v[126:129]
	v_mfma_f32_16x16x32_bf16 v[122:125], v[114:117], v[174:177], v[122:125]
	v_mfma_f32_16x16x32_bf16 v[102:105], v[94:97], v[182:185], v[102:105]
	v_mfma_f32_16x16x32_bf16 v[98:101], v[114:117], v[182:185], v[98:101]
	v_mfma_f32_16x16x32_bf16 v[78:81], v[94:97], v[194:197], v[78:81]
	v_mfma_f32_16x16x32_bf16 v[74:77], v[114:117], v[194:197], v[74:77]
	v_mfma_f32_16x16x32_bf16 v[142:145], v[130:133], v[154:157], v[142:145]
	v_mfma_f32_16x16x32_bf16 v[138:141], v[146:149], v[154:157], v[138:141]
	v_mfma_f32_16x16x32_bf16 v[118:121], v[130:133], v[170:173], v[118:121]
	v_mfma_f32_16x16x32_bf16 v[110:113], v[146:149], v[170:173], v[110:113]
	v_mfma_f32_16x16x32_bf16 v[90:93], v[130:133], v[178:181], v[90:93]
	v_mfma_f32_16x16x32_bf16 v[86:89], v[146:149], v[178:181], v[86:89]
	v_mfma_f32_16x16x32_bf16 v[70:73], v[130:133], v[186:189], v[70:73]
	v_mfma_f32_16x16x32_bf16 v[66:69], v[146:149], v[186:189], v[66:69]
	v_mfma_f32_16x16x32_bf16 v[142:145], v[134:137], v[166:169], v[142:145]
	v_mfma_f32_16x16x32_bf16 v[138:141], v[150:153], v[166:169], v[138:141]
	v_mfma_f32_16x16x32_bf16 v[118:121], v[134:137], v[174:177], v[118:121]
	v_mfma_f32_16x16x32_bf16 v[110:113], v[150:153], v[174:177], v[110:113]
	v_mfma_f32_16x16x32_bf16 v[90:93], v[134:137], v[182:185], v[90:93]
	v_mfma_f32_16x16x32_bf16 v[86:89], v[150:153], v[182:185], v[86:89]
	v_mfma_f32_16x16x32_bf16 v[70:73], v[134:137], v[194:197], v[70:73]
	v_mfma_f32_16x16x32_bf16 v[66:69], v[150:153], v[194:197], v[66:69]
	s_barrier
; #define PG8_STAGE(bufoff, gbase, voff) do { _Pragma("unroll") for (int _i = 0; _i < 2; ++_i) \
;         __builtin_amdgcn_global_load_lds((const unsigned*)((const char*)(gbase) + (voff)[_i]), (LAS unsigned*)(lds + (bufoff) + ldsw + _i * 8192), 16, 0, 0); } while (0)
; #define PG8_LDA(dst, b, h) do { _Pragma("unroll") for (int m = 0; m < 4; ++m) _Pragma("unroll") for (int k = 0; k < 2; ++k) dst[m][k] = *(const LAS bf16x8*)(lds + PG8_SA(b, h) + aoff + m * 2048 + k * 1024); } while (0)
; #define PG8_LDB(dst, b, h) do { _Pragma("unroll") for (int n = 0; n < 2; ++n) _Pragma("unroll") for (int k = 0; k < 2; ++k) dst[n][k] = *(const LAS bf16x8*)(lds + PG8_SB(b, h) + boff + n * 2048 + k * 1024); } while (0)
; #define PG8_MMA(ai, bj, At, Bt) do { __builtin_amdgcn_s_setprio(1); _Pragma("unroll") for (int m = 0; m < 4; ++m) _Pragma("unroll") for (int n = 0; n < 2; ++n) _Pragma("unroll") for (int k = 0; k < 2; ++k) \
;         acc[ai][bj][m][n] = __builtin_amdgcn_mfma_f32_16x16x32_bf16(Bt[n][k], At[m][k], acc[ai][bj][m][n], 0, 0, 0); __builtin_amdgcn_s_setprio(0); } while (0)
; #define PG8_WAIT_V(n) asm volatile("s_waitcnt vmcnt(" #n ")" ::: "memory")
; #define PG8_WAIT_L(n) asm volatile("s_waitcnt lgkmcnt(" #n ")" ::: "memory")
; #define PG8_BAR __builtin_amdgcn_s_barrier()
; #define PG8_SCHED __builtin_amdgcn_sched_barrier(0)
; template <class Epi, class Sched, int KC, bool ALIGN_EPI = false, bool SP2 = false, bool ATILED = false>
; __device__ __forceinline__ void gemm_phase(LAS unsigned char* lds, const Gemm g, const Sched& S, const Epi& E, int wave_s) {
;     ...
;             PG8_WAIT_V(8); PG8_WAIT_L(0); PG8_BAR; PG8_MMA(0, 0, At, B0); PG8_MMA(0, 1, At, B1); PG8_BAR; PG8_SCHED;
;             PG8_LDA(At, 0, 1); PG8_STAGE(PG8_SB(0, 0), b2, voffB); PG8_STAGE(PG8_SB(0, 1), b2 + hstepB, voffB); PG8_STAGE(PG8_SA(0, 0), a2, voffA);
;             PG8_WAIT_V(8); PG8_WAIT_L(0); PG8_BAR; PG8_MMA(1, 0, At, B0); PG8_MMA(1, 1, At, B1); PG8_BAR; PG8_SCHED;
;             PG8_LDB(B0, 1, 0); PG8_LDB(B1, 1, 1); PG8_SCHED; PG8_LDA(At, 1, 0); PG8_STAGE(PG8_SA(0, 1), a2 + hstepA, voffA);
;             PG8_WAIT_V(8); PG8_WAIT_L(0); PG8_BAR; PG8_MMA(0, 0, At, B0); PG8_MMA(0, 1, At, B1); PG8_BAR; PG8_SCHED;
	s_add_i32 s20, s53, s35
	s_mov_b32 m0, s20
	ds_read_b128 v[154:157], v251 offset:16384
	ds_read_b128 v[166:169], v251 offset:17408
	ds_read_b128 v[170:173], v251 offset:18432
	ds_read_b128 v[174:177], v251 offset:19456
	ds_read_b128 v[178:181], v251 offset:20480
	ds_read_b128 v[182:185], v251 offset:21504
	ds_read_b128 v[186:189], v251 offset:22528
	ds_read_b128 v[194:197], v251 offset:23552
	global_load_lds_dwordx4 v0, s[22:23]
	s_add_i32 m0, s20, 0x2000
	s_add_u32 s20, s22, 0x58000
	s_addc_u32 s21, s23, 0
	s_add_i32 s53, s54, s35
	global_load_lds_dwordx4 v198, s[22:23]
	s_mov_b32 m0, s53
	s_nop 0
	global_load_lds_dwordx4 v0, s[20:21]
	s_add_i32 m0, s53, 0x2000
	s_nop 0
	global_load_lds_dwordx4 v198, s[20:21]
	s_mov_b32 m0, s36
	s_nop 0
	global_load_lds_dwordx4 v190, s[24:25]
	s_mov_b32 m0, s37
	s_nop 0
	global_load_lds_dwordx4 v192, s[24:25]
	s_waitcnt vmcnt(32)
	s_waitcnt lgkmcnt(0)
	s_barrier
	v_mfma_f32_16x16x32_bf16 v[62:65], v[82:85], v[154:157], v[62:65]
	v_mfma_f32_16x16x32_bf16 v[58:61], v[106:109], v[154:157], v[58:61]
	v_mfma_f32_16x16x32_bf16 v[46:49], v[82:85], v[170:173], v[46:49]
	v_mfma_f32_16x16x32_bf16 v[42:45], v[106:109], v[170:173], v[42:45]
	v_mfma_f32_16x16x32_bf16 v[30:33], v[82:85], v[178:181], v[30:33]
	v_mfma_f32_16x16x32_bf16 v[26:29], v[106:109], v[178:181], v[26:29]
	v_mfma_f32_16x16x32_bf16 v[14:17], v[82:85], v[186:189], v[14:17]
	v_mfma_f32_16x16x32_bf16 v[10:13], v[106:109], v[186:189], v[10:13]
	v_mfma_f32_16x16x32_bf16 v[62:65], v[94:97], v[166:169], v[62:65]
	v_mfma_f32_16x16x32_bf16 v[58:61], v[114:117], v[166:169], v[58:61]
	v_mfma_f32_16x16x32_bf16 v[46:49], v[94:97], v[174:177], v[46:49]
	v_mfma_f32_16x16x32_bf16 v[42:45], v[114:117], v[174:177], v[42:45]
	v_mfma_f32_16x16x32_bf16 v[30:33], v[94:97], v[182:185], v[30:33]
	v_mfma_f32_16x16x32_bf16 v[26:29], v[114:117], v[182:185], v[26:29]
	v_mfma_f32_16x16x32_bf16 v[14:17], v[94:97], v[194:197], v[14:17]
	v_mfma_f32_16x16x32_bf16 v[10:13], v[114:117], v[194:197], v[10:13]
	v_mfma_f32_16x16x32_bf16 v[54:57], v[130:133], v[154:157], v[54:57]
	v_mfma_f32_16x16x32_bf16 v[50:53], v[146:149], v[154:157], v[50:53]
	v_mfma_f32_16x16x32_bf16 v[38:41], v[130:133], v[170:173], v[38:41]
	v_mfma_f32_16x16x32_bf16 v[34:37], v[146:149], v[170:173], v[34:37]
	v_mfma_f32_16x16x32_bf16 v[22:25], v[130:133], v[178:181], v[22:25]
	v_mfma_f32_16x16x32_bf16 v[18:21], v[146:149], v[178:181], v[18:21]
	v_mfma_f32_16x16x32_bf16 v[6:9], v[130:133], v[186:189], v[6:9]
	v_mfma_f32_16x16x32_bf16 v[2:5], v[146:149], v[186:189], v[2:5]
	v_mfma_f32_16x16x32_bf16 v[54:57], v[134:137], v[166:169], v[54:57]
	v_mfma_f32_16x16x32_bf16 v[50:53], v[150:153], v[166:169], v[50:53]
	v_mfma_f32_16x16x32_bf16 v[38:41], v[134:137], v[174:177], v[38:41]
	v_mfma_f32_16x16x32_bf16 v[34:37], v[150:153], v[174:177], v[34:37]
	v_mfma_f32_16x16x32_bf16 v[22:25], v[134:137], v[182:185], v[22:25]
	v_mfma_f32_16x16x32_bf16 v[18:21], v[150:153], v[182:185], v[18:21]
	v_mfma_f32_16x16x32_bf16 v[6:9], v[134:137], v[194:197], v[6:9]
	v_mfma_f32_16x16x32_bf16 v[2:5], v[150:153], v[194:197], v[2:5]
	s_barrier
	s_add_i32 s53, 0, 0x18000
	s_add_i32 s54, 0, 0x1c000
	v_add_u32_e32 v114, s53, v249
	v_add_u32_e32 v150, s54, v249
	ds_read_b128 v[82:85], v114
	ds_read_b128 v[94:97], v114 offset:1024
	ds_read_b128 v[106:109], v114 offset:2048
	ds_read_b128 v[114:117], v114 offset:3072
	ds_read_b128 v[130:133], v150
	ds_read_b128 v[134:137], v150 offset:1024
	ds_read_b128 v[146:149], v150 offset:2048
	ds_read_b128 v[150:153], v150 offset:3072
	s_add_u32 s20, s24, 0x160000
	s_addc_u32 s21, s25, 0
	s_mov_b32 m0, s38
	ds_read_b128 v[154:157], v251 offset:32768
	ds_read_b128 v[166:169], v251 offset:33792
	ds_read_b128 v[170:173], v251 offset:34816
	ds_read_b128 v[174:177], v251 offset:35840
	ds_read_b128 v[178:181], v251 offset:36864
	ds_read_b128 v[182:185], v251 offset:37888
	ds_read_b128 v[186:189], v251 offset:38912
	ds_read_b128 v[194:197], v251 offset:39936
	global_load_lds_dwordx4 v190, s[20:21]
	s_mov_b32 m0, s39
	s_nop 0
	global_load_lds_dwordx4 v192, s[20:21]
	s_waitcnt vmcnt(8)
	s_waitcnt lgkmcnt(0)
	s_barrier
	v_mfma_f32_16x16x32_bf16 v[162:165], v[82:85], v[154:157], v[162:165]
	v_mfma_f32_16x16x32_bf16 v[158:161], v[106:109], v[154:157], v[158:161]
	v_mfma_f32_16x16x32_bf16 v[126:129], v[82:85], v[170:173], v[126:129]
	v_mfma_f32_16x16x32_bf16 v[122:125], v[106:109], v[170:173], v[122:125]
	v_mfma_f32_16x16x32_bf16 v[102:105], v[82:85], v[178:181], v[102:105]
	v_mfma_f32_16x16x32_bf16 v[98:101], v[106:109], v[178:181], v[98:101]
	v_mfma_f32_16x16x32_bf16 v[78:81], v[82:85], v[186:189], v[78:81]
	v_mfma_f32_16x16x32_bf16 v[74:77], v[106:109], v[186:189], v[74:77]
	v_mfma_f32_16x16x32_bf16 v[162:165], v[94:97], v[166:169], v[162:165]
	v_mfma_f32_16x16x32_bf16 v[158:161], v[114:117], v[166:169], v[158:161]
	v_mfma_f32_16x16x32_bf16 v[126:129], v[94:97], v[174:177], v[126:129]
	v_mfma_f32_16x16x32_bf16 v[122:125], v[114:117], v[174:177], v[122:125]
	v_mfma_f32_16x16x32_bf16 v[102:105], v[94:97], v[182:185], v[102:105]
	v_mfma_f32_16x16x32_bf16 v[98:101], v[114:117], v[182:185], v[98:101]
	v_mfma_f32_16x16x32_bf16 v[78:81], v[94:97], v[194:197], v[78:81]
	v_mfma_f32_16x16x32_bf16 v[74:77], v[114:117], v[194:197], v[74:77]
	v_mfma_f32_16x16x32_bf16 v[142:145], v[130:133], v[154:157], v[142:145]
	v_mfma_f32_16x16x32_bf16 v[138:141], v[146:149], v[154:157], v[138:141]
	v_mfma_f32_16x16x32_bf16 v[118:121], v[130:133], v[170:173], v[118:121]
	v_mfma_f32_16x16x32_bf16 v[110:113], v[146:149], v[170:173], v[110:113]
	v_mfma_f32_16x16x32_bf16 v[90:93], v[130:133], v[178:181], v[90:93]
	v_mfma_f32_16x16x32_bf16 v[86:89], v[146:149], v[178:181], v[86:89]
	v_mfma_f32_16x16x32_bf16 v[70:73], v[130:133], v[186:189], v[70:73]
	v_mfma_f32_16x16x32_bf16 v[66:69], v[146:149], v[186:189], v[66:69]
	v_mfma_f32_16x16x32_bf16 v[142:145], v[134:137], v[166:169], v[142:145]
	v_mfma_f32_16x16x32_bf16 v[138:141], v[150:153], v[166:169], v[138:141]
	v_mfma_f32_16x16x32_bf16 v[118:121], v[134:137], v[174:177], v[118:121]
	v_mfma_f32_16x16x32_bf16 v[110:113], v[150:153], v[174:177], v[110:113]
	v_mfma_f32_16x16x32_bf16 v[90:93], v[134:137], v[182:185], v[90:93]
	v_mfma_f32_16x16x32_bf16 v[86:89], v[150:153], v[182:185], v[86:89]
	v_mfma_f32_16x16x32_bf16 v[70:73], v[134:137], v[194:197], v[70:73]
	v_mfma_f32_16x16x32_bf16 v[66:69], v[150:153], v[194:197], v[66:69]
	s_barrier
; #define PG8_STAGE(bufoff, gbase, voff) do { _Pragma("unroll") for (int _i = 0; _i < 2; ++_i) \
;         __builtin_amdgcn_global_load_lds((const unsigned*)((const char*)(gbase) + (voff)[_i]), (LAS unsigned*)(lds + (bufoff) + ldsw + _i * 8192), 16, 0, 0); } while (0)
; #define PG8_LDA(dst, b, h) do { _Pragma("unroll") for (int m = 0; m < 4; ++m) _Pragma("unroll") for (int k = 0; k < 2; ++k) dst[m][k] = *(const LAS bf16x8*)(lds + PG8_SA(b, h) + aoff + m * 2048 + k * 1024); } while (0)
; #define PG8_LDB(dst, b, h) do { _Pragma("unroll") for (int n = 0; n < 2; ++n) _Pragma("unroll") for (int k = 0; k < 2; ++k) dst[n][k] = *(const LAS bf16x8*)(lds + PG8_SB(b, h) + boff + n * 2048 + k * 1024); } while (0)
; #define PG8_MMA(ai, bj, At, Bt) do { __builtin_amdgcn_s_setprio(1); _Pragma("unroll") for (int m = 0; m < 4; ++m) _Pragma("unroll") for (int n = 0; n < 2; ++n) _Pragma("unroll") for (int k = 0; k < 2; ++k) \
;         acc[ai][bj][m][n] = __builtin_amdgcn_mfma_f32_16x16x32_bf16(Bt[n][k], At[m][k], acc[ai][bj][m][n], 0, 0, 0); __builtin_amdgcn_s_setprio(0); } while (0)
; #define PG8_WAIT_V(n) asm volatile("s_waitcnt vmcnt(" #n ")" ::: "memory")
; #define PG8_BAR __builtin_amdgcn_s_barrier()
; template <class Epi, class Sched, int KC, bool ALIGN_EPI = false, bool SP2 = false, bool ATILED = false>
; __device__ __forceinline__ void gemm_phase(LAS unsigned char* lds, const Gemm g, const Sched& S, const Epi& E, int wave_s) {
;     ...
;         for (int t = 0; t < nt; t += 2) {
;             const bool last = (t == nt - 2);
;             const char* a1 = cA + PG8_AOFF(t + 1);
;             const char* a2 = last ? nA : cA + PG8_AOFF(t + 2); const char* b2 = last ? nB : cB + (size_t)(t + 2) * kstep;
;             const char* a3 = a2 + kstep; const char* b3 = b2 + kstep;
;             if (last && has_next) S.a_ready(nxt);
;             if constexpr (SP2) {
;             PG8_LDB(B0, 0, 0); PG8_LDB(B1, 0, 1); PG8_SCHED; PG8_LDA(At, 0, 0); PG8_STAGE(PG8_SA(1, 1), a1 + hstepA, voffA);
;             PG8_WAIT_V(8); PG8_WAIT_L(0); PG8_BAR; PG8_MMA(0, 0, At, B0); PG8_MMA(0, 1, At, B1); PG8_BAR; PG8_SCHED;
;     ...
;             PG8_LDA(At, 1, 1); PG8_STAGE(PG8_SB(1, 0), b3, voffB); PG8_STAGE(PG8_SB(1, 1), b3 + hstepB, voffB); PG8_STAGE(PG8_SA(1, 0), a3, voffA);
;             PG8_WAIT_V(8); PG8_WAIT_L(0); PG8_BAR; PG8_MMA(1, 0, At, B0); PG8_MMA(1, 1, At, B1); PG8_BAR; PG8_SCHED;
	s_add_u32 s98, s22, 0x80
	s_addc_u32 s99, s23, 0
	s_add_u32 s100, s24, 0x80
	s_addc_u32 s101, s25, 0
	s_add_i32 s20, s53, s35
	s_mov_b32 m0, s20
	ds_read_b128 v[154:157], v251 offset:49152
	ds_read_b128 v[166:169], v251 offset:50176
	ds_read_b128 v[170:173], v251 offset:51200
	ds_read_b128 v[174:177], v251 offset:52224
	ds_read_b128 v[178:181], v251 offset:53248
	ds_read_b128 v[182:185], v251 offset:54272
	ds_read_b128 v[186:189], v251 offset:55296
	ds_read_b128 v[194:197], v251 offset:56320
	global_load_lds_dwordx4 v0, s[98:99]
	s_add_i32 m0, s20, 0x2000
	s_add_u32 s20, s22, 0x58080
	s_addc_u32 s21, s23, 0
	s_add_i32 s22, s54, s35
	global_load_lds_dwordx4 v198, s[98:99]
	s_mov_b32 m0, s22
	s_nop 0
	global_load_lds_dwordx4 v0, s[20:21]
	s_add_i32 m0, s22, 0x2000
	s_nop 0
	global_load_lds_dwordx4 v198, s[20:21]
	s_mov_b32 m0, s43
	s_nop 0
	global_load_lds_dwordx4 v190, s[100:101]
	s_mov_b32 m0, s44
	s_nop 0
	global_load_lds_dwordx4 v192, s[100:101]
	s_waitcnt vmcnt(8)
	s_waitcnt lgkmcnt(0)
	s_barrier
	v_mfma_f32_16x16x32_bf16 v[62:65], v[82:85], v[154:157], v[62:65]
	v_mfma_f32_16x16x32_bf16 v[58:61], v[106:109], v[154:157], v[58:61]
	v_mfma_f32_16x16x32_bf16 v[46:49], v[82:85], v[170:173], v[46:49]
	v_mfma_f32_16x16x32_bf16 v[42:45], v[106:109], v[170:173], v[42:45]
	v_mfma_f32_16x16x32_bf16 v[30:33], v[82:85], v[178:181], v[30:33]
	v_mfma_f32_16x16x32_bf16 v[26:29], v[106:109], v[178:181], v[26:29]
	v_mfma_f32_16x16x32_bf16 v[14:17], v[82:85], v[186:189], v[14:17]
	v_mfma_f32_16x16x32_bf16 v[10:13], v[106:109], v[186:189], v[10:13]
	v_mfma_f32_16x16x32_bf16 v[62:65], v[94:97], v[166:169], v[62:65]
	v_mfma_f32_16x16x32_bf16 v[58:61], v[114:117], v[166:169], v[58:61]
	v_mfma_f32_16x16x32_bf16 v[46:49], v[94:97], v[174:177], v[46:49]
	v_mfma_f32_16x16x32_bf16 v[42:45], v[114:117], v[174:177], v[42:45]
	v_mfma_f32_16x16x32_bf16 v[30:33], v[94:97], v[182:185], v[30:33]
	v_mfma_f32_16x16x32_bf16 v[26:29], v[114:117], v[182:185], v[26:29]
	v_mfma_f32_16x16x32_bf16 v[14:17], v[94:97], v[194:197], v[14:17]
	v_mfma_f32_16x16x32_bf16 v[10:13], v[114:117], v[194:197], v[10:13]
	v_mfma_f32_16x16x32_bf16 v[54:57], v[130:133], v[154:157], v[54:57]
	v_mfma_f32_16x16x32_bf16 v[50:53], v[146:149], v[154:157], v[50:53]
	v_mfma_f32_16x16x32_bf16 v[38:41], v[130:133], v[170:173], v[38:41]
	v_mfma_f32_16x16x32_bf16 v[34:37], v[146:149], v[170:173], v[34:37]
	v_mfma_f32_16x16x32_bf16 v[22:25], v[130:133], v[178:181], v[22:25]
	v_mfma_f32_16x16x32_bf16 v[18:21], v[146:149], v[178:181], v[18:21]
	v_mfma_f32_16x16x32_bf16 v[6:9], v[130:133], v[186:189], v[6:9]
	v_mfma_f32_16x16x32_bf16 v[2:5], v[146:149], v[186:189], v[2:5]
	v_mfma_f32_16x16x32_bf16 v[54:57], v[134:137], v[166:169], v[54:57]
	v_mfma_f32_16x16x32_bf16 v[50:53], v[150:153], v[166:169], v[50:53]
	v_mfma_f32_16x16x32_bf16 v[38:41], v[134:137], v[174:177], v[38:41]
	v_mfma_f32_16x16x32_bf16 v[34:37], v[150:153], v[174:177], v[34:37]
	v_mfma_f32_16x16x32_bf16 v[22:25], v[134:137], v[182:185], v[22:25]
	v_mfma_f32_16x16x32_bf16 v[18:21], v[150:153], v[182:185], v[18:21]
	v_mfma_f32_16x16x32_bf16 v[6:9], v[134:137], v[194:197], v[6:9]
	v_mfma_f32_16x16x32_bf16 v[2:5], v[150:153], v[194:197], v[2:5]
	s_barrier
	s_add_i32 s52, s52, 2
	s_add_u32 s50, s50, 0x100
	s_addc_u32 s51, s51, 0
	s_cmpk_gt_u32 s52, 0x55
	s_mov_b64 s[20:21], s[8:9]
.LBB0_318:
	s_add_u32 s8, s20, 0x100
	s_addc_u32 s9, s21, 0
	s_add_i32 s53, 0, 0x10000
	s_cmpk_eq_i32 s52, 0x54
	s_cselect_b32 s25, s17, s9
	s_cselect_b32 s24, s16, s8
	s_cselect_b32 s23, s11, s51
	s_cselect_b32 s22, s10, s50
	s_add_i32 s54, 0, 0x14000
	v_add_u32_e32 v114, s53, v249
	v_add_u32_e32 v150, s54, v249
	ds_read_b128 v[82:85], v114
	ds_read_b128 v[94:97], v114 offset:1024
	ds_read_b128 v[106:109], v114 offset:2048
	ds_read_b128 v[114:117], v114 offset:3072
	ds_read_b128 v[130:133], v150
	ds_read_b128 v[134:137], v150 offset:1024
	ds_read_b128 v[146:149], v150 offset:2048
	ds_read_b128 v[150:153], v150 offset:3072
	s_add_i32 m0, s36, 0xc000
	ds_read_b128 v[154:157], v251
	ds_read_b128 v[166:169], v251 offset:1024
	ds_read_b128 v[170:173], v251 offset:2048
	ds_read_b128 v[174:177], v251 offset:3072
	ds_read_b128 v[178:181], v251 offset:4096
	ds_read_b128 v[182:185], v251 offset:5120
	ds_read_b128 v[186:189], v251 offset:6144
	ds_read_b128 v[194:197], v251 offset:7168
	global_load_lds_dwordx4 v204, s[20:21]
	s_add_i32 m0, s36, 0xe000
	s_nop 0
	global_load_lds_dwordx4 v202, s[20:21]
	s_waitcnt vmcnt(8)
	s_waitcnt lgkmcnt(0)
	s_barrier
	v_mfma_f32_16x16x32_bf16 v[162:165], v[82:85], v[154:157], v[162:165]
	v_mfma_f32_16x16x32_bf16 v[158:161], v[106:109], v[154:157], v[158:161]
	v_mfma_f32_16x16x32_bf16 v[126:129], v[82:85], v[170:173], v[126:129]
	v_mfma_f32_16x16x32_bf16 v[122:125], v[106:109], v[170:173], v[122:125]
	v_mfma_f32_16x16x32_bf16 v[102:105], v[82:85], v[178:181], v[102:105]
	v_mfma_f32_16x16x32_bf16 v[98:101], v[106:109], v[178:181], v[98:101]
	v_mfma_f32_16x16x32_bf16 v[78:81], v[82:85], v[186:189], v[78:81]
	v_mfma_f32_16x16x32_bf16 v[74:77], v[106:109], v[186:189], v[74:77]
	v_mfma_f32_16x16x32_bf16 v[162:165], v[94:97], v[166:169], v[162:165]
	v_mfma_f32_16x16x32_bf16 v[158:161], v[114:117], v[166:169], v[158:161]
	v_mfma_f32_16x16x32_bf16 v[126:129], v[94:97], v[174:177], v[126:129]
	v_mfma_f32_16x16x32_bf16 v[122:125], v[114:117], v[174:177], v[122:125]
	v_mfma_f32_16x16x32_bf16 v[102:105], v[94:97], v[182:185], v[102:105]
	v_mfma_f32_16x16x32_bf16 v[98:101], v[114:117], v[182:185], v[98:101]
	v_mfma_f32_16x16x32_bf16 v[78:81], v[94:97], v[194:197], v[78:81]
	v_mfma_f32_16x16x32_bf16 v[74:77], v[114:117], v[194:197], v[74:77]
	v_mfma_f32_16x16x32_bf16 v[142:145], v[130:133], v[154:157], v[142:145]
	v_mfma_f32_16x16x32_bf16 v[138:141], v[146:149], v[154:157], v[138:141]
	v_mfma_f32_16x16x32_bf16 v[118:121], v[130:133], v[170:173], v[118:121]
	v_mfma_f32_16x16x32_bf16 v[110:113], v[146:149], v[170:173], v[110:113]
	v_mfma_f32_16x16x32_bf16 v[90:93], v[130:133], v[178:181], v[90:93]
	v_mfma_f32_16x16x32_bf16 v[86:89], v[146:149], v[178:181], v[86:89]
	v_mfma_f32_16x16x32_bf16 v[70:73], v[130:133], v[186:189], v[70:73]
	v_mfma_f32_16x16x32_bf16 v[66:69], v[146:149], v[186:189], v[66:69]
	v_mfma_f32_16x16x32_bf16 v[142:145], v[134:137], v[166:169], v[142:145]
	v_mfma_f32_16x16x32_bf16 v[138:141], v[150:153], v[166:169], v[138:141]
	v_mfma_f32_16x16x32_bf16 v[118:121], v[134:137], v[174:177], v[118:121]
	v_mfma_f32_16x16x32_bf16 v[110:113], v[150:153], v[174:177], v[110:113]
	v_mfma_f32_16x16x32_bf16 v[90:93], v[134:137], v[182:185], v[90:93]
	v_mfma_f32_16x16x32_bf16 v[86:89], v[150:153], v[182:185], v[86:89]
	v_mfma_f32_16x16x32_bf16 v[70:73], v[134:137], v[194:197], v[70:73]
	v_mfma_f32_16x16x32_bf16 v[66:69], v[150:153], v[194:197], v[66:69]
	s_barrier
; #define PG8_STAGE(bufoff, gbase, voff) do { _Pragma("unroll") for (int _i = 0; _i < 2; ++_i) \
;         __builtin_amdgcn_global_load_lds((const unsigned*)((const char*)(gbase) + (voff)[_i]), (LAS unsigned*)(lds + (bufoff) + ldsw + _i * 8192), 16, 0, 0); } while (0)
; #define PG8_LDA(dst, b, h) do { _Pragma("unroll") for (int m = 0; m < 4; ++m) _Pragma("unroll") for (int k = 0; k < 2; ++k) dst[m][k] = *(const LAS bf16x8*)(lds + PG8_SA(b, h) + aoff + m * 2048 + k * 1024); } while (0)
; #define PG8_LDB(dst, b, h) do { _Pragma("unroll") for (int n = 0; n < 2; ++n) _Pragma("unroll") for (int k = 0; k < 2; ++k) dst[n][k] = *(const LAS bf16x8*)(lds + PG8_SB(b, h) + boff + n * 2048 + k * 1024); } while (0)
; #define PG8_MMA(ai, bj, At, Bt) do { __builtin_amdgcn_s_setprio(1); _Pragma("unroll") for (int m = 0; m < 4; ++m) _Pragma("unroll") for (int n = 0; n < 2; ++n) _Pragma("unroll") for (int k = 0; k < 2; ++k) \
;         acc[ai][bj][m][n] = __builtin_amdgcn_mfma_f32_16x16x32_bf16(Bt[n][k], At[m][k], acc[ai][bj][m][n], 0, 0, 0); __builtin_amdgcn_s_setprio(0); } while (0)
; #define PG8_WAIT_V(n) asm volatile("s_waitcnt vmcnt(" #n ")" ::: "memory")
; #define PG8_WAIT_L(n) asm volatile("s_waitcnt lgkmcnt(" #n ")" ::: "memory")
; #define PG8_BAR __builtin_amdgcn_s_barrier()
; #define PG8_SCHED __builtin_amdgcn_sched_barrier(0)
; template <class Epi, class Sched, int KC, bool ALIGN_EPI = false, bool SP2 = false, bool ATILED = false>
; __device__ __forceinline__ void gemm_phase(LAS unsigned char* lds, const Gemm g, const Sched& S, const Epi& E, int wave_s) {
;     ...
;             PG8_WAIT_V(8); PG8_WAIT_L(0); PG8_BAR; PG8_MMA(0, 0, At, B0); PG8_MMA(0, 1, At, B1); PG8_BAR; PG8_SCHED;
;             PG8_LDA(At, 0, 1); PG8_STAGE(PG8_SB(0, 0), b2, voffB); PG8_STAGE(PG8_SB(0, 1), b2 + hstepB, voffB); PG8_STAGE(PG8_SA(0, 0), a2, voffA);
;             PG8_WAIT_V(8); PG8_WAIT_L(0); PG8_BAR; PG8_MMA(1, 0, At, B0); PG8_MMA(1, 1, At, B1); PG8_BAR; PG8_SCHED;
;             PG8_LDB(B0, 1, 0); PG8_LDB(B1, 1, 1); PG8_SCHED; PG8_LDA(At, 1, 0); PG8_STAGE(PG8_SA(0, 1), a2 + hstepA, voffA);
;             PG8_WAIT_V(8); PG8_WAIT_L(0); PG8_BAR; PG8_MMA(0, 0, At, B0); PG8_MMA(0, 1, At, B1); PG8_BAR; PG8_SCHED;
	s_add_i32 s20, s53, s35
	s_mov_b32 m0, s20
	ds_read_b128 v[154:157], v251 offset:16384
	ds_read_b128 v[166:169], v251 offset:17408
	ds_read_b128 v[170:173], v251 offset:18432
	ds_read_b128 v[174:177], v251 offset:19456
	ds_read_b128 v[178:181], v251 offset:20480
	ds_read_b128 v[182:185], v251 offset:21504
	ds_read_b128 v[186:189], v251 offset:22528
	ds_read_b128 v[194:197], v251 offset:23552
	global_load_lds_dwordx4 v0, s[22:23]
	s_add_i32 m0, s20, 0x2000
	s_add_u32 s20, s22, 0x58000
	s_addc_u32 s21, s23, 0
	s_add_i32 s53, s54, s35
	global_load_lds_dwordx4 v198, s[22:23]
	s_mov_b32 m0, s53
	s_nop 0
	global_load_lds_dwordx4 v0, s[20:21]
	s_add_i32 m0, s53, 0x2000
	s_nop 0
	global_load_lds_dwordx4 v198, s[20:21]
	s_mov_b32 m0, s36
	s_nop 0
	global_load_lds_dwordx4 v190, s[24:25]
	s_mov_b32 m0, s37
	s_nop 0
	global_load_lds_dwordx4 v192, s[24:25]
	s_waitcnt vmcnt(8)
	s_waitcnt lgkmcnt(0)
	s_barrier
	v_mfma_f32_16x16x32_bf16 v[62:65], v[82:85], v[154:157], v[62:65]
	v_mfma_f32_16x16x32_bf16 v[58:61], v[106:109], v[154:157], v[58:61]
	v_mfma_f32_16x16x32_bf16 v[46:49], v[82:85], v[170:173], v[46:49]
	v_mfma_f32_16x16x32_bf16 v[42:45], v[106:109], v[170:173], v[42:45]
	v_mfma_f32_16x16x32_bf16 v[30:33], v[82:85], v[178:181], v[30:33]
	v_mfma_f32_16x16x32_bf16 v[26:29], v[106:109], v[178:181], v[26:29]
	v_mfma_f32_16x16x32_bf16 v[14:17], v[82:85], v[186:189], v[14:17]
	v_mfma_f32_16x16x32_bf16 v[10:13], v[106:109], v[186:189], v[10:13]
	v_mfma_f32_16x16x32_bf16 v[62:65], v[94:97], v[166:169], v[62:65]
	v_mfma_f32_16x16x32_bf16 v[58:61], v[114:117], v[166:169], v[58:61]
	v_mfma_f32_16x16x32_bf16 v[46:49], v[94:97], v[174:177], v[46:49]
	v_mfma_f32_16x16x32_bf16 v[42:45], v[114:117], v[174:177], v[42:45]
	v_mfma_f32_16x16x32_bf16 v[30:33], v[94:97], v[182:185], v[30:33]
	v_mfma_f32_16x16x32_bf16 v[26:29], v[114:117], v[182:185], v[26:29]
	v_mfma_f32_16x16x32_bf16 v[14:17], v[94:97], v[194:197], v[14:17]
	v_mfma_f32_16x16x32_bf16 v[10:13], v[114:117], v[194:197], v[10:13]
	v_mfma_f32_16x16x32_bf16 v[54:57], v[130:133], v[154:157], v[54:57]
	v_mfma_f32_16x16x32_bf16 v[50:53], v[146:149], v[154:157], v[50:53]
	v_mfma_f32_16x16x32_bf16 v[38:41], v[130:133], v[170:173], v[38:41]
	v_mfma_f32_16x16x32_bf16 v[34:37], v[146:149], v[170:173], v[34:37]
	v_mfma_f32_16x16x32_bf16 v[22:25], v[130:133], v[178:181], v[22:25]
	v_mfma_f32_16x16x32_bf16 v[18:21], v[146:149], v[178:181], v[18:21]
	v_mfma_f32_16x16x32_bf16 v[6:9], v[130:133], v[186:189], v[6:9]
	v_mfma_f32_16x16x32_bf16 v[2:5], v[146:149], v[186:189], v[2:5]
	v_mfma_f32_16x16x32_bf16 v[54:57], v[134:137], v[166:169], v[54:57]
	v_mfma_f32_16x16x32_bf16 v[50:53], v[150:153], v[166:169], v[50:53]
	v_mfma_f32_16x16x32_bf16 v[38:41], v[134:137], v[174:177], v[38:41]
	v_mfma_f32_16x16x32_bf16 v[34:37], v[150:153], v[174:177], v[34:37]
	v_mfma_f32_16x16x32_bf16 v[22:25], v[134:137], v[182:185], v[22:25]
	v_mfma_f32_16x16x32_bf16 v[18:21], v[150:153], v[182:185], v[18:21]
	v_mfma_f32_16x16x32_bf16 v[6:9], v[134:137], v[194:197], v[6:9]
	v_mfma_f32_16x16x32_bf16 v[2:5], v[150:153], v[194:197], v[2:5]
	s_barrier
	s_add_i32 s53, 0, 0x18000
	s_add_i32 s54, 0, 0x1c000
	v_add_u32_e32 v114, s53, v249
	v_add_u32_e32 v150, s54, v249
	ds_read_b128 v[82:85], v114
	ds_read_b128 v[94:97], v114 offset:1024
	ds_read_b128 v[106:109], v114 offset:2048
	ds_read_b128 v[114:117], v114 offset:3072
	ds_read_b128 v[130:133], v150
	ds_read_b128 v[134:137], v150 offset:1024
	ds_read_b128 v[146:149], v150 offset:2048
	ds_read_b128 v[150:153], v150 offset:3072
	s_add_u32 s20, s24, 0x160000
	s_addc_u32 s21, s25, 0
	s_mov_b32 m0, s38
	ds_read_b128 v[154:157], v251 offset:32768
	ds_read_b128 v[166:169], v251 offset:33792
	ds_read_b128 v[170:173], v251 offset:34816
	ds_read_b128 v[174:177], v251 offset:35840
	ds_read_b128 v[178:181], v251 offset:36864
	ds_read_b128 v[182:185], v251 offset:37888
	ds_read_b128 v[186:189], v251 offset:38912
	ds_read_b128 v[194:197], v251 offset:39936
	global_load_lds_dwordx4 v190, s[20:21]
	s_mov_b32 m0, s39
	s_nop 0
	global_load_lds_dwordx4 v192, s[20:21]
	s_waitcnt vmcnt(8)
	s_waitcnt lgkmcnt(0)
	s_barrier
	v_mfma_f32_16x16x32_bf16 v[162:165], v[82:85], v[154:157], v[162:165]
	v_mfma_f32_16x16x32_bf16 v[158:161], v[106:109], v[154:157], v[158:161]
	v_mfma_f32_16x16x32_bf16 v[126:129], v[82:85], v[170:173], v[126:129]
	v_mfma_f32_16x16x32_bf16 v[122:125], v[106:109], v[170:173], v[122:125]
	v_mfma_f32_16x16x32_bf16 v[102:105], v[82:85], v[178:181], v[102:105]
	v_mfma_f32_16x16x32_bf16 v[98:101], v[106:109], v[178:181], v[98:101]
	v_mfma_f32_16x16x32_bf16 v[78:81], v[82:85], v[186:189], v[78:81]
	v_mfma_f32_16x16x32_bf16 v[74:77], v[106:109], v[186:189], v[74:77]
	v_mfma_f32_16x16x32_bf16 v[162:165], v[94:97], v[166:169], v[162:165]
	v_mfma_f32_16x16x32_bf16 v[158:161], v[114:117], v[166:169], v[158:161]
	v_mfma_f32_16x16x32_bf16 v[126:129], v[94:97], v[174:177], v[126:129]
	v_mfma_f32_16x16x32_bf16 v[122:125], v[114:117], v[174:177], v[122:125]
	v_mfma_f32_16x16x32_bf16 v[102:105], v[94:97], v[182:185], v[102:105]
	v_mfma_f32_16x16x32_bf16 v[98:101], v[114:117], v[182:185], v[98:101]
	v_mfma_f32_16x16x32_bf16 v[78:81], v[94:97], v[194:197], v[78:81]
	v_mfma_f32_16x16x32_bf16 v[74:77], v[114:117], v[194:197], v[74:77]
	v_mfma_f32_16x16x32_bf16 v[142:145], v[130:133], v[154:157], v[142:145]
	v_mfma_f32_16x16x32_bf16 v[138:141], v[146:149], v[154:157], v[138:141]
	v_mfma_f32_16x16x32_bf16 v[118:121], v[130:133], v[170:173], v[118:121]
	v_mfma_f32_16x16x32_bf16 v[110:113], v[146:149], v[170:173], v[110:113]
	v_mfma_f32_16x16x32_bf16 v[90:93], v[130:133], v[178:181], v[90:93]
	v_mfma_f32_16x16x32_bf16 v[86:89], v[146:149], v[178:181], v[86:89]
	v_mfma_f32_16x16x32_bf16 v[70:73], v[130:133], v[186:189], v[70:73]
	v_mfma_f32_16x16x32_bf16 v[66:69], v[146:149], v[186:189], v[66:69]
	v_mfma_f32_16x16x32_bf16 v[142:145], v[134:137], v[166:169], v[142:145]
	v_mfma_f32_16x16x32_bf16 v[138:141], v[150:153], v[166:169], v[138:141]
	v_mfma_f32_16x16x32_bf16 v[118:121], v[134:137], v[174:177], v[118:121]
	v_mfma_f32_16x16x32_bf16 v[110:113], v[150:153], v[174:177], v[110:113]
	v_mfma_f32_16x16x32_bf16 v[90:93], v[134:137], v[182:185], v[90:93]
	v_mfma_f32_16x16x32_bf16 v[86:89], v[150:153], v[182:185], v[86:89]
	v_mfma_f32_16x16x32_bf16 v[70:73], v[134:137], v[194:197], v[70:73]
	v_mfma_f32_16x16x32_bf16 v[66:69], v[150:153], v[194:197], v[66:69]
	s_barrier
; #define GAS __attribute__((address_space(1)))
; #define PG8_BAR __builtin_amdgcn_s_barrier()
;     DI void operator()(const f32x4 (&acc)[2][2][4][2], const Unit& u, int wr, int wc, int fr, int fq) const {
;         const int row0 = u.pm * BM + wr * 64 + fr, col0 = u.pn * BM + wc * 64 + 8 * fq;
;         const size_t hbase = (size_t)u.pn * ((size_t)M * 256) + wc * 64 + 8 * fq;
;         u32x4 H[2][4][2];
; #pragma unroll
;         for (int ai = 0; ai < 2; ++ai)
; #pragma unroll
;             for (int m = 0; m < 4; ++m)
; #pragma unroll
;                 for (int bj = 0; bj < 2; ++bj) H[ai][m][bj] = *(const GAS u32x4*)(hi + hbase + (size_t)(row0 + ai * HALF + m * 16) * 256 + bj * 32);
;         asm volatile("" ::: "memory");
; #pragma unroll
;         for (int ai = 0; ai < 2; ++ai) {
; #pragma unroll
;             for (int m = 0; m < 4; ++m) {
;                 const int r = row0 + ai * HALF + m * 16; const size_t off = (size_t)r * DM + col0; float ss = 0.f;
; #pragma unroll
;                 for (int bj = 0; bj < 2; ++bj) {
;                     const u32x4 h = H[ai][m][bj];
;                     const f32x4 a0 = acc[ai][bj][m][0], a1 = acc[ai][bj][m][1];
;                     float v[8];
;                     v[0] = bflo(h.x) + a0[0] * scale; v[1] = bfhi(h.x) + a0[1] * scale;
;                     v[2] = bflo(h.y) + a0[2] * scale; v[3] = bfhi(h.y) + a0[3] * scale;
;                     v[4] = bflo(h.z) + a1[0] * scale; v[5] = bfhi(h.z) + a1[1] * scale;
;                     v[6] = bflo(h.w) + a1[2] * scale; v[7] = bfhi(h.w) + a1[3] * scale;
; #pragma unroll
;                     for (int e = 0; e < 8; ++e) ss += v[e] * v[e];
;                     u32x4 nh;
;                     nh.x = cvtpk(v[0], v[1]); nh.y = cvtpk(v[2], v[3]); nh.z = cvtpk(v[4], v[5]); nh.w = cvtpk(v[6], v[7]);
;                     *(GAS u32x4*)(hi + hbase + (size_t)r * 256 + bj * 32) = nh;
; template <class Epi, class Sched, int KC, bool ALIGN_EPI = false, bool SP2 = false, bool ATILED = false>
; __device__ __forceinline__ void gemm_phase(LAS unsigned char* lds, const Gemm g, const Sched& S, const Epi& E, int wave_s) {
;     ...
;             PG8_LDA(At, 1, 1); PG8_STAGE(PG8_SB(1, 0), b3, voffB); PG8_STAGE(PG8_SB(1, 1), b3 + hstepB, voffB); PG8_STAGE(PG8_SA(1, 0), a3, voffA);
;             PG8_WAIT_V(8); PG8_WAIT_L(0); PG8_BAR; PG8_MMA(1, 0, At, B0); PG8_MMA(1, 1, At, B1); PG8_BAR; PG8_SCHED;
	s_add_u32 s98, s22, 0x80
	s_addc_u32 s99, s23, 0
	s_add_u32 s100, s24, 0x80
	s_addc_u32 s101, s25, 0
	s_add_i32 s20, s53, s35
	s_mov_b32 m0, s20
	ds_read_b128 v[154:157], v251 offset:49152
	ds_read_b128 v[166:169], v251 offset:50176
	ds_read_b128 v[170:173], v251 offset:51200
	ds_read_b128 v[174:177], v251 offset:52224
	ds_read_b128 v[178:181], v251 offset:53248
	ds_read_b128 v[182:185], v251 offset:54272
	ds_read_b128 v[186:189], v251 offset:55296
	ds_read_b128 v[194:197], v251 offset:56320
	global_load_lds_dwordx4 v0, s[98:99]
	s_add_i32 m0, s20, 0x2000
	s_add_u32 s20, s22, 0x58080
	s_addc_u32 s21, s23, 0
	s_add_i32 s22, s54, s35
	global_load_lds_dwordx4 v198, s[98:99]
	s_mov_b32 m0, s22
	s_nop 0
	global_load_lds_dwordx4 v0, s[20:21]
	s_add_i32 m0, s22, 0x2000
	s_nop 0
	global_load_lds_dwordx4 v198, s[20:21]
	s_mov_b32 m0, s43
	s_nop 0
	global_load_lds_dwordx4 v190, s[100:101]
	s_mov_b32 m0, s44
	s_nop 0
	global_load_lds_dwordx4 v192, s[100:101]
	s_waitcnt vmcnt(8)
	s_waitcnt lgkmcnt(0)
	s_barrier
	v_mfma_f32_16x16x32_bf16 v[62:65], v[82:85], v[154:157], v[62:65]
	v_mfma_f32_16x16x32_bf16 v[58:61], v[106:109], v[154:157], v[58:61]
	v_mfma_f32_16x16x32_bf16 v[46:49], v[82:85], v[170:173], v[46:49]
	v_mfma_f32_16x16x32_bf16 v[42:45], v[106:109], v[170:173], v[42:45]
	v_mfma_f32_16x16x32_bf16 v[30:33], v[82:85], v[178:181], v[30:33]
	v_mfma_f32_16x16x32_bf16 v[26:29], v[106:109], v[178:181], v[26:29]
	v_mfma_f32_16x16x32_bf16 v[14:17], v[82:85], v[186:189], v[14:17]
	v_mfma_f32_16x16x32_bf16 v[10:13], v[106:109], v[186:189], v[10:13]
	v_mfma_f32_16x16x32_bf16 v[62:65], v[94:97], v[166:169], v[62:65]
	v_mfma_f32_16x16x32_bf16 v[58:61], v[114:117], v[166:169], v[58:61]
	v_mfma_f32_16x16x32_bf16 v[46:49], v[94:97], v[174:177], v[46:49]
	v_mfma_f32_16x16x32_bf16 v[42:45], v[114:117], v[174:177], v[42:45]
	v_mfma_f32_16x16x32_bf16 v[30:33], v[94:97], v[182:185], v[30:33]
	v_mfma_f32_16x16x32_bf16 v[26:29], v[114:117], v[182:185], v[26:29]
	v_mfma_f32_16x16x32_bf16 v[14:17], v[94:97], v[194:197], v[14:17]
	v_mfma_f32_16x16x32_bf16 v[10:13], v[114:117], v[194:197], v[10:13]
	v_mfma_f32_16x16x32_bf16 v[54:57], v[130:133], v[154:157], v[54:57]
	v_mfma_f32_16x16x32_bf16 v[50:53], v[146:149], v[154:157], v[50:53]
	v_mfma_f32_16x16x32_bf16 v[38:41], v[130:133], v[170:173], v[38:41]
	v_mfma_f32_16x16x32_bf16 v[34:37], v[146:149], v[170:173], v[34:37]
	v_mfma_f32_16x16x32_bf16 v[22:25], v[130:133], v[178:181], v[22:25]
	v_mfma_f32_16x16x32_bf16 v[18:21], v[146:149], v[178:181], v[18:21]
	v_mfma_f32_16x16x32_bf16 v[6:9], v[130:133], v[186:189], v[6:9]
	v_mfma_f32_16x16x32_bf16 v[2:5], v[146:149], v[186:189], v[2:5]
	v_mfma_f32_16x16x32_bf16 v[54:57], v[134:137], v[166:169], v[54:57]
	v_mfma_f32_16x16x32_bf16 v[50:53], v[150:153], v[166:169], v[50:53]
	v_mfma_f32_16x16x32_bf16 v[38:41], v[134:137], v[174:177], v[38:41]
	v_mfma_f32_16x16x32_bf16 v[34:37], v[150:153], v[174:177], v[34:37]
	v_mfma_f32_16x16x32_bf16 v[22:25], v[134:137], v[182:185], v[22:25]
	v_mfma_f32_16x16x32_bf16 v[18:21], v[150:153], v[182:185], v[18:21]
	v_mfma_f32_16x16x32_bf16 v[6:9], v[134:137], v[194:197], v[6:9]
	v_mfma_f32_16x16x32_bf16 v[2:5], v[150:153], v[194:197], v[2:5]
	s_barrier
	s_add_i32 s52, s52, 2
	s_add_u32 s50, s50, 0x100
	s_addc_u32 s51, s51, 0
	s_cmpk_gt_u32 s52, 0x55
	s_mov_b64 s[20:21], s[8:9]
	s_cbranch_scc0 .LBB0_318
	v_lshl_add_u32 v206, s19, 8, v248
	s_ashr_i32 s19, s18, 31
	s_lshl_b64 s[8:9], s[18:19], 23
	v_ashrrev_i32_e32 v207, 31, v206
	v_or_b32_e32 v236, 16, v206
	v_lshl_add_u64 v[82:83], v[200:201], 0, s[8:9]
	v_lshlrev_b64 v[84:85], 9, v[206:207]
	v_ashrrev_i32_e32 v237, 31, v236
	v_or_b32_e32 v232, 32, v206
	v_lshl_add_u64 v[238:239], v[82:83], 0, v[84:85]
	v_lshlrev_b64 v[84:85], 9, v[236:237]
	v_ashrrev_i32_e32 v233, 31, v232
	v_or_b32_e32 v228, 48, v206
	v_lshl_add_u64 v[234:235], v[82:83], 0, v[84:85]
	v_lshlrev_b64 v[84:85], 9, v[232:233]
	v_ashrrev_i32_e32 v229, 31, v228
	v_add_u32_e32 v224, 0x80, v206
	v_lshl_add_u64 v[230:231], v[82:83], 0, v[84:85]
	v_lshlrev_b64 v[84:85], 9, v[228:229]
	v_ashrrev_i32_e32 v225, 31, v224
	v_add_u32_e32 v220, 0x90, v206
	global_load_dwordx4 v[194:197], v[238:239], off
	global_load_dwordx4 v[186:189], v[238:239], off offset:64
	v_lshl_add_u64 v[226:227], v[82:83], 0, v[84:85]
	v_lshlrev_b64 v[84:85], 9, v[224:225]
	v_ashrrev_i32_e32 v221, 31, v220
	v_add_u32_e32 v216, 0xa0, v206
	v_lshl_add_u64 v[222:223], v[82:83], 0, v[84:85]
	v_lshlrev_b64 v[84:85], 9, v[220:221]
	v_ashrrev_i32_e32 v217, 31, v216
	v_add_u32_e32 v210, 0xb0, v206
	v_lshl_add_u64 v[218:219], v[82:83], 0, v[84:85]
	v_lshlrev_b64 v[84:85], 9, v[216:217]
	v_ashrrev_i32_e32 v211, 31, v210
	v_lshl_add_u64 v[214:215], v[82:83], 0, v[84:85]
	v_lshlrev_b64 v[84:85], 9, v[210:211]
	v_lshl_add_u64 v[208:209], v[82:83], 0, v[84:85]
	global_load_dwordx4 v[182:185], v[234:235], off
	global_load_dwordx4 v[178:181], v[234:235], off offset:64
	global_load_dwordx4 v[174:177], v[230:231], off
	global_load_dwordx4 v[170:173], v[230:231], off offset:64
	global_load_dwordx4 v[166:169], v[226:227], off
	global_load_dwordx4 v[154:157], v[226:227], off offset:64
	global_load_dwordx4 v[150:153], v[222:223], off
	global_load_dwordx4 v[146:149], v[222:223], off offset:64
	global_load_dwordx4 v[134:137], v[218:219], off
	global_load_dwordx4 v[130:133], v[218:219], off offset:64
	global_load_dwordx4 v[114:117], v[214:215], off
	global_load_dwordx4 v[106:109], v[214:215], off offset:64
	global_load_dwordx4 v[94:97], v[208:209], off
	global_load_dwordx4 v[82:85], v[208:209], off offset:64
	v_lshl_or_b32 v212, s18, 8, v250
	v_ashrrev_i32_e32 v213, 31, v212
	v_lshlrev_b64 v[240:241], 11, v[206:207]
	v_lshl_add_u64 v[240:241], v[240:241], 0, v[212:213]
	s_andn2_b64 vcc, exec, s[14:15]
	v_lshl_add_u64 v[240:241], v[240:241], 2, s[12:13]
	s_waitcnt vmcnt(0)
	v_lshlrev_b32_e32 v252, 16, v194
	v_and_b32_e32 v253, 0xffff0000, v194
	v_lshlrev_b32_e32 v194, 16, v195
	v_and_b32_e32 v195, 0xffff0000, v195
	v_pk_fma_f32 v[164:165], v[164:165], 0.5, v[194:195] op_sel_hi:[1,0,1]
	v_lshlrev_b32_e32 v194, 16, v196
	v_and_b32_e32 v195, 0xffff0000, v196
	v_pk_fma_f32 v[158:159], v[158:159], 0.5, v[194:195] op_sel_hi:[1,0,1]
	v_lshlrev_b32_e32 v194, 16, v197
	v_and_b32_e32 v195, 0xffff0000, v197
	v_pk_fma_f32 v[162:163], v[162:163], 0.5, v[252:253] op_sel_hi:[1,0,1]
	v_pk_fma_f32 v[160:161], v[160:161], 0.5, v[194:195] op_sel_hi:[1,0,1]
	v_cvt_pk_bf16_f32 v194, v162, v163
	v_cvt_pk_bf16_f32 v195, v164, v165
	v_cvt_pk_bf16_f32 v196, v158, v159
	s_nop 0
	v_cvt_pk_bf16_f32 v197, v160, v161
	global_store_dwordx4 v[238:239], v[194:197], off
	s_nop 1
	v_cndmask_b32_e64 v194, 0, 1, s[14:15]
	v_cmp_ne_u32_e64 s[8:9], 1, v194
	s_cbranch_vccnz .LBB0_321
	global_store_dwordx4 v[240:241], v[162:165], off
	global_store_dwordx4 v[240:241], v[158:161], off offset:16

; #define PG8_STAGE(bufoff, gbase, voff) do { _Pragma("unroll") for (int _i = 0; _i < 2; ++_i) \
;         __builtin_amdgcn_global_load_lds((const unsigned*)((const char*)(gbase) + (voff)[_i]), (LAS unsigned*)(lds + (bufoff) + ldsw + _i * 8192), 16, 0, 0); } while (0)
; #define PG8_LDA(dst, b, h) do { _Pragma("unroll") for (int m = 0; m < 4; ++m) _Pragma("unroll") for (int k = 0; k < 2; ++k) dst[m][k] = *(const LAS bf16x8*)(lds + PG8_SA(b, h) + aoff + m * 2048 + k * 1024); } while (0)
; #define PG8_LDB(dst, b, h) do { _Pragma("unroll") for (int n = 0; n < 2; ++n) _Pragma("unroll") for (int k = 0; k < 2; ++k) dst[n][k] = *(const LAS bf16x8*)(lds + PG8_SB(b, h) + boff + n * 2048 + k * 1024); } while (0)
; #define PG8_WAIT_V(n) asm volatile("s_waitcnt vmcnt(" #n ")" ::: "memory")
; #define PG8_WAIT_L(n) asm volatile("s_waitcnt lgkmcnt(" #n ")" ::: "memory")
; #define PG8_BAR __builtin_amdgcn_s_barrier()
; #define PG8_SCHED __builtin_amdgcn_sched_barrier(0)
; template <class Epi, class Sched, int KC, bool ALIGN_EPI = false, bool SP2 = false, bool ATILED = false>
; __device__ __forceinline__ void gemm_phase(LAS unsigned char* lds, const Gemm g, const Sched& S, const Epi& E, int wave_s) {
;     ...
;         const bool has_next = S.next(ui + 1, nxt);
;         const char* nA = has_next ? (const char*)g.A + (size_t)nxt.pm * tstepA : cA; const char* nB = has_next ? (const char*)g.Bt + (size_t)nxt.pn * tstep : cB;
;         for (int t = 0; t < nt; t += 2) {
;             const bool last = (t == nt - 2);
;             const char* a1 = cA + PG8_AOFF(t + 1);
;             const char* a2 = last ? nA : cA + PG8_AOFF(t + 2); const char* b2 = last ? nB : cB + (size_t)(t + 2) * kstep;
;             const char* a3 = a2 + kstep; const char* b3 = b2 + kstep;
;             if (last && has_next) S.a_ready(nxt);
;             if constexpr (SP2) {
;             PG8_LDB(B0, 0, 0); PG8_LDB(B1, 0, 1); PG8_SCHED; PG8_LDA(At, 0, 0); PG8_STAGE(PG8_SA(1, 1), a1 + hstepA, voffA);
;             PG8_WAIT_V(8); PG8_WAIT_L(0); PG8_BAR; PG8_MMA(0, 0, At, B0); PG8_MMA(0, 1, At, B1); PG8_BAR; PG8_SCHED;
;     ...
; #pragma unroll
;         for (int a = 0; a < 2; ++a)
; #pragma unroll
;             for (int b = 0; b < 2; ++b)
; #pragma unroll
;                 for (int m = 0; m < 4; ++m)
; #pragma unroll
;                     for (int n = 0; n < 2; ++n) acc[a][b][m][n] = (f32x4){0.f, 0.f, 0.f, 0.f};
.LBB0_429:
	s_ashr_i32 s19, s18, 31
	s_lshl_b64 s[20:21], s[18:19], 17
	s_add_u32 s20, s42, s20
	s_addc_u32 s21, s43, s21
	s_and_b64 s[22:23], s[6:7], exec
	s_cselect_b32 s19, s21, s27
	s_cselect_b32 s61, s20, s26
	s_ashr_i32 s17, s16, 31
	s_lshl_b64 s[22:23], s[16:17], 20
	s_add_u32 s22, s44, s22
	s_addc_u32 s23, s45, s23
	s_and_b64 s[30:31], s[6:7], exec
	s_cselect_b32 s17, s23, s29
	s_cselect_b32 s62, s22, s28
	s_add_u32 s63, s28, 0x100
	v_mov_b32_e32 v2, 0
	s_addc_u32 s64, s29, 0
	s_mov_b32 s65, -2
	s_mov_b64 s[28:29], 0
	s_mov_b32 s66, 0x400000
	v_mov_b32_e32 v3, v2
	v_mov_b32_e32 v4, v2
	v_mov_b32_e32 v5, v2
	v_mov_b32_e32 v6, v2
	v_mov_b32_e32 v7, v2
	v_mov_b32_e32 v8, v2
	v_mov_b32_e32 v9, v2
	v_mov_b32_e32 v14, v2
	v_mov_b32_e32 v15, v2
	v_mov_b32_e32 v16, v2
	v_mov_b32_e32 v17, v2
	v_mov_b32_e32 v22, v2
	v_mov_b32_e32 v23, v2
	v_mov_b32_e32 v24, v2
	v_mov_b32_e32 v25, v2
	v_mov_b32_e32 v30, v2
	v_mov_b32_e32 v31, v2
	v_mov_b32_e32 v32, v2
	v_mov_b32_e32 v33, v2
	v_mov_b32_e32 v38, v2
	v_mov_b32_e32 v39, v2
	v_mov_b32_e32 v40, v2
	v_mov_b32_e32 v41, v2
	v_mov_b32_e32 v46, v2
	v_mov_b32_e32 v47, v2
	v_mov_b32_e32 v48, v2
	v_mov_b32_e32 v49, v2
	v_mov_b32_e32 v54, v2
	v_mov_b32_e32 v55, v2
	v_mov_b32_e32 v56, v2
	v_mov_b32_e32 v57, v2
	v_mov_b32_e32 v10, v2
	v_mov_b32_e32 v11, v2
	v_mov_b32_e32 v12, v2
	v_mov_b32_e32 v13, v2
	v_mov_b32_e32 v18, v2
	v_mov_b32_e32 v19, v2
	v_mov_b32_e32 v20, v2
	v_mov_b32_e32 v21, v2
	v_mov_b32_e32 v26, v2
	v_mov_b32_e32 v27, v2
	v_mov_b32_e32 v28, v2
	v_mov_b32_e32 v29, v2
	v_mov_b32_e32 v34, v2
	v_mov_b32_e32 v35, v2
	v_mov_b32_e32 v36, v2
	v_mov_b32_e32 v37, v2
	v_mov_b32_e32 v42, v2
	v_mov_b32_e32 v43, v2
	v_mov_b32_e32 v44, v2
	v_mov_b32_e32 v45, v2
	v_mov_b32_e32 v50, v2
	v_mov_b32_e32 v51, v2
	v_mov_b32_e32 v52, v2
	v_mov_b32_e32 v53, v2
	v_mov_b32_e32 v58, v2
	v_mov_b32_e32 v59, v2
	v_mov_b32_e32 v60, v2
	v_mov_b32_e32 v61, v2
	v_mov_b32_e32 v62, v2
	v_mov_b32_e32 v63, v2
	v_mov_b32_e32 v64, v2
	v_mov_b32_e32 v65, v2
	v_mov_b32_e32 v66, v2
	v_mov_b32_e32 v67, v2
	v_mov_b32_e32 v68, v2
	v_mov_b32_e32 v69, v2
	v_mov_b32_e32 v70, v2
	v_mov_b32_e32 v71, v2
	v_mov_b32_e32 v72, v2
	v_mov_b32_e32 v73, v2
	v_mov_b32_e32 v78, v2
	v_mov_b32_e32 v79, v2
	v_mov_b32_e32 v80, v2
	v_mov_b32_e32 v81, v2
	v_mov_b32_e32 v86, v2
	v_mov_b32_e32 v87, v2
	v_mov_b32_e32 v88, v2
	v_mov_b32_e32 v89, v2
	v_mov_b32_e32 v94, v2
	v_mov_b32_e32 v95, v2
	v_mov_b32_e32 v96, v2
	v_mov_b32_e32 v97, v2
	v_mov_b32_e32 v102, v2
	v_mov_b32_e32 v103, v2
	v_mov_b32_e32 v104, v2
	v_mov_b32_e32 v105, v2
	v_mov_b32_e32 v110, v2
	v_mov_b32_e32 v111, v2
	v_mov_b32_e32 v112, v2
	v_mov_b32_e32 v113, v2
	v_mov_b32_e32 v118, v2
	v_mov_b32_e32 v119, v2
	v_mov_b32_e32 v120, v2
	v_mov_b32_e32 v121, v2
	v_mov_b32_e32 v74, v2
	v_mov_b32_e32 v75, v2
	v_mov_b32_e32 v76, v2
	v_mov_b32_e32 v77, v2
	v_mov_b32_e32 v82, v2
	v_mov_b32_e32 v83, v2
	v_mov_b32_e32 v84, v2
	v_mov_b32_e32 v85, v2
	v_mov_b32_e32 v90, v2
	v_mov_b32_e32 v91, v2
	v_mov_b32_e32 v92, v2
	v_mov_b32_e32 v93, v2
	v_mov_b32_e32 v98, v2
	v_mov_b32_e32 v99, v2
	v_mov_b32_e32 v100, v2
	v_mov_b32_e32 v101, v2
	v_mov_b32_e32 v106, v2
	v_mov_b32_e32 v107, v2
	v_mov_b32_e32 v108, v2
	v_mov_b32_e32 v109, v2
	v_mov_b32_e32 v114, v2
	v_mov_b32_e32 v115, v2
	v_mov_b32_e32 v116, v2
	v_mov_b32_e32 v117, v2
	v_mov_b32_e32 v122, v2
	v_mov_b32_e32 v123, v2
	v_mov_b32_e32 v124, v2
	v_mov_b32_e32 v125, v2
	v_mov_b32_e32 v126, v2
	v_mov_b32_e32 v127, v2
	v_mov_b32_e32 v128, v2
	v_mov_b32_e32 v129, v2
	s_add_i32 s30, s66, 0xffc00000
	s_and_b32 s30, s30, 0x3800000
	s_and_b32 s31, s28, 0x100
	s_or_b32 s67, s31, s30
	s_and_b32 s34, s66, 0x7800000
	s_add_u32 s30, s28, 0x100
	s_addc_u32 s31, s29, 0
	s_and_b32 s35, s30, 0x100
	s_or_b32 s34, s34, s35
	s_add_u32 s34, s26, s34
	s_addc_u32 s35, s27, 0
	s_add_u32 s28, s63, s28
	s_addc_u32 s29, s64, s29
	s_add_i32 s70, 0, 0x10000
	s_cmp_eq_u32 s65, 28
	s_cselect_b32 s35, s19, s35
	s_cselect_b32 s34, s61, s34
	v_add_u32_e32 v139, s70, v165
	s_cselect_b32 s29, s17, s29
	s_cselect_b32 s28, s62, s28
	s_add_i32 s71, 0, 0x14000
	ds_read_b128 v[152:155], v139
	ds_read_b128 v[160:163], v139 offset:1024
	ds_read_b128 v[174:177], v139 offset:2048
	ds_read_b128 v[178:181], v139 offset:3072
	v_add_u32_e32 v139, s71, v165
	ds_read_b128 v[182:185], v139
	ds_read_b128 v[186:189], v139 offset:1024
	ds_read_b128 v[190:193], v139 offset:2048
	ds_read_b128 v[194:197], v139 offset:3072
	s_add_u32 s67, s26, s67
	s_addc_u32 s69, s27, 0
	s_add_u32 s68, s67, 0x10080
	s_addc_u32 s69, s69, 0
	s_add_i32 m0, s25, 0xc000
	ds_read_b128 v[198:201], v173
	ds_read_b128 v[202:205], v173 offset:1024
	ds_read_b128 v[206:209], v173 offset:2048
	ds_read_b128 v[210:213], v173 offset:3072
	ds_read_b128 v[214:217], v173 offset:4096
	ds_read_b128 v[218:221], v173 offset:5120
	ds_read_b128 v[222:225], v173 offset:6144
	ds_read_b128 v[226:229], v173 offset:7168
	global_load_lds_dwordx4 v136, s[68:69]
	s_add_i32 m0, s25, 0xe000
	s_nop 0
	global_load_lds_dwordx4 v132, s[68:69]
	s_waitcnt vmcnt(24)
	s_waitcnt lgkmcnt(0)
	s_barrier
; #define PG8_STAGE(bufoff, gbase, voff) do { _Pragma("unroll") for (int _i = 0; _i < 2; ++_i) \
;         __builtin_amdgcn_global_load_lds((const unsigned*)((const char*)(gbase) + (voff)[_i]), (LAS unsigned*)(lds + (bufoff) + ldsw + _i * 8192), 16, 0, 0); } while (0)
; #define PG8_LDA(dst, b, h) do { _Pragma("unroll") for (int m = 0; m < 4; ++m) _Pragma("unroll") for (int k = 0; k < 2; ++k) dst[m][k] = *(const LAS bf16x8*)(lds + PG8_SA(b, h) + aoff + m * 2048 + k * 1024); } while (0)
; #define PG8_MMA(ai, bj, At, Bt) do { __builtin_amdgcn_s_setprio(1); _Pragma("unroll") for (int m = 0; m < 4; ++m) _Pragma("unroll") for (int n = 0; n < 2; ++n) _Pragma("unroll") for (int k = 0; k < 2; ++k) \
;         acc[ai][bj][m][n] = __builtin_amdgcn_mfma_f32_16x16x32_bf16(Bt[n][k], At[m][k], acc[ai][bj][m][n], 0, 0, 0); __builtin_amdgcn_s_setprio(0); } while (0)
; #define PG8_WAIT_V(n) asm volatile("s_waitcnt vmcnt(" #n ")" ::: "memory")
; #define PG8_WAIT_L(n) asm volatile("s_waitcnt lgkmcnt(" #n ")" ::: "memory")
; #define PG8_BAR __builtin_amdgcn_s_barrier()
; #define PG8_SCHED __builtin_amdgcn_sched_barrier(0)
; template <class Epi, class Sched, int KC, bool ALIGN_EPI = false, bool SP2 = false, bool ATILED = false>
; __device__ __forceinline__ void gemm_phase(LAS unsigned char* lds, const Gemm g, const Sched& S, const Epi& E, int wave_s) {
;     ...
;             PG8_WAIT_V(8); PG8_WAIT_L(0); PG8_BAR; PG8_MMA(0, 0, At, B0); PG8_MMA(0, 1, At, B1); PG8_BAR; PG8_SCHED;
;             PG8_LDA(At, 0, 1); PG8_STAGE(PG8_SB(0, 0), b2, voffB); PG8_STAGE(PG8_SB(0, 1), b2 + hstepB, voffB); PG8_STAGE(PG8_SA(0, 0), a2, voffA);
;             PG8_WAIT_V(8); PG8_WAIT_L(0); PG8_BAR; PG8_MMA(1, 0, At, B0); PG8_MMA(1, 1, At, B1); PG8_BAR; PG8_SCHED;
	v_mfma_f32_16x16x32_bf16 v[126:129], v[152:155], v[198:201], v[126:129]
	v_mfma_f32_16x16x32_bf16 v[122:125], v[174:177], v[198:201], v[122:125]
	v_mfma_f32_16x16x32_bf16 v[114:117], v[152:155], v[206:209], v[114:117]
	v_mfma_f32_16x16x32_bf16 v[106:109], v[174:177], v[206:209], v[106:109]
	v_mfma_f32_16x16x32_bf16 v[98:101], v[152:155], v[214:217], v[98:101]
	v_mfma_f32_16x16x32_bf16 v[90:93], v[174:177], v[214:217], v[90:93]
	v_mfma_f32_16x16x32_bf16 v[82:85], v[152:155], v[222:225], v[82:85]
	v_mfma_f32_16x16x32_bf16 v[74:77], v[174:177], v[222:225], v[74:77]
	v_mfma_f32_16x16x32_bf16 v[126:129], v[160:163], v[202:205], v[126:129]
	v_mfma_f32_16x16x32_bf16 v[122:125], v[178:181], v[202:205], v[122:125]
	v_mfma_f32_16x16x32_bf16 v[114:117], v[160:163], v[210:213], v[114:117]
	v_mfma_f32_16x16x32_bf16 v[106:109], v[178:181], v[210:213], v[106:109]
	v_mfma_f32_16x16x32_bf16 v[98:101], v[160:163], v[218:221], v[98:101]
	v_mfma_f32_16x16x32_bf16 v[90:93], v[178:181], v[218:221], v[90:93]
	v_mfma_f32_16x16x32_bf16 v[82:85], v[160:163], v[226:229], v[82:85]
	v_mfma_f32_16x16x32_bf16 v[74:77], v[178:181], v[226:229], v[74:77]
	v_mfma_f32_16x16x32_bf16 v[118:121], v[182:185], v[198:201], v[118:121]
	v_mfma_f32_16x16x32_bf16 v[110:113], v[190:193], v[198:201], v[110:113]
	v_mfma_f32_16x16x32_bf16 v[102:105], v[182:185], v[206:209], v[102:105]
	v_mfma_f32_16x16x32_bf16 v[94:97], v[190:193], v[206:209], v[94:97]
	v_mfma_f32_16x16x32_bf16 v[86:89], v[182:185], v[214:217], v[86:89]
	v_mfma_f32_16x16x32_bf16 v[78:81], v[190:193], v[214:217], v[78:81]
	v_mfma_f32_16x16x32_bf16 v[70:73], v[182:185], v[222:225], v[70:73]
	v_mfma_f32_16x16x32_bf16 v[66:69], v[190:193], v[222:225], v[66:69]
	v_mfma_f32_16x16x32_bf16 v[118:121], v[186:189], v[202:205], v[118:121]
	v_mfma_f32_16x16x32_bf16 v[110:113], v[194:197], v[202:205], v[110:113]
	v_mfma_f32_16x16x32_bf16 v[102:105], v[186:189], v[210:213], v[102:105]
	v_mfma_f32_16x16x32_bf16 v[94:97], v[194:197], v[210:213], v[94:97]
	v_mfma_f32_16x16x32_bf16 v[86:89], v[186:189], v[218:221], v[86:89]
	v_mfma_f32_16x16x32_bf16 v[78:81], v[194:197], v[218:221], v[78:81]
	v_mfma_f32_16x16x32_bf16 v[70:73], v[186:189], v[226:229], v[70:73]
	v_mfma_f32_16x16x32_bf16 v[66:69], v[194:197], v[226:229], v[66:69]
	s_barrier
	s_add_u32 s100, s34, 0x80
	s_addc_u32 s101, s35, 0
	s_add_i32 s67, s70, s41
	s_mov_b32 m0, s67
	ds_read_b128 v[198:201], v173 offset:16384
	ds_read_b128 v[202:205], v173 offset:17408
	ds_read_b128 v[206:209], v173 offset:18432
	ds_read_b128 v[210:213], v173 offset:19456
	ds_read_b128 v[214:217], v173 offset:20480
	ds_read_b128 v[218:221], v173 offset:21504
	ds_read_b128 v[222:225], v173 offset:22528
	ds_read_b128 v[226:229], v173 offset:23552
	global_load_lds_dwordx4 v134, s[28:29]
	s_add_i32 m0, s67, 0x2000
	s_add_u32 s68, s28, 0x80000
	s_addc_u32 s69, s29, 0
	s_add_i32 s67, s71, s41
	global_load_lds_dwordx4 v130, s[28:29]
	s_mov_b32 m0, s67
	s_nop 0
	global_load_lds_dwordx4 v134, s[68:69]
	s_add_i32 m0, s67, 0x2000
	s_nop 0
	global_load_lds_dwordx4 v130, s[68:69]
	s_mov_b32 m0, s25
	s_nop 0
	global_load_lds_dwordx4 v136, s[34:35]
	s_mov_b32 m0, s52
	s_nop 0
	global_load_lds_dwordx4 v132, s[34:35]
	s_waitcnt vmcnt(24)
	s_waitcnt lgkmcnt(0)
	s_barrier
	v_mfma_f32_16x16x32_bf16 v[62:65], v[152:155], v[198:201], v[62:65]
	v_mfma_f32_16x16x32_bf16 v[58:61], v[174:177], v[198:201], v[58:61]
	v_mfma_f32_16x16x32_bf16 v[50:53], v[152:155], v[206:209], v[50:53]
	v_mfma_f32_16x16x32_bf16 v[42:45], v[174:177], v[206:209], v[42:45]
	v_mfma_f32_16x16x32_bf16 v[34:37], v[152:155], v[214:217], v[34:37]
	v_mfma_f32_16x16x32_bf16 v[26:29], v[174:177], v[214:217], v[26:29]
	v_mfma_f32_16x16x32_bf16 v[18:21], v[152:155], v[222:225], v[18:21]
	v_mfma_f32_16x16x32_bf16 v[10:13], v[174:177], v[222:225], v[10:13]
	v_mfma_f32_16x16x32_bf16 v[62:65], v[160:163], v[202:205], v[62:65]
	v_mfma_f32_16x16x32_bf16 v[58:61], v[178:181], v[202:205], v[58:61]
	v_mfma_f32_16x16x32_bf16 v[50:53], v[160:163], v[210:213], v[50:53]
	v_mfma_f32_16x16x32_bf16 v[42:45], v[178:181], v[210:213], v[42:45]
	v_mfma_f32_16x16x32_bf16 v[34:37], v[160:163], v[218:221], v[34:37]
	v_mfma_f32_16x16x32_bf16 v[26:29], v[178:181], v[218:221], v[26:29]
	v_mfma_f32_16x16x32_bf16 v[18:21], v[160:163], v[226:229], v[18:21]
	v_mfma_f32_16x16x32_bf16 v[10:13], v[178:181], v[226:229], v[10:13]
	v_mfma_f32_16x16x32_bf16 v[54:57], v[182:185], v[198:201], v[54:57]
	v_mfma_f32_16x16x32_bf16 v[46:49], v[190:193], v[198:201], v[46:49]
	v_mfma_f32_16x16x32_bf16 v[38:41], v[182:185], v[206:209], v[38:41]
	v_mfma_f32_16x16x32_bf16 v[30:33], v[190:193], v[206:209], v[30:33]
	v_mfma_f32_16x16x32_bf16 v[22:25], v[182:185], v[214:217], v[22:25]
	v_mfma_f32_16x16x32_bf16 v[14:17], v[190:193], v[214:217], v[14:17]
	v_mfma_f32_16x16x32_bf16 v[6:9], v[182:185], v[222:225], v[6:9]
	v_mfma_f32_16x16x32_bf16 v[2:5], v[190:193], v[222:225], v[2:5]
	v_mfma_f32_16x16x32_bf16 v[54:57], v[186:189], v[202:205], v[54:57]
	v_mfma_f32_16x16x32_bf16 v[46:49], v[194:197], v[202:205], v[46:49]
	v_mfma_f32_16x16x32_bf16 v[38:41], v[186:189], v[210:213], v[38:41]
	v_mfma_f32_16x16x32_bf16 v[30:33], v[194:197], v[210:213], v[30:33]
	v_mfma_f32_16x16x32_bf16 v[22:25], v[186:189], v[218:221], v[22:25]
	v_mfma_f32_16x16x32_bf16 v[14:17], v[194:197], v[218:221], v[14:17]
	v_mfma_f32_16x16x32_bf16 v[6:9], v[186:189], v[226:229], v[6:9]
	v_mfma_f32_16x16x32_bf16 v[2:5], v[194:197], v[226:229], v[2:5]
	s_barrier
; #define PG8_STAGE(bufoff, gbase, voff) do { _Pragma("unroll") for (int _i = 0; _i < 2; ++_i) \
;         __builtin_amdgcn_global_load_lds((const unsigned*)((const char*)(gbase) + (voff)[_i]), (LAS unsigned*)(lds + (bufoff) + ldsw + _i * 8192), 16, 0, 0); } while (0)
; #define PG8_LDA(dst, b, h) do { _Pragma("unroll") for (int m = 0; m < 4; ++m) _Pragma("unroll") for (int k = 0; k < 2; ++k) dst[m][k] = *(const LAS bf16x8*)(lds + PG8_SA(b, h) + aoff + m * 2048 + k * 1024); } while (0)
; #define PG8_LDB(dst, b, h) do { _Pragma("unroll") for (int n = 0; n < 2; ++n) _Pragma("unroll") for (int k = 0; k < 2; ++k) dst[n][k] = *(const LAS bf16x8*)(lds + PG8_SB(b, h) + boff + n * 2048 + k * 1024); } while (0)
; #define PG8_MMA(ai, bj, At, Bt) do { __builtin_amdgcn_s_setprio(1); _Pragma("unroll") for (int m = 0; m < 4; ++m) _Pragma("unroll") for (int n = 0; n < 2; ++n) _Pragma("unroll") for (int k = 0; k < 2; ++k) \
;         acc[ai][bj][m][n] = __builtin_amdgcn_mfma_f32_16x16x32_bf16(Bt[n][k], At[m][k], acc[ai][bj][m][n], 0, 0, 0); __builtin_amdgcn_s_setprio(0); } while (0)
; #define PG8_WAIT_V(n) asm volatile("s_waitcnt vmcnt(" #n ")" ::: "memory")
; #define PG8_WAIT_L(n) asm volatile("s_waitcnt lgkmcnt(" #n ")" ::: "memory")
; #define PG8_BAR __builtin_amdgcn_s_barrier()
; #define PG8_SCHED __builtin_amdgcn_sched_barrier(0)
; template <class Epi, class Sched, int KC, bool ALIGN_EPI = false, bool SP2 = false, bool ATILED = false>
; __device__ __forceinline__ void gemm_phase(LAS unsigned char* lds, const Gemm g, const Sched& S, const Epi& E, int wave_s) {
;     ...
;             PG8_LDB(B0, 1, 0); PG8_LDB(B1, 1, 1); PG8_SCHED; PG8_LDA(At, 1, 0); PG8_STAGE(PG8_SA(0, 1), a2 + hstepA, voffA);
;             PG8_WAIT_V(8); PG8_WAIT_L(0); PG8_BAR; PG8_MMA(0, 0, At, B0); PG8_MMA(0, 1, At, B1); PG8_BAR; PG8_SCHED;
;             PG8_LDA(At, 1, 1); PG8_STAGE(PG8_SB(1, 0), b3, voffB); PG8_STAGE(PG8_SB(1, 1), b3 + hstepB, voffB); PG8_STAGE(PG8_SA(1, 0), a3, voffA);
;             PG8_WAIT_V(8); PG8_WAIT_L(0); PG8_BAR; PG8_MMA(1, 0, At, B0); PG8_MMA(1, 1, At, B1); PG8_BAR; PG8_SCHED;
	s_add_i32 s67, 0, 0x18000
	v_add_u32_e32 v139, s67, v165
	s_add_i32 s68, 0, 0x1c000
	ds_read_b128 v[152:155], v139
	ds_read_b128 v[160:163], v139 offset:1024
	ds_read_b128 v[174:177], v139 offset:2048
	ds_read_b128 v[178:181], v139 offset:3072
	v_add_u32_e32 v139, s68, v165
	ds_read_b128 v[182:185], v139
	ds_read_b128 v[186:189], v139 offset:1024
	ds_read_b128 v[190:193], v139 offset:2048
	ds_read_b128 v[194:197], v139 offset:3072
	s_add_u32 s34, s34, 0x10000
	s_addc_u32 s35, s35, 0
	s_mov_b32 m0, s53
	ds_read_b128 v[198:201], v173 offset:32768
	ds_read_b128 v[202:205], v173 offset:33792
	ds_read_b128 v[206:209], v173 offset:34816
	ds_read_b128 v[210:213], v173 offset:35840
	ds_read_b128 v[214:217], v173 offset:36864
	ds_read_b128 v[218:221], v173 offset:37888
	ds_read_b128 v[222:225], v173 offset:38912
	ds_read_b128 v[226:229], v173 offset:39936
	global_load_lds_dwordx4 v136, s[34:35]
	s_mov_b32 m0, s54
	s_nop 0
	global_load_lds_dwordx4 v132, s[34:35]
	s_waitcnt vmcnt(8)
	s_waitcnt lgkmcnt(0)
	s_barrier
	v_mfma_f32_16x16x32_bf16 v[126:129], v[152:155], v[198:201], v[126:129]
	v_mfma_f32_16x16x32_bf16 v[122:125], v[174:177], v[198:201], v[122:125]
	v_mfma_f32_16x16x32_bf16 v[114:117], v[152:155], v[206:209], v[114:117]
	v_mfma_f32_16x16x32_bf16 v[106:109], v[174:177], v[206:209], v[106:109]
	v_mfma_f32_16x16x32_bf16 v[98:101], v[152:155], v[214:217], v[98:101]
	v_mfma_f32_16x16x32_bf16 v[90:93], v[174:177], v[214:217], v[90:93]
	v_mfma_f32_16x16x32_bf16 v[82:85], v[152:155], v[222:225], v[82:85]
	v_mfma_f32_16x16x32_bf16 v[74:77], v[174:177], v[222:225], v[74:77]
	v_mfma_f32_16x16x32_bf16 v[126:129], v[160:163], v[202:205], v[126:129]
	v_mfma_f32_16x16x32_bf16 v[122:125], v[178:181], v[202:205], v[122:125]
	v_mfma_f32_16x16x32_bf16 v[114:117], v[160:163], v[210:213], v[114:117]
	v_mfma_f32_16x16x32_bf16 v[106:109], v[178:181], v[210:213], v[106:109]
	v_mfma_f32_16x16x32_bf16 v[98:101], v[160:163], v[218:221], v[98:101]
	v_mfma_f32_16x16x32_bf16 v[90:93], v[178:181], v[218:221], v[90:93]
	v_mfma_f32_16x16x32_bf16 v[82:85], v[160:163], v[226:229], v[82:85]
	v_mfma_f32_16x16x32_bf16 v[74:77], v[178:181], v[226:229], v[74:77]
	v_mfma_f32_16x16x32_bf16 v[118:121], v[182:185], v[198:201], v[118:121]
	v_mfma_f32_16x16x32_bf16 v[110:113], v[190:193], v[198:201], v[110:113]
	v_mfma_f32_16x16x32_bf16 v[102:105], v[182:185], v[206:209], v[102:105]
	v_mfma_f32_16x16x32_bf16 v[94:97], v[190:193], v[206:209], v[94:97]
	v_mfma_f32_16x16x32_bf16 v[86:89], v[182:185], v[214:217], v[86:89]
	v_mfma_f32_16x16x32_bf16 v[78:81], v[190:193], v[214:217], v[78:81]
	v_mfma_f32_16x16x32_bf16 v[70:73], v[182:185], v[222:225], v[70:73]
	v_mfma_f32_16x16x32_bf16 v[66:69], v[190:193], v[222:225], v[66:69]
	v_mfma_f32_16x16x32_bf16 v[118:121], v[186:189], v[202:205], v[118:121]
	v_mfma_f32_16x16x32_bf16 v[110:113], v[194:197], v[202:205], v[110:113]
	v_mfma_f32_16x16x32_bf16 v[102:105], v[186:189], v[210:213], v[102:105]
	v_mfma_f32_16x16x32_bf16 v[94:97], v[194:197], v[210:213], v[94:97]
	v_mfma_f32_16x16x32_bf16 v[86:89], v[186:189], v[218:221], v[86:89]
	v_mfma_f32_16x16x32_bf16 v[78:81], v[194:197], v[218:221], v[78:81]
	v_mfma_f32_16x16x32_bf16 v[70:73], v[186:189], v[226:229], v[70:73]
	v_mfma_f32_16x16x32_bf16 v[66:69], v[194:197], v[226:229], v[66:69]
	s_barrier
	s_add_u32 s98, s28, 0x80
	s_addc_u32 s99, s29, 0
	s_add_i32 s34, s67, s41
	s_mov_b32 m0, s34
	ds_read_b128 v[198:201], v173 offset:49152
	ds_read_b128 v[202:205], v173 offset:50176
	ds_read_b128 v[206:209], v173 offset:51200
	ds_read_b128 v[210:213], v173 offset:52224
	ds_read_b128 v[214:217], v173 offset:53248
	ds_read_b128 v[218:221], v173 offset:54272
	ds_read_b128 v[222:225], v173 offset:55296
	ds_read_b128 v[226:229], v173 offset:56320
	global_load_lds_dwordx4 v134, s[98:99]
	s_add_i32 m0, s34, 0x2000
	s_add_u32 s28, s28, 0x80080
	s_addc_u32 s29, s29, 0
	s_add_i32 s34, s68, s41
	global_load_lds_dwordx4 v130, s[98:99]
	s_mov_b32 m0, s34
	s_nop 0
	global_load_lds_dwordx4 v134, s[28:29]
	s_add_i32 m0, s34, 0x2000
	s_nop 0
	global_load_lds_dwordx4 v130, s[28:29]
	s_mov_b32 m0, s55
	s_nop 0
	global_load_lds_dwordx4 v136, s[100:101]
	s_mov_b32 m0, s56
	s_nop 0
	global_load_lds_dwordx4 v132, s[100:101]
	s_waitcnt vmcnt(8)
	s_waitcnt lgkmcnt(0)
	s_barrier
	v_mfma_f32_16x16x32_bf16 v[62:65], v[152:155], v[198:201], v[62:65]
	v_mfma_f32_16x16x32_bf16 v[58:61], v[174:177], v[198:201], v[58:61]
	v_mfma_f32_16x16x32_bf16 v[50:53], v[152:155], v[206:209], v[50:53]
	v_mfma_f32_16x16x32_bf16 v[42:45], v[174:177], v[206:209], v[42:45]
	v_mfma_f32_16x16x32_bf16 v[34:37], v[152:155], v[214:217], v[34:37]
	v_mfma_f32_16x16x32_bf16 v[26:29], v[174:177], v[214:217], v[26:29]
	v_mfma_f32_16x16x32_bf16 v[18:21], v[152:155], v[222:225], v[18:21]
	v_mfma_f32_16x16x32_bf16 v[10:13], v[174:177], v[222:225], v[10:13]
	v_mfma_f32_16x16x32_bf16 v[62:65], v[160:163], v[202:205], v[62:65]
	v_mfma_f32_16x16x32_bf16 v[58:61], v[178:181], v[202:205], v[58:61]
	v_mfma_f32_16x16x32_bf16 v[50:53], v[160:163], v[210:213], v[50:53]
	v_mfma_f32_16x16x32_bf16 v[42:45], v[178:181], v[210:213], v[42:45]
	v_mfma_f32_16x16x32_bf16 v[34:37], v[160:163], v[218:221], v[34:37]
	v_mfma_f32_16x16x32_bf16 v[26:29], v[178:181], v[218:221], v[26:29]
	v_mfma_f32_16x16x32_bf16 v[18:21], v[160:163], v[226:229], v[18:21]
	v_mfma_f32_16x16x32_bf16 v[10:13], v[178:181], v[226:229], v[10:13]
	v_mfma_f32_16x16x32_bf16 v[54:57], v[182:185], v[198:201], v[54:57]
	v_mfma_f32_16x16x32_bf16 v[46:49], v[190:193], v[198:201], v[46:49]
	v_mfma_f32_16x16x32_bf16 v[38:41], v[182:185], v[206:209], v[38:41]
	v_mfma_f32_16x16x32_bf16 v[30:33], v[190:193], v[206:209], v[30:33]
	v_mfma_f32_16x16x32_bf16 v[22:25], v[182:185], v[214:217], v[22:25]
	v_mfma_f32_16x16x32_bf16 v[14:17], v[190:193], v[214:217], v[14:17]
	v_mfma_f32_16x16x32_bf16 v[6:9], v[182:185], v[222:225], v[6:9]
	v_mfma_f32_16x16x32_bf16 v[2:5], v[190:193], v[222:225], v[2:5]
	v_mfma_f32_16x16x32_bf16 v[54:57], v[186:189], v[202:205], v[54:57]
	v_mfma_f32_16x16x32_bf16 v[46:49], v[194:197], v[202:205], v[46:49]
	v_mfma_f32_16x16x32_bf16 v[38:41], v[186:189], v[210:213], v[38:41]
	v_mfma_f32_16x16x32_bf16 v[30:33], v[194:197], v[210:213], v[30:33]
	v_mfma_f32_16x16x32_bf16 v[22:25], v[186:189], v[218:221], v[22:25]
	v_mfma_f32_16x16x32_bf16 v[14:17], v[194:197], v[218:221], v[14:17]
	v_mfma_f32_16x16x32_bf16 v[6:9], v[186:189], v[226:229], v[6:9]
	v_mfma_f32_16x16x32_bf16 v[2:5], v[194:197], v[226:229], v[2:5]
	s_barrier
	s_add_i32 s65, s65, 2
	s_add_i32 s66, s66, 0x400000
	s_cmp_gt_u32 s65, 29
	s_mov_b64 s[28:29], s[30:31]
; #define PG8_STAGE(bufoff, gbase, voff) do { _Pragma("unroll") for (int _i = 0; _i < 2; ++_i) \
;         __builtin_amdgcn_global_load_lds((const unsigned*)((const char*)(gbase) + (voff)[_i]), (LAS unsigned*)(lds + (bufoff) + ldsw + _i * 8192), 16, 0, 0); } while (0)
; #define PG8_LDA(dst, b, h) do { _Pragma("unroll") for (int m = 0; m < 4; ++m) _Pragma("unroll") for (int k = 0; k < 2; ++k) dst[m][k] = *(const LAS bf16x8*)(lds + PG8_SA(b, h) + aoff + m * 2048 + k * 1024); } while (0)
; #define PG8_LDB(dst, b, h) do { _Pragma("unroll") for (int n = 0; n < 2; ++n) _Pragma("unroll") for (int k = 0; k < 2; ++k) dst[n][k] = *(const LAS bf16x8*)(lds + PG8_SB(b, h) + boff + n * 2048 + k * 1024); } while (0)
; #define PG8_MMA(ai, bj, At, Bt) do { __builtin_amdgcn_s_setprio(1); _Pragma("unroll") for (int m = 0; m < 4; ++m) _Pragma("unroll") for (int n = 0; n < 2; ++n) _Pragma("unroll") for (int k = 0; k < 2; ++k) \
;         acc[ai][bj][m][n] = __builtin_amdgcn_mfma_f32_16x16x32_bf16(Bt[n][k], At[m][k], acc[ai][bj][m][n], 0, 0, 0); __builtin_amdgcn_s_setprio(0); } while (0)
; #define PG8_WAIT_V(n) asm volatile("s_waitcnt vmcnt(" #n ")" ::: "memory")
; #define PG8_WAIT_L(n) asm volatile("s_waitcnt lgkmcnt(" #n ")" ::: "memory")
; #define PG8_BAR __builtin_amdgcn_s_barrier()
; #define PG8_SCHED __builtin_amdgcn_sched_barrier(0)
; template <class Epi, class Sched, int KC, bool ALIGN_EPI = false, bool SP2 = false, bool ATILED = false>
; __device__ __forceinline__ void gemm_phase(LAS unsigned char* lds, const Gemm g, const Sched& S, const Epi& E, int wave_s) {
;     ...
;             const bool last = (t == nt - 2);
;             const char* a1 = cA + PG8_AOFF(t + 1);
;             const char* a2 = last ? nA : cA + PG8_AOFF(t + 2); const char* b2 = last ? nB : cB + (size_t)(t + 2) * kstep;
;             const char* a3 = a2 + kstep; const char* b3 = b2 + kstep;
;             if (last && has_next) S.a_ready(nxt);
;             if constexpr (SP2) {
;             PG8_LDB(B0, 0, 0); PG8_LDB(B1, 0, 1); PG8_SCHED; PG8_LDA(At, 0, 0); PG8_STAGE(PG8_SA(1, 1), a1 + hstepA, voffA);
;             PG8_WAIT_V(8); PG8_WAIT_L(0); PG8_BAR; PG8_MMA(0, 0, At, B0); PG8_MMA(0, 1, At, B1); PG8_BAR; PG8_SCHED;
.LBB0_430:
	s_add_i32 s30, s66, 0xffc00000
	s_and_b32 s30, s30, 0x3800000
	s_and_b32 s31, s28, 0x100
	s_or_b32 s67, s31, s30
	s_and_b32 s34, s66, 0x7800000
	s_add_u32 s30, s28, 0x100
	s_addc_u32 s31, s29, 0
	s_and_b32 s35, s30, 0x100
	s_or_b32 s34, s34, s35
	s_add_u32 s34, s26, s34
	s_addc_u32 s35, s27, 0
	s_add_u32 s28, s63, s28
	s_addc_u32 s29, s64, s29
	s_add_i32 s70, 0, 0x10000
	s_cmp_eq_u32 s65, 28
	s_cselect_b32 s35, s19, s35
	s_cselect_b32 s34, s61, s34
	v_add_u32_e32 v139, s70, v165
	s_cselect_b32 s29, s17, s29
	s_cselect_b32 s28, s62, s28
	s_add_i32 s71, 0, 0x14000
	ds_read_b128 v[152:155], v139
	ds_read_b128 v[160:163], v139 offset:1024
	ds_read_b128 v[174:177], v139 offset:2048
	ds_read_b128 v[178:181], v139 offset:3072
	v_add_u32_e32 v139, s71, v165
	ds_read_b128 v[182:185], v139
	ds_read_b128 v[186:189], v139 offset:1024
	ds_read_b128 v[190:193], v139 offset:2048
	ds_read_b128 v[194:197], v139 offset:3072
	s_add_u32 s67, s26, s67
	s_addc_u32 s69, s27, 0
	s_add_u32 s68, s67, 0x10080
	s_addc_u32 s69, s69, 0
	s_add_i32 m0, s25, 0xc000
	ds_read_b128 v[198:201], v173
	ds_read_b128 v[202:205], v173 offset:1024
	ds_read_b128 v[206:209], v173 offset:2048
	ds_read_b128 v[210:213], v173 offset:3072
	ds_read_b128 v[214:217], v173 offset:4096
	ds_read_b128 v[218:221], v173 offset:5120
	ds_read_b128 v[222:225], v173 offset:6144
	ds_read_b128 v[226:229], v173 offset:7168
	global_load_lds_dwordx4 v136, s[68:69]
	s_add_i32 m0, s25, 0xe000
	s_nop 0
	global_load_lds_dwordx4 v132, s[68:69]
	s_waitcnt vmcnt(8)
	s_waitcnt lgkmcnt(0)
	s_barrier
	v_mfma_f32_16x16x32_bf16 v[126:129], v[152:155], v[198:201], v[126:129]
	v_mfma_f32_16x16x32_bf16 v[122:125], v[174:177], v[198:201], v[122:125]
	v_mfma_f32_16x16x32_bf16 v[114:117], v[152:155], v[206:209], v[114:117]
	v_mfma_f32_16x16x32_bf16 v[106:109], v[174:177], v[206:209], v[106:109]
	v_mfma_f32_16x16x32_bf16 v[98:101], v[152:155], v[214:217], v[98:101]
	v_mfma_f32_16x16x32_bf16 v[90:93], v[174:177], v[214:217], v[90:93]
	v_mfma_f32_16x16x32_bf16 v[82:85], v[152:155], v[222:225], v[82:85]
	v_mfma_f32_16x16x32_bf16 v[74:77], v[174:177], v[222:225], v[74:77]
	v_mfma_f32_16x16x32_bf16 v[126:129], v[160:163], v[202:205], v[126:129]
	v_mfma_f32_16x16x32_bf16 v[122:125], v[178:181], v[202:205], v[122:125]
	v_mfma_f32_16x16x32_bf16 v[114:117], v[160:163], v[210:213], v[114:117]
	v_mfma_f32_16x16x32_bf16 v[106:109], v[178:181], v[210:213], v[106:109]
	v_mfma_f32_16x16x32_bf16 v[98:101], v[160:163], v[218:221], v[98:101]
	v_mfma_f32_16x16x32_bf16 v[90:93], v[178:181], v[218:221], v[90:93]
	v_mfma_f32_16x16x32_bf16 v[82:85], v[160:163], v[226:229], v[82:85]
	v_mfma_f32_16x16x32_bf16 v[74:77], v[178:181], v[226:229], v[74:77]
	v_mfma_f32_16x16x32_bf16 v[118:121], v[182:185], v[198:201], v[118:121]
	v_mfma_f32_16x16x32_bf16 v[110:113], v[190:193], v[198:201], v[110:113]
	v_mfma_f32_16x16x32_bf16 v[102:105], v[182:185], v[206:209], v[102:105]
	v_mfma_f32_16x16x32_bf16 v[94:97], v[190:193], v[206:209], v[94:97]
	v_mfma_f32_16x16x32_bf16 v[86:89], v[182:185], v[214:217], v[86:89]
	v_mfma_f32_16x16x32_bf16 v[78:81], v[190:193], v[214:217], v[78:81]
	v_mfma_f32_16x16x32_bf16 v[70:73], v[182:185], v[222:225], v[70:73]
	v_mfma_f32_16x16x32_bf16 v[66:69], v[190:193], v[222:225], v[66:69]
	v_mfma_f32_16x16x32_bf16 v[118:121], v[186:189], v[202:205], v[118:121]
	v_mfma_f32_16x16x32_bf16 v[110:113], v[194:197], v[202:205], v[110:113]
	v_mfma_f32_16x16x32_bf16 v[102:105], v[186:189], v[210:213], v[102:105]
	v_mfma_f32_16x16x32_bf16 v[94:97], v[194:197], v[210:213], v[94:97]
	v_mfma_f32_16x16x32_bf16 v[86:89], v[186:189], v[218:221], v[86:89]
	v_mfma_f32_16x16x32_bf16 v[78:81], v[194:197], v[218:221], v[78:81]
	v_mfma_f32_16x16x32_bf16 v[70:73], v[186:189], v[226:229], v[70:73]
	v_mfma_f32_16x16x32_bf16 v[66:69], v[194:197], v[226:229], v[66:69]
	s_barrier
	s_add_u32 s100, s34, 0x80
	s_addc_u32 s101, s35, 0
	s_add_i32 s67, s70, s41
	s_mov_b32 m0, s67
	ds_read_b128 v[198:201], v173 offset:16384
	ds_read_b128 v[202:205], v173 offset:17408
	ds_read_b128 v[206:209], v173 offset:18432
	ds_read_b128 v[210:213], v173 offset:19456
	ds_read_b128 v[214:217], v173 offset:20480
	ds_read_b128 v[218:221], v173 offset:21504
	ds_read_b128 v[222:225], v173 offset:22528
	ds_read_b128 v[226:229], v173 offset:23552
	global_load_lds_dwordx4 v134, s[28:29]
	s_add_i32 m0, s67, 0x2000
	s_add_u32 s68, s28, 0x80000
	s_addc_u32 s69, s29, 0
	s_add_i32 s67, s71, s41
	global_load_lds_dwordx4 v130, s[28:29]
	s_mov_b32 m0, s67
	s_nop 0
	global_load_lds_dwordx4 v134, s[68:69]
	s_add_i32 m0, s67, 0x2000
	s_nop 0
	global_load_lds_dwordx4 v130, s[68:69]
	s_mov_b32 m0, s25
	s_nop 0
	global_load_lds_dwordx4 v136, s[34:35]
	s_mov_b32 m0, s52
	s_nop 0
	global_load_lds_dwordx4 v132, s[34:35]
	s_waitcnt vmcnt(8)
	s_waitcnt lgkmcnt(0)
	s_barrier
; #define PG8_STAGE(bufoff, gbase, voff) do { _Pragma("unroll") for (int _i = 0; _i < 2; ++_i) \
;         __builtin_amdgcn_global_load_lds((const unsigned*)((const char*)(gbase) + (voff)[_i]), (LAS unsigned*)(lds + (bufoff) + ldsw + _i * 8192), 16, 0, 0); } while (0)
; #define PG8_LDA(dst, b, h) do { _Pragma("unroll") for (int m = 0; m < 4; ++m) _Pragma("unroll") for (int k = 0; k < 2; ++k) dst[m][k] = *(const LAS bf16x8*)(lds + PG8_SA(b, h) + aoff + m * 2048 + k * 1024); } while (0)
; #define PG8_LDB(dst, b, h) do { _Pragma("unroll") for (int n = 0; n < 2; ++n) _Pragma("unroll") for (int k = 0; k < 2; ++k) dst[n][k] = *(const LAS bf16x8*)(lds + PG8_SB(b, h) + boff + n * 2048 + k * 1024); } while (0)
; #define PG8_MMA(ai, bj, At, Bt) do { __builtin_amdgcn_s_setprio(1); _Pragma("unroll") for (int m = 0; m < 4; ++m) _Pragma("unroll") for (int n = 0; n < 2; ++n) _Pragma("unroll") for (int k = 0; k < 2; ++k) \
;         acc[ai][bj][m][n] = __builtin_amdgcn_mfma_f32_16x16x32_bf16(Bt[n][k], At[m][k], acc[ai][bj][m][n], 0, 0, 0); __builtin_amdgcn_s_setprio(0); } while (0)
; #define PG8_WAIT_V(n) asm volatile("s_waitcnt vmcnt(" #n ")" ::: "memory")
; #define PG8_WAIT_L(n) asm volatile("s_waitcnt lgkmcnt(" #n ")" ::: "memory")
; #define PG8_BAR __builtin_amdgcn_s_barrier()
; #define PG8_SCHED __builtin_amdgcn_sched_barrier(0)
; template <class Epi, class Sched, int KC, bool ALIGN_EPI = false, bool SP2 = false, bool ATILED = false>
; __device__ __forceinline__ void gemm_phase(LAS unsigned char* lds, const Gemm g, const Sched& S, const Epi& E, int wave_s) {
;     ...
;             PG8_WAIT_V(8); PG8_WAIT_L(0); PG8_BAR; PG8_MMA(0, 0, At, B0); PG8_MMA(0, 1, At, B1); PG8_BAR; PG8_SCHED;
;             PG8_LDA(At, 0, 1); PG8_STAGE(PG8_SB(0, 0), b2, voffB); PG8_STAGE(PG8_SB(0, 1), b2 + hstepB, voffB); PG8_STAGE(PG8_SA(0, 0), a2, voffA);
;             PG8_WAIT_V(8); PG8_WAIT_L(0); PG8_BAR; PG8_MMA(1, 0, At, B0); PG8_MMA(1, 1, At, B1); PG8_BAR; PG8_SCHED;
;             PG8_LDB(B0, 1, 0); PG8_LDB(B1, 1, 1); PG8_SCHED; PG8_LDA(At, 1, 0); PG8_STAGE(PG8_SA(0, 1), a2 + hstepA, voffA);
;             PG8_WAIT_V(8); PG8_WAIT_L(0); PG8_BAR; PG8_MMA(0, 0, At, B0); PG8_MMA(0, 1, At, B1); PG8_BAR; PG8_SCHED;
	v_mfma_f32_16x16x32_bf16 v[62:65], v[152:155], v[198:201], v[62:65]
	v_mfma_f32_16x16x32_bf16 v[58:61], v[174:177], v[198:201], v[58:61]
	v_mfma_f32_16x16x32_bf16 v[50:53], v[152:155], v[206:209], v[50:53]
	v_mfma_f32_16x16x32_bf16 v[42:45], v[174:177], v[206:209], v[42:45]
	v_mfma_f32_16x16x32_bf16 v[34:37], v[152:155], v[214:217], v[34:37]
	v_mfma_f32_16x16x32_bf16 v[26:29], v[174:177], v[214:217], v[26:29]
	v_mfma_f32_16x16x32_bf16 v[18:21], v[152:155], v[222:225], v[18:21]
	v_mfma_f32_16x16x32_bf16 v[10:13], v[174:177], v[222:225], v[10:13]
	v_mfma_f32_16x16x32_bf16 v[62:65], v[160:163], v[202:205], v[62:65]
	v_mfma_f32_16x16x32_bf16 v[58:61], v[178:181], v[202:205], v[58:61]
	v_mfma_f32_16x16x32_bf16 v[50:53], v[160:163], v[210:213], v[50:53]
	v_mfma_f32_16x16x32_bf16 v[42:45], v[178:181], v[210:213], v[42:45]
	v_mfma_f32_16x16x32_bf16 v[34:37], v[160:163], v[218:221], v[34:37]
	v_mfma_f32_16x16x32_bf16 v[26:29], v[178:181], v[218:221], v[26:29]
	v_mfma_f32_16x16x32_bf16 v[18:21], v[160:163], v[226:229], v[18:21]
	v_mfma_f32_16x16x32_bf16 v[10:13], v[178:181], v[226:229], v[10:13]
	v_mfma_f32_16x16x32_bf16 v[54:57], v[182:185], v[198:201], v[54:57]
	v_mfma_f32_16x16x32_bf16 v[46:49], v[190:193], v[198:201], v[46:49]
	v_mfma_f32_16x16x32_bf16 v[38:41], v[182:185], v[206:209], v[38:41]
	v_mfma_f32_16x16x32_bf16 v[30:33], v[190:193], v[206:209], v[30:33]
	v_mfma_f32_16x16x32_bf16 v[22:25], v[182:185], v[214:217], v[22:25]
	v_mfma_f32_16x16x32_bf16 v[14:17], v[190:193], v[214:217], v[14:17]
	v_mfma_f32_16x16x32_bf16 v[6:9], v[182:185], v[222:225], v[6:9]
	v_mfma_f32_16x16x32_bf16 v[2:5], v[190:193], v[222:225], v[2:5]
	v_mfma_f32_16x16x32_bf16 v[54:57], v[186:189], v[202:205], v[54:57]
	v_mfma_f32_16x16x32_bf16 v[46:49], v[194:197], v[202:205], v[46:49]
	v_mfma_f32_16x16x32_bf16 v[38:41], v[186:189], v[210:213], v[38:41]
	v_mfma_f32_16x16x32_bf16 v[30:33], v[194:197], v[210:213], v[30:33]
	v_mfma_f32_16x16x32_bf16 v[22:25], v[186:189], v[218:221], v[22:25]
	v_mfma_f32_16x16x32_bf16 v[14:17], v[194:197], v[218:221], v[14:17]
	v_mfma_f32_16x16x32_bf16 v[6:9], v[186:189], v[226:229], v[6:9]
	v_mfma_f32_16x16x32_bf16 v[2:5], v[194:197], v[226:229], v[2:5]
	s_barrier
	s_add_i32 s67, 0, 0x18000
	v_add_u32_e32 v139, s67, v165
	s_add_i32 s68, 0, 0x1c000
	ds_read_b128 v[152:155], v139
	ds_read_b128 v[160:163], v139 offset:1024
	ds_read_b128 v[174:177], v139 offset:2048
	ds_read_b128 v[178:181], v139 offset:3072
	v_add_u32_e32 v139, s68, v165
	ds_read_b128 v[182:185], v139
	ds_read_b128 v[186:189], v139 offset:1024
	ds_read_b128 v[190:193], v139 offset:2048
	ds_read_b128 v[194:197], v139 offset:3072
	s_add_u32 s34, s34, 0x10000
	s_addc_u32 s35, s35, 0
	s_mov_b32 m0, s53
	ds_read_b128 v[198:201], v173 offset:32768
	ds_read_b128 v[202:205], v173 offset:33792
	ds_read_b128 v[206:209], v173 offset:34816
	ds_read_b128 v[210:213], v173 offset:35840
	ds_read_b128 v[214:217], v173 offset:36864
	ds_read_b128 v[218:221], v173 offset:37888
	ds_read_b128 v[222:225], v173 offset:38912
	ds_read_b128 v[226:229], v173 offset:39936
	global_load_lds_dwordx4 v136, s[34:35]
	s_mov_b32 m0, s54
	s_nop 0
	global_load_lds_dwordx4 v132, s[34:35]
	s_waitcnt vmcnt(8)
	s_waitcnt lgkmcnt(0)
	s_barrier
	v_mfma_f32_16x16x32_bf16 v[126:129], v[152:155], v[198:201], v[126:129]
	v_mfma_f32_16x16x32_bf16 v[122:125], v[174:177], v[198:201], v[122:125]
	v_mfma_f32_16x16x32_bf16 v[114:117], v[152:155], v[206:209], v[114:117]
	v_mfma_f32_16x16x32_bf16 v[106:109], v[174:177], v[206:209], v[106:109]
	v_mfma_f32_16x16x32_bf16 v[98:101], v[152:155], v[214:217], v[98:101]
	v_mfma_f32_16x16x32_bf16 v[90:93], v[174:177], v[214:217], v[90:93]
	v_mfma_f32_16x16x32_bf16 v[82:85], v[152:155], v[222:225], v[82:85]
	v_mfma_f32_16x16x32_bf16 v[74:77], v[174:177], v[222:225], v[74:77]
	v_mfma_f32_16x16x32_bf16 v[126:129], v[160:163], v[202:205], v[126:129]
	v_mfma_f32_16x16x32_bf16 v[122:125], v[178:181], v[202:205], v[122:125]
	v_mfma_f32_16x16x32_bf16 v[114:117], v[160:163], v[210:213], v[114:117]
	v_mfma_f32_16x16x32_bf16 v[106:109], v[178:181], v[210:213], v[106:109]
	v_mfma_f32_16x16x32_bf16 v[98:101], v[160:163], v[218:221], v[98:101]
	v_mfma_f32_16x16x32_bf16 v[90:93], v[178:181], v[218:221], v[90:93]
	v_mfma_f32_16x16x32_bf16 v[82:85], v[160:163], v[226:229], v[82:85]
	v_mfma_f32_16x16x32_bf16 v[74:77], v[178:181], v[226:229], v[74:77]
	v_mfma_f32_16x16x32_bf16 v[118:121], v[182:185], v[198:201], v[118:121]
	v_mfma_f32_16x16x32_bf16 v[110:113], v[190:193], v[198:201], v[110:113]
	v_mfma_f32_16x16x32_bf16 v[102:105], v[182:185], v[206:209], v[102:105]
	v_mfma_f32_16x16x32_bf16 v[94:97], v[190:193], v[206:209], v[94:97]
	v_mfma_f32_16x16x32_bf16 v[86:89], v[182:185], v[214:217], v[86:89]
	v_mfma_f32_16x16x32_bf16 v[78:81], v[190:193], v[214:217], v[78:81]
	v_mfma_f32_16x16x32_bf16 v[70:73], v[182:185], v[222:225], v[70:73]
	v_mfma_f32_16x16x32_bf16 v[66:69], v[190:193], v[222:225], v[66:69]
	v_mfma_f32_16x16x32_bf16 v[118:121], v[186:189], v[202:205], v[118:121]
	v_mfma_f32_16x16x32_bf16 v[110:113], v[194:197], v[202:205], v[110:113]
	v_mfma_f32_16x16x32_bf16 v[102:105], v[186:189], v[210:213], v[102:105]
	v_mfma_f32_16x16x32_bf16 v[94:97], v[194:197], v[210:213], v[94:97]
	v_mfma_f32_16x16x32_bf16 v[86:89], v[186:189], v[218:221], v[86:89]
	v_mfma_f32_16x16x32_bf16 v[78:81], v[194:197], v[218:221], v[78:81]
	v_mfma_f32_16x16x32_bf16 v[70:73], v[186:189], v[226:229], v[70:73]
	v_mfma_f32_16x16x32_bf16 v[66:69], v[194:197], v[226:229], v[66:69]
	s_barrier
; #define PG8_STAGE(bufoff, gbase, voff) do { _Pragma("unroll") for (int _i = 0; _i < 2; ++_i) \
;         __builtin_amdgcn_global_load_lds((const unsigned*)((const char*)(gbase) + (voff)[_i]), (LAS unsigned*)(lds + (bufoff) + ldsw + _i * 8192), 16, 0, 0); } while (0)
; #define PG8_LDA(dst, b, h) do { _Pragma("unroll") for (int m = 0; m < 4; ++m) _Pragma("unroll") for (int k = 0; k < 2; ++k) dst[m][k] = *(const LAS bf16x8*)(lds + PG8_SA(b, h) + aoff + m * 2048 + k * 1024); } while (0)
; #define PG8_MMA(ai, bj, At, Bt) do { __builtin_amdgcn_s_setprio(1); _Pragma("unroll") for (int m = 0; m < 4; ++m) _Pragma("unroll") for (int n = 0; n < 2; ++n) _Pragma("unroll") for (int k = 0; k < 2; ++k) \
;         acc[ai][bj][m][n] = __builtin_amdgcn_mfma_f32_16x16x32_bf16(Bt[n][k], At[m][k], acc[ai][bj][m][n], 0, 0, 0); __builtin_amdgcn_s_setprio(0); } while (0)
; #define PG8_WAIT_V(n) asm volatile("s_waitcnt vmcnt(" #n ")" ::: "memory")
; #define PG8_WAIT_L(n) asm volatile("s_waitcnt lgkmcnt(" #n ")" ::: "memory")
; #define PG8_BAR __builtin_amdgcn_s_barrier()
; #define PG8_SCHED __builtin_amdgcn_sched_barrier(0)
; template <class Epi, class Sched, int KC, bool ALIGN_EPI = false, bool SP2 = false, bool ATILED = false>
; __device__ __forceinline__ void gemm_phase(LAS unsigned char* lds, const Gemm g, const Sched& S, const Epi& E, int wave_s) {
;     ...
;             PG8_LDA(At, 1, 1); PG8_STAGE(PG8_SB(1, 0), b3, voffB); PG8_STAGE(PG8_SB(1, 1), b3 + hstepB, voffB); PG8_STAGE(PG8_SA(1, 0), a3, voffA);
;             PG8_WAIT_V(8); PG8_WAIT_L(0); PG8_BAR; PG8_MMA(1, 0, At, B0); PG8_MMA(1, 1, At, B1); PG8_BAR; PG8_SCHED;
;     ...
;         if constexpr (ALIGN_EPI) { if (wr == 0) PG8_BAR; }
	s_add_u32 s98, s28, 0x80
	s_addc_u32 s99, s29, 0
	s_add_i32 s34, s67, s41
	s_mov_b32 m0, s34
	ds_read_b128 v[198:201], v173 offset:49152
	ds_read_b128 v[202:205], v173 offset:50176
	ds_read_b128 v[206:209], v173 offset:51200
	ds_read_b128 v[210:213], v173 offset:52224
	ds_read_b128 v[214:217], v173 offset:53248
	ds_read_b128 v[218:221], v173 offset:54272
	ds_read_b128 v[222:225], v173 offset:55296
	ds_read_b128 v[226:229], v173 offset:56320
	global_load_lds_dwordx4 v134, s[98:99]
	s_add_i32 m0, s34, 0x2000
	s_add_u32 s28, s28, 0x80080
	s_addc_u32 s29, s29, 0
	s_add_i32 s34, s68, s41
	global_load_lds_dwordx4 v130, s[98:99]
	s_mov_b32 m0, s34
	s_nop 0
	global_load_lds_dwordx4 v134, s[28:29]
	s_add_i32 m0, s34, 0x2000
	s_nop 0
	global_load_lds_dwordx4 v130, s[28:29]
	s_mov_b32 m0, s55
	s_nop 0
	global_load_lds_dwordx4 v136, s[100:101]
	s_mov_b32 m0, s56
	s_nop 0
	global_load_lds_dwordx4 v132, s[100:101]
	s_waitcnt vmcnt(8)
	s_waitcnt lgkmcnt(0)
	s_barrier
	v_mfma_f32_16x16x32_bf16 v[62:65], v[152:155], v[198:201], v[62:65]
	v_mfma_f32_16x16x32_bf16 v[58:61], v[174:177], v[198:201], v[58:61]
	v_mfma_f32_16x16x32_bf16 v[50:53], v[152:155], v[206:209], v[50:53]
	v_mfma_f32_16x16x32_bf16 v[42:45], v[174:177], v[206:209], v[42:45]
	v_mfma_f32_16x16x32_bf16 v[34:37], v[152:155], v[214:217], v[34:37]
	v_mfma_f32_16x16x32_bf16 v[26:29], v[174:177], v[214:217], v[26:29]
	v_mfma_f32_16x16x32_bf16 v[18:21], v[152:155], v[222:225], v[18:21]
	v_mfma_f32_16x16x32_bf16 v[10:13], v[174:177], v[222:225], v[10:13]
	v_mfma_f32_16x16x32_bf16 v[62:65], v[160:163], v[202:205], v[62:65]
	v_mfma_f32_16x16x32_bf16 v[58:61], v[178:181], v[202:205], v[58:61]
	v_mfma_f32_16x16x32_bf16 v[50:53], v[160:163], v[210:213], v[50:53]
	v_mfma_f32_16x16x32_bf16 v[42:45], v[178:181], v[210:213], v[42:45]
	v_mfma_f32_16x16x32_bf16 v[34:37], v[160:163], v[218:221], v[34:37]
	v_mfma_f32_16x16x32_bf16 v[26:29], v[178:181], v[218:221], v[26:29]
	v_mfma_f32_16x16x32_bf16 v[18:21], v[160:163], v[226:229], v[18:21]
	v_mfma_f32_16x16x32_bf16 v[10:13], v[178:181], v[226:229], v[10:13]
	v_mfma_f32_16x16x32_bf16 v[54:57], v[182:185], v[198:201], v[54:57]
	v_mfma_f32_16x16x32_bf16 v[46:49], v[190:193], v[198:201], v[46:49]
	v_mfma_f32_16x16x32_bf16 v[38:41], v[182:185], v[206:209], v[38:41]
	v_mfma_f32_16x16x32_bf16 v[30:33], v[190:193], v[206:209], v[30:33]
	v_mfma_f32_16x16x32_bf16 v[22:25], v[182:185], v[214:217], v[22:25]
	v_mfma_f32_16x16x32_bf16 v[14:17], v[190:193], v[214:217], v[14:17]
	v_mfma_f32_16x16x32_bf16 v[6:9], v[182:185], v[222:225], v[6:9]
	v_mfma_f32_16x16x32_bf16 v[2:5], v[190:193], v[222:225], v[2:5]
	v_mfma_f32_16x16x32_bf16 v[54:57], v[186:189], v[202:205], v[54:57]
	v_mfma_f32_16x16x32_bf16 v[46:49], v[194:197], v[202:205], v[46:49]
	v_mfma_f32_16x16x32_bf16 v[38:41], v[186:189], v[210:213], v[38:41]
	v_mfma_f32_16x16x32_bf16 v[30:33], v[194:197], v[210:213], v[30:33]
	v_mfma_f32_16x16x32_bf16 v[22:25], v[186:189], v[218:221], v[22:25]
	v_mfma_f32_16x16x32_bf16 v[14:17], v[194:197], v[218:221], v[14:17]
	v_mfma_f32_16x16x32_bf16 v[6:9], v[186:189], v[226:229], v[6:9]
	v_mfma_f32_16x16x32_bf16 v[2:5], v[194:197], v[226:229], v[2:5]
	s_barrier
	s_add_i32 s65, s65, 2
	s_add_i32 s66, s66, 0x400000
	s_cmp_gt_u32 s65, 29
	s_mov_b64 s[28:29], s[30:31]
	s_cbranch_scc0 .LBB0_430
	s_and_b64 vcc, exec, s[14:15]
	s_cbranch_vccz .LBB0_433
	s_barrier

; DI float fast_exp2(float x) { return __builtin_amdgcn_exp2f(x); }
; #define LDS_WAIT() asm volatile("s_waitcnt lgkmcnt(0)" ::: "memory")
; DI int crow(int r, int hi) { return (r & 3) + 8 * (r >> 2) + 4 * hi; }
; template <int OFF> DI s16x4 tr_read(int vb) { s16x4 r; asm volatile("ds_read_b64_tr_b16 %0, %1 offset:%2" : "=&v"(r) : "v"(vb), "i"(OFF) : "memory"); return r; }
; template <int D> DI void softmax_tile(f32x16& p0, f32x16& p1, float& m_reg, float& l_reg, float& alpha, bf16x8& pa0, bf16x8& pa1, bf16x8& pa2, bf16x8& pa3, bool rowok) {
;     ...
;     const float mnC = rowok ? -mn * C : -__builtin_inff();
; #pragma unroll
;     for (int r = 0; r < 16; ++r) { p0[r] = fast_exp2(fmaf(p0[r], C, mnC)); p1[r] = fast_exp2(fmaf(p1[r], C, mnC)); }
;     float ps = 0.f;
; #pragma unroll
;     for (int r = 0; r < 16; ++r) ps += p0[r];
; #pragma unroll
;     for (int r = 0; r < 16; ++r) ps += p1[r];
;     { auto rr = __builtin_amdgcn_permlane32_swap(__float_as_uint(ps), __float_as_uint(ps), false, false);
;       ps = __uint_as_float(rr[0]) + __uint_as_float(rr[1]); }
;     l_reg = l_reg * alpha + ps;
;     ...
;     PK4(p0, 0, pa0); PK4(p0, 8, pa1); PK4(p1, 0, pa2); PK4(p1, 8, pa3);
;     ...
; }
; template <int D, int D0> DI void pv_one(f32x16& od, int vb, bf16x8 pa0, bf16x8 pa1, bf16x8 pa2, bf16x8 pa3) {
;     const s16x4 l0 = tr_read<v_rd_off<D>(D0, 0, 0)>(vb), h0 = tr_read<v_rd_off<D>(D0, 0, 1)>(vb), l1 = tr_read<v_rd_off<D>(D0, 1, 0)>(vb), h1 = tr_read<v_rd_off<D>(D0, 1, 1)>(vb);
; template <int D, class MaskF>
; DI void tile_finish(Core<D>& c, f32x16& p0, f32x16& p1, int j, const MaskF& mk, float* ws, int vb, int r32, int hi) {
;     ...
;     if (__any(alpha < 1.f)) { if (hi == 0) ws[32 + r32] = alpha; LDS_WAIT();
; #pragma unroll
;         for (int r = 0; r < 16; ++r) { const float a = ws[32 + crow(r, hi)];
; #pragma unroll
;             for (int d = 0; d < D / 32; ++d) c.o[d][r] *= a; } }
.LBB0_867:
	v_mul_f32_e32 v177, 0xbe0293ee, v217
	v_mov_b32_e32 v186, 0xff800000
	v_cndmask_b32_e32 v177, v177, v186, vcc
	v_fmamk_f32 v82, v82, 0x3e0293ee, v177
	v_fmamk_f32 v66, v66, 0x3e0293ee, v177
	v_exp_f32_e32 v186, v82
	v_exp_f32_e32 v187, v66
	v_fmamk_f32 v66, v83, 0x3e0293ee, v177
	v_fmamk_f32 v67, v67, 0x3e0293ee, v177
	v_exp_f32_e32 v66, v66
	v_exp_f32_e32 v188, v67
	v_fmamk_f32 v67, v84, 0x3e0293ee, v177
	v_fmamk_f32 v68, v68, 0x3e0293ee, v177
	v_exp_f32_e32 v67, v67
	v_exp_f32_e32 v84, v68
	v_fmamk_f32 v68, v85, 0x3e0293ee, v177
	v_fmamk_f32 v69, v69, 0x3e0293ee, v177
	v_exp_f32_e32 v68, v68
	v_exp_f32_e32 v85, v69
	v_fmamk_f32 v69, v86, 0x3e0293ee, v177
	v_fmamk_f32 v70, v70, 0x3e0293ee, v177
	v_exp_f32_e32 v69, v69
	v_exp_f32_e32 v86, v70
	v_fmamk_f32 v70, v87, 0x3e0293ee, v177
	v_fmamk_f32 v71, v71, 0x3e0293ee, v177
	v_add_f32_e32 v82, 0, v186
	v_exp_f32_e32 v70, v70
	v_exp_f32_e32 v87, v71
	v_fmamk_f32 v71, v88, 0x3e0293ee, v177
	v_fmamk_f32 v72, v72, 0x3e0293ee, v177
	v_add_f32_e32 v82, v66, v82
	v_exp_f32_e32 v71, v71
	v_exp_f32_e32 v88, v72
	v_fmamk_f32 v72, v89, 0x3e0293ee, v177
	v_fmamk_f32 v73, v73, 0x3e0293ee, v177
	v_add_f32_e32 v82, v67, v82
	v_exp_f32_e32 v72, v72
	v_exp_f32_e32 v89, v73
	v_fmamk_f32 v73, v90, 0x3e0293ee, v177
	v_fmamk_f32 v74, v74, 0x3e0293ee, v177
	v_add_f32_e32 v82, v68, v82
	v_exp_f32_e32 v73, v73
	v_exp_f32_e32 v90, v74
	v_fmamk_f32 v74, v91, 0x3e0293ee, v177
	v_fmamk_f32 v75, v75, 0x3e0293ee, v177
	v_add_f32_e32 v82, v69, v82
	v_exp_f32_e32 v74, v74
	v_exp_f32_e32 v91, v75
	v_fmamk_f32 v75, v92, 0x3e0293ee, v177
	v_fmamk_f32 v76, v76, 0x3e0293ee, v177
	v_add_f32_e32 v82, v70, v82
	v_exp_f32_e32 v75, v75
	v_exp_f32_e32 v92, v76
	v_fmamk_f32 v76, v93, 0x3e0293ee, v177
	v_fmamk_f32 v77, v77, 0x3e0293ee, v177
	v_add_f32_e32 v82, v71, v82
	v_exp_f32_e32 v76, v76
	v_exp_f32_e32 v93, v77
	v_fmamk_f32 v77, v94, 0x3e0293ee, v177
	v_fmamk_f32 v78, v78, 0x3e0293ee, v177
	v_add_f32_e32 v82, v72, v82
	v_exp_f32_e32 v77, v77
	v_exp_f32_e32 v94, v78
	v_fmamk_f32 v78, v95, 0x3e0293ee, v177
	v_fmamk_f32 v79, v79, 0x3e0293ee, v177
	v_add_f32_e32 v82, v73, v82
	v_exp_f32_e32 v78, v78
	v_exp_f32_e32 v95, v79
	v_fmamk_f32 v79, v96, 0x3e0293ee, v177
	v_fmamk_f32 v80, v80, 0x3e0293ee, v177
	v_add_f32_e32 v82, v74, v82
	v_exp_f32_e32 v79, v79
	v_exp_f32_e32 v96, v80
	v_fmamk_f32 v80, v97, 0x3e0293ee, v177
	v_add_f32_e32 v82, v75, v82
	v_exp_f32_e32 v80, v80
	v_add_f32_e32 v82, v76, v82
	v_add_f32_e32 v82, v77, v82
	v_add_f32_e32 v82, v78, v82
	v_add_f32_e32 v82, v79, v82
	v_add_f32_e32 v82, v80, v82
	v_add_f32_e32 v82, v187, v82
	v_add_f32_e32 v82, v188, v82
	v_add_f32_e32 v82, v84, v82
	v_add_f32_e32 v82, v85, v82
	v_add_f32_e32 v82, v86, v82
	v_add_f32_e32 v82, v87, v82
	v_add_f32_e32 v82, v88, v82
	v_add_f32_e32 v82, v89, v82
	v_add_f32_e32 v82, v90, v82
	v_add_f32_e32 v82, v91, v82
	v_fmac_f32_e32 v177, 0x3e0293ee, v81
	v_add_f32_e32 v82, v92, v82
	v_exp_f32_e32 v81, v177
	v_add_f32_e32 v82, v93, v82
	v_add_f32_e32 v82, v94, v82
	v_add_f32_e32 v82, v95, v82
	v_add_f32_e32 v82, v96, v82
	v_add_f32_e32 v82, v81, v82
	v_mov_b32_e32 v83, v82
	v_cvt_pk_bf16_f32 v66, v186, v66
	v_cvt_pk_bf16_f32 v67, v67, v68
	v_cvt_pk_bf16_f32 v68, v69, v70
	v_cvt_pk_bf16_f32 v69, v71, v72
	v_cvt_pk_bf16_f32 v70, v73, v74
	v_cvt_pk_bf16_f32 v71, v75, v76
	v_cvt_pk_bf16_f32 v72, v77, v78
	v_cvt_pk_bf16_f32 v73, v79, v80
	v_cvt_pk_bf16_f32 v74, v187, v188
	v_cvt_pk_bf16_f32 v75, v84, v85
	v_cvt_pk_bf16_f32 v76, v86, v87
	v_cvt_pk_bf16_f32 v77, v88, v89
	v_cvt_pk_bf16_f32 v78, v90, v91
	v_cvt_pk_bf16_f32 v79, v92, v93
	v_cvt_pk_bf16_f32 v80, v94, v95
	v_cvt_pk_bf16_f32 v81, v96, v81
	v_add_u32_e32 v96, s61, v216
	ds_read_b64_tr_b16 v[84:85], v96 offset:0
	ds_read_b64_tr_b16 v[86:87], v96 offset:0x800
	ds_read_b64_tr_b16 v[88:89], v96 offset:0x1000
	ds_read_b64_tr_b16 v[90:91], v96 offset:0x1800
	ds_read_b64_tr_b16 v[92:93], v96 offset:0x2000
	ds_read_b64_tr_b16 v[94:95], v96 offset:0x2800
	ds_read_b64_tr_b16 v[186:187], v96 offset:0x3000
	ds_read_b64_tr_b16 v[188:189], v96 offset:0x3800
	s_nop 1
	v_permlane32_swap_b32_e32 v82, v83
	v_permlane32_swap_b32_e32 v66, v68
	v_permlane32_swap_b32_e32 v67, v69
	v_permlane32_swap_b32_e32 v70, v72
	v_permlane32_swap_b32_e32 v71, v73
	v_permlane32_swap_b32_e32 v74, v76
	v_permlane32_swap_b32_e32 v75, v77
	v_permlane32_swap_b32_e32 v78, v80
	v_permlane32_swap_b32_e32 v79, v81
	v_cmp_gt_f32_e32 vcc, 1.0, v0
	s_cbranch_vccz .Lpv_fast_sel
	s_and_saveexec_b64 s[14:15], s[12:13]
	ds_write_b32 v207, v0 offset:128
	s_or_b64 exec, exec, s[14:15]
	s_waitcnt lgkmcnt(0)
	ds_read_b128 v[84:87], v213 offset:224
	ds_read_b128 v[88:91], v213 offset:192
	ds_read_b128 v[92:95], v213 offset:160
	ds_read_b128 v[186:189], v213 offset:128
	s_waitcnt lgkmcnt(3)
	v_pk_mul_f32 v[64:65], v[64:65], v[86:87]
	s_waitcnt lgkmcnt(2)
	v_pk_mul_f32 v[60:61], v[60:61], v[90:91]
	s_waitcnt lgkmcnt(1)
	v_pk_mul_f32 v[56:57], v[56:57], v[94:95]
	s_waitcnt lgkmcnt(0)
	v_pk_mul_f32 v[52:53], v[52:53], v[188:189]
	v_pk_mul_f32 v[62:63], v[62:63], v[84:85]
	v_pk_mul_f32 v[58:59], v[58:59], v[88:89]
	v_pk_mul_f32 v[54:55], v[54:55], v[92:93]
	v_pk_mul_f32 v[50:51], v[50:51], v[186:187]
	v_pk_mul_f32 v[48:49], v[48:49], v[86:87]
	v_pk_mul_f32 v[44:45], v[44:45], v[90:91]
	v_pk_mul_f32 v[40:41], v[40:41], v[94:95]
	v_pk_mul_f32 v[36:37], v[36:37], v[188:189]
	v_pk_mul_f32 v[46:47], v[46:47], v[84:85]
	v_pk_mul_f32 v[42:43], v[42:43], v[88:89]
	v_pk_mul_f32 v[38:39], v[38:39], v[92:93]
	v_pk_mul_f32 v[34:35], v[34:35], v[186:187]
	v_pk_mul_f32 v[32:33], v[32:33], v[86:87]
	v_pk_mul_f32 v[28:29], v[28:29], v[90:91]
	v_pk_mul_f32 v[24:25], v[24:25], v[94:95]
	v_pk_mul_f32 v[20:21], v[20:21], v[188:189]
	v_pk_mul_f32 v[30:31], v[30:31], v[84:85]
	v_pk_mul_f32 v[26:27], v[26:27], v[88:89]
	v_pk_mul_f32 v[22:23], v[22:23], v[92:93]
	v_pk_mul_f32 v[18:19], v[18:19], v[186:187]
	v_pk_mul_f32 v[16:17], v[16:17], v[86:87]
	v_pk_mul_f32 v[12:13], v[12:13], v[90:91]
	v_pk_mul_f32 v[8:9], v[8:9], v[94:95]
	v_pk_mul_f32 v[4:5], v[4:5], v[188:189]
	v_pk_mul_f32 v[14:15], v[14:15], v[84:85]
	v_pk_mul_f32 v[10:11], v[10:11], v[88:89]
	v_pk_mul_f32 v[6:7], v[6:7], v[92:93]
	v_pk_mul_f32 v[2:3], v[2:3], v[186:187]

; #define SBAR() __builtin_amdgcn_sched_barrier(0)
; template <int OFF> DI s16x4 tr_read(int vb) { s16x4 r; asm volatile("ds_read_b64_tr_b16 %0, %1 offset:%2" : "=&v"(r) : "v"(vb), "i"(OFF) : "memory"); return r; }
; template <int D, int D0> DI void pv_one(f32x16& od, int vb, bf16x8 pa0, bf16x8 pa1, bf16x8 pa2, bf16x8 pa3) {
;     const s16x4 l0 = tr_read<v_rd_off<D>(D0, 0, 0)>(vb), h0 = tr_read<v_rd_off<D>(D0, 0, 1)>(vb), l1 = tr_read<v_rd_off<D>(D0, 1, 0)>(vb), h1 = tr_read<v_rd_off<D>(D0, 1, 1)>(vb);
;     const s16x4 l2 = tr_read<v_rd_off<D>(D0, 2, 0)>(vb), h2 = tr_read<v_rd_off<D>(D0, 2, 1)>(vb), l3 = tr_read<v_rd_off<D>(D0, 3, 0)>(vb), h3 = tr_read<v_rd_off<D>(D0, 3, 1)>(vb);
;     asm volatile("s_waitcnt lgkmcnt(0)" ::: "memory"); SBAR();
;     ...
;     od = __builtin_amdgcn_mfma_f32_32x32x16_bf16(pa0, PK(l0, h0), od, 0, 0, 0);
;     od = __builtin_amdgcn_mfma_f32_32x32x16_bf16(pa1, PK(l1, h1), od, 0, 0, 0);
;     od = __builtin_amdgcn_mfma_f32_32x32x16_bf16(pa2, PK(l2, h2), od, 0, 0, 0);
;     od = __builtin_amdgcn_mfma_f32_32x32x16_bf16(pa3, PK(l3, h3), od, 0, 0, 0);
;     ...
; }
; template <int D> DI void pv_all(f32x16* o, int vb, bf16x8 pa0, bf16x8 pa1, bf16x8 pa2, bf16x8 pa3) {
;     pv_one<D, 0>(o[0], vb, pa0, pa1, pa2, pa3); pv_one<D, 1>(o[1], vb, pa0, pa1, pa2, pa3);
;     if constexpr (D == 128) { pv_one<D, 2>(o[2], vb, pa0, pa1, pa2, pa3); pv_one<D, 3>(o[3], vb, pa0, pa1, pa2, pa3); }
; template <int D, bool PIPE, class Seq, class MaskF, class KX>
; DI void run_tiles(Core<D>& c, char* kv, float* ws, const bf16_t* Kg0, const bf16_t* Vg0, int pitch, const Seq& seq, const MaskF& mk, const KX& kx, int tid_, int lane_) {
;     ...
;             if (e1) { stg_ld<D>(sk, Kg0 + (size_t)64 * t1 * pitch, pitch, tid); stg_ld<D>(sv, Vg0 + (size_t)64 * t1 * pitch, pitch, tid); }
;             f32x16 p0, p1; qkt<D>(p0, p1, kv + buf * KB, c.qr, r32, hi);
;             tile_finish<D>(c, p0, p1, t0, mk, ws, vb0 + buf * KB, r32, hi);
;             if (e1) { kx.apply(sk, t1, tid); stg_wrK<D>(sk, kv + (buf ^ 1) * KB, tid); stg_wrV<D>(sv, kv + 2 * KB + (buf ^ 1) * KB, tid); }
.Lpv_fast_sel:
	s_waitcnt lgkmcnt(0)
	s_nop 0
	v_mfma_f32_32x32x16_bf16 v[50:65], v[66:69], v[84:87], v[50:65]
	ds_read_b64_tr_b16 v[84:85], v96 offset:0x200
	ds_read_b64_tr_b16 v[86:87], v96 offset:0xa00
	v_mfma_f32_32x32x16_bf16 v[50:65], v[70:73], v[88:91], v[50:65]
	ds_read_b64_tr_b16 v[88:89], v96 offset:0x1200
	ds_read_b64_tr_b16 v[90:91], v96 offset:0x1a00
	v_mfma_f32_32x32x16_bf16 v[50:65], v[74:77], v[92:95], v[50:65]
	ds_read_b64_tr_b16 v[92:93], v96 offset:0x2200
	ds_read_b64_tr_b16 v[94:95], v96 offset:0x2a00
	v_mfma_f32_32x32x16_bf16 v[50:65], v[78:81], v[186:189], v[50:65]
	ds_read_b64_tr_b16 v[186:187], v96 offset:0x3200
	ds_read_b64_tr_b16 v[188:189], v96 offset:0x3a00
	s_waitcnt lgkmcnt(0)
	v_mfma_f32_32x32x16_bf16 v[34:49], v[66:69], v[84:87], v[34:49]
	ds_read_b64_tr_b16 v[84:85], v96 offset:0x400
	ds_read_b64_tr_b16 v[86:87], v96 offset:0xc00
	v_mfma_f32_32x32x16_bf16 v[34:49], v[70:73], v[88:91], v[34:49]
	ds_read_b64_tr_b16 v[88:89], v96 offset:0x1400
	ds_read_b64_tr_b16 v[90:91], v96 offset:0x1c00
	v_mfma_f32_32x32x16_bf16 v[34:49], v[74:77], v[92:95], v[34:49]
	ds_read_b64_tr_b16 v[92:93], v96 offset:0x2400
	ds_read_b64_tr_b16 v[94:95], v96 offset:0x2c00
	v_mfma_f32_32x32x16_bf16 v[34:49], v[78:81], v[186:189], v[34:49]
	ds_read_b64_tr_b16 v[186:187], v96 offset:0x3400
	ds_read_b64_tr_b16 v[188:189], v96 offset:0x3c00
	s_waitcnt lgkmcnt(0)
	v_mfma_f32_32x32x16_bf16 v[18:33], v[66:69], v[84:87], v[18:33]
	ds_read_b64_tr_b16 v[84:85], v96 offset:0x600
	ds_read_b64_tr_b16 v[86:87], v96 offset:0xe00
	v_mfma_f32_32x32x16_bf16 v[18:33], v[70:73], v[88:91], v[18:33]
	ds_read_b64_tr_b16 v[88:89], v96 offset:0x1600
	ds_read_b64_tr_b16 v[90:91], v96 offset:0x1e00
	v_mfma_f32_32x32x16_bf16 v[18:33], v[74:77], v[92:95], v[18:33]
	ds_read_b64_tr_b16 v[92:93], v96 offset:0x2600
	ds_read_b64_tr_b16 v[94:95], v96 offset:0x2e00
	v_mfma_f32_32x32x16_bf16 v[18:33], v[78:81], v[186:189], v[18:33]
	ds_read_b64_tr_b16 v[186:187], v96 offset:0x3600
	ds_read_b64_tr_b16 v[188:189], v96 offset:0x3e00
	s_waitcnt lgkmcnt(0)
	v_mfma_f32_32x32x16_bf16 v[2:17], v[66:69], v[84:87], v[2:17]
	v_cndmask_b32_e64 v67, 0, 1, s[52:53]
	s_andn2_b64 vcc, exec, s[52:53]
	v_mfma_f32_32x32x16_bf16 v[2:17], v[70:73], v[88:91], v[2:17]
	v_mfma_f32_32x32x16_bf16 v[2:17], v[74:77], v[92:95], v[2:17]
	v_mfma_f32_32x32x16_bf16 v[2:17], v[78:81], v[186:189], v[2:17]
	s_cbranch_vccnz .LBB0_873
	s_xor_b32 s14, s61, 0x4000
	s_add_i32 s14, s14, 0
	v_add_u32_e32 v69, s14, v208
	s_mov_b32 s59, s60
	v_add_u32_e32 v66, s14, v215
	v_add_u32_e32 v68, s14, v214
	s_waitcnt vmcnt(3)
	ds_write_b128 v69, v[98:101]
	s_waitcnt vmcnt(2)
	ds_write_b128 v69, v[102:105] offset:8192
	s_waitcnt vmcnt(1)
	ds_write_b128 v68, v[106:109] offset:32768
	s_waitcnt vmcnt(0)
	ds_write_b128 v66, v[144:147] offset:32768

; DI float fast_exp2(float x) { return __builtin_amdgcn_exp2f(x); }
; #define LDS_WAIT() asm volatile("s_waitcnt lgkmcnt(0)" ::: "memory")
; DI int crow(int r, int hi) { return (r & 3) + 8 * (r >> 2) + 4 * hi; }
; template <int OFF> DI s16x4 tr_read(int vb) { s16x4 r; asm volatile("ds_read_b64_tr_b16 %0, %1 offset:%2" : "=&v"(r) : "v"(vb), "i"(OFF) : "memory"); return r; }
; template <int D> DI void softmax_tile(f32x16& p0, f32x16& p1, float& m_reg, float& l_reg, float& alpha, bf16x8& pa0, bf16x8& pa1, bf16x8& pa2, bf16x8& pa3, bool rowok) {
;     ...
;     const float mnC = rowok ? -mn * C : -__builtin_inff();
; #pragma unroll
;     for (int r = 0; r < 16; ++r) { p0[r] = fast_exp2(fmaf(p0[r], C, mnC)); p1[r] = fast_exp2(fmaf(p1[r], C, mnC)); }
;     float ps = 0.f;
; #pragma unroll
;     for (int r = 0; r < 16; ++r) ps += p0[r];
; #pragma unroll
;     for (int r = 0; r < 16; ++r) ps += p1[r];
;     { auto rr = __builtin_amdgcn_permlane32_swap(__float_as_uint(ps), __float_as_uint(ps), false, false);
;       ps = __uint_as_float(rr[0]) + __uint_as_float(rr[1]); }
;     l_reg = l_reg * alpha + ps;
;     ...
;     PK4(p0, 0, pa0); PK4(p0, 8, pa1); PK4(p1, 0, pa2); PK4(p1, 8, pa3);
;     ...
; }
; template <int D, int D0> DI void pv_one(f32x16& od, int vb, bf16x8 pa0, bf16x8 pa1, bf16x8 pa2, bf16x8 pa3) {
;     const s16x4 l0 = tr_read<v_rd_off<D>(D0, 0, 0)>(vb), h0 = tr_read<v_rd_off<D>(D0, 0, 1)>(vb), l1 = tr_read<v_rd_off<D>(D0, 1, 0)>(vb), h1 = tr_read<v_rd_off<D>(D0, 1, 1)>(vb);
; template <int D, class MaskF>
; DI void tile_finish(Core<D>& c, f32x16& p0, f32x16& p1, int j, const MaskF& mk, float* ws, int vb, int r32, int hi) {
;     ...
;     if (__any(alpha < 1.f)) { if (hi == 0) ws[32 + r32] = alpha; LDS_WAIT();
; #pragma unroll
;         for (int r = 0; r < 16; ++r) { const float a = ws[32 + crow(r, hi)];
; #pragma unroll
;             for (int d = 0; d < D / 32; ++d) c.o[d][r] *= a; } }
.LBB0_888:
	v_mul_f32_e32 v186, 0xbe0293ee, v215
	v_fmamk_f32 v82, v82, 0x3e0293ee, v186
	v_fmamk_f32 v66, v66, 0x3e0293ee, v186
	v_exp_f32_e32 v187, v82
	v_exp_f32_e32 v188, v66
	v_fmamk_f32 v66, v83, 0x3e0293ee, v186
	v_fmamk_f32 v67, v67, 0x3e0293ee, v186
	v_exp_f32_e32 v66, v66
	v_exp_f32_e32 v189, v67
	v_fmamk_f32 v67, v84, 0x3e0293ee, v186
	v_fmamk_f32 v68, v68, 0x3e0293ee, v186
	v_exp_f32_e32 v67, v67
	v_exp_f32_e32 v84, v68
	v_fmamk_f32 v68, v85, 0x3e0293ee, v186
	v_fmamk_f32 v69, v69, 0x3e0293ee, v186
	v_exp_f32_e32 v68, v68
	v_exp_f32_e32 v85, v69
	v_fmamk_f32 v69, v86, 0x3e0293ee, v186
	v_fmamk_f32 v70, v70, 0x3e0293ee, v186
	v_exp_f32_e32 v69, v69
	v_exp_f32_e32 v86, v70
	v_fmamk_f32 v70, v87, 0x3e0293ee, v186
	v_fmamk_f32 v71, v71, 0x3e0293ee, v186
	v_add_f32_e32 v82, 0, v187
	v_exp_f32_e32 v70, v70
	v_exp_f32_e32 v87, v71
	v_fmamk_f32 v71, v88, 0x3e0293ee, v186
	v_fmamk_f32 v72, v72, 0x3e0293ee, v186
	v_add_f32_e32 v82, v66, v82
	v_exp_f32_e32 v71, v71
	v_exp_f32_e32 v88, v72
	v_fmamk_f32 v72, v89, 0x3e0293ee, v186
	v_fmamk_f32 v73, v73, 0x3e0293ee, v186
	v_add_f32_e32 v82, v67, v82
	v_exp_f32_e32 v72, v72
	v_exp_f32_e32 v89, v73
	v_fmamk_f32 v73, v90, 0x3e0293ee, v186
	v_fmamk_f32 v74, v74, 0x3e0293ee, v186
	v_add_f32_e32 v82, v68, v82
	v_exp_f32_e32 v73, v73
	v_exp_f32_e32 v90, v74
	v_fmamk_f32 v74, v91, 0x3e0293ee, v186
	v_fmamk_f32 v75, v75, 0x3e0293ee, v186
	v_add_f32_e32 v82, v69, v82
	v_exp_f32_e32 v74, v74
	v_exp_f32_e32 v91, v75
	v_fmamk_f32 v75, v92, 0x3e0293ee, v186
	v_fmamk_f32 v76, v76, 0x3e0293ee, v186
	v_add_f32_e32 v82, v70, v82
	v_exp_f32_e32 v75, v75
	v_exp_f32_e32 v92, v76
	v_fmamk_f32 v76, v93, 0x3e0293ee, v186
	v_fmamk_f32 v77, v77, 0x3e0293ee, v186
	v_add_f32_e32 v82, v71, v82
	v_exp_f32_e32 v76, v76
	v_exp_f32_e32 v93, v77
	v_fmamk_f32 v77, v94, 0x3e0293ee, v186
	v_fmamk_f32 v78, v78, 0x3e0293ee, v186
	v_add_f32_e32 v82, v72, v82
	v_exp_f32_e32 v77, v77
	v_exp_f32_e32 v94, v78
	v_fmamk_f32 v78, v95, 0x3e0293ee, v186
	v_fmamk_f32 v79, v79, 0x3e0293ee, v186
	v_add_f32_e32 v82, v73, v82
	v_exp_f32_e32 v78, v78
	v_exp_f32_e32 v95, v79
	v_fmamk_f32 v79, v96, 0x3e0293ee, v186
	v_fmamk_f32 v80, v80, 0x3e0293ee, v186
	v_add_f32_e32 v82, v74, v82
	v_exp_f32_e32 v79, v79
	v_exp_f32_e32 v96, v80
	v_fmamk_f32 v80, v97, 0x3e0293ee, v186
	v_add_f32_e32 v82, v75, v82
	v_exp_f32_e32 v80, v80
	v_add_f32_e32 v82, v76, v82
	v_add_f32_e32 v82, v77, v82
	v_add_f32_e32 v82, v78, v82
	v_add_f32_e32 v82, v79, v82
	v_add_f32_e32 v82, v80, v82
	v_add_f32_e32 v82, v188, v82
	v_add_f32_e32 v82, v189, v82
	v_add_f32_e32 v82, v84, v82
	v_add_f32_e32 v82, v85, v82
	v_add_f32_e32 v82, v86, v82
	v_add_f32_e32 v82, v87, v82
	v_add_f32_e32 v82, v88, v82
	v_add_f32_e32 v82, v89, v82
	v_add_f32_e32 v82, v90, v82
	v_add_f32_e32 v82, v91, v82
	v_fmac_f32_e32 v186, 0x3e0293ee, v81
	v_add_f32_e32 v82, v92, v82
	v_exp_f32_e32 v81, v186
	v_add_f32_e32 v82, v93, v82
	v_add_f32_e32 v82, v94, v82
	v_add_f32_e32 v82, v95, v82
	v_add_f32_e32 v82, v96, v82
	v_add_f32_e32 v82, v81, v82
	v_mov_b32_e32 v83, v82
	v_cvt_pk_bf16_f32 v66, v187, v66
	v_cvt_pk_bf16_f32 v67, v67, v68
	v_cvt_pk_bf16_f32 v68, v69, v70
	v_cvt_pk_bf16_f32 v69, v71, v72
	v_cvt_pk_bf16_f32 v70, v73, v74
	v_cvt_pk_bf16_f32 v71, v75, v76
	v_cvt_pk_bf16_f32 v72, v77, v78
	v_cvt_pk_bf16_f32 v73, v79, v80
	v_cvt_pk_bf16_f32 v74, v188, v189
	v_cvt_pk_bf16_f32 v75, v84, v85
	v_cvt_pk_bf16_f32 v76, v86, v87
	v_cvt_pk_bf16_f32 v77, v88, v89
	v_cvt_pk_bf16_f32 v78, v90, v91
	v_cvt_pk_bf16_f32 v79, v92, v93
	v_cvt_pk_bf16_f32 v80, v94, v95
	v_cvt_pk_bf16_f32 v81, v96, v81
	v_add_u32_e32 v96, s93, v214
	ds_read_b64_tr_b16 v[84:85], v96 offset:0
	ds_read_b64_tr_b16 v[86:87], v96 offset:0x800
	ds_read_b64_tr_b16 v[88:89], v96 offset:0x1000
	ds_read_b64_tr_b16 v[90:91], v96 offset:0x1800
	ds_read_b64_tr_b16 v[92:93], v96 offset:0x2000
	ds_read_b64_tr_b16 v[94:95], v96 offset:0x2800
	ds_read_b64_tr_b16 v[186:187], v96 offset:0x3000
	ds_read_b64_tr_b16 v[188:189], v96 offset:0x3800
	s_nop 1
	v_permlane32_swap_b32_e32 v82, v83
	v_permlane32_swap_b32_e32 v66, v68
	v_permlane32_swap_b32_e32 v67, v69
	v_permlane32_swap_b32_e32 v70, v72
	v_permlane32_swap_b32_e32 v71, v73
	v_permlane32_swap_b32_e32 v74, v76
	v_permlane32_swap_b32_e32 v75, v77
	v_permlane32_swap_b32_e32 v78, v80
	v_permlane32_swap_b32_e32 v79, v81
	v_cmp_gt_f32_e32 vcc, 1.0, v217
	s_cbranch_vccz .Lpv_fast_win
	s_and_saveexec_b64 s[14:15], s[12:13]
	ds_write_b32 v204, v217 offset:128
	s_or_b64 exec, exec, s[14:15]
	s_waitcnt lgkmcnt(0)
	ds_read_b128 v[84:87], v211 offset:224
	ds_read_b128 v[88:91], v211 offset:192
	ds_read_b128 v[92:95], v211 offset:160
	ds_read_b128 v[186:189], v211 offset:128
	s_waitcnt lgkmcnt(3)
	v_pk_mul_f32 v[64:65], v[64:65], v[86:87]
	s_waitcnt lgkmcnt(2)
	v_pk_mul_f32 v[60:61], v[60:61], v[90:91]
	s_waitcnt lgkmcnt(1)
	v_pk_mul_f32 v[56:57], v[56:57], v[94:95]
	s_waitcnt lgkmcnt(0)
	v_pk_mul_f32 v[52:53], v[52:53], v[188:189]
	v_pk_mul_f32 v[62:63], v[62:63], v[84:85]
	v_pk_mul_f32 v[58:59], v[58:59], v[88:89]
	v_pk_mul_f32 v[54:55], v[54:55], v[92:93]
	v_pk_mul_f32 v[50:51], v[50:51], v[186:187]
	v_pk_mul_f32 v[48:49], v[48:49], v[86:87]
	v_pk_mul_f32 v[44:45], v[44:45], v[90:91]
	v_pk_mul_f32 v[40:41], v[40:41], v[94:95]
	v_pk_mul_f32 v[36:37], v[36:37], v[188:189]
	v_pk_mul_f32 v[46:47], v[46:47], v[84:85]
	v_pk_mul_f32 v[42:43], v[42:43], v[88:89]
	v_pk_mul_f32 v[38:39], v[38:39], v[92:93]
	v_pk_mul_f32 v[34:35], v[34:35], v[186:187]
	v_pk_mul_f32 v[32:33], v[32:33], v[86:87]
	v_pk_mul_f32 v[28:29], v[28:29], v[90:91]
	v_pk_mul_f32 v[24:25], v[24:25], v[94:95]
	v_pk_mul_f32 v[20:21], v[20:21], v[188:189]
	v_pk_mul_f32 v[30:31], v[30:31], v[84:85]
	v_pk_mul_f32 v[26:27], v[26:27], v[88:89]
	v_pk_mul_f32 v[22:23], v[22:23], v[92:93]
	v_pk_mul_f32 v[18:19], v[18:19], v[186:187]
	v_pk_mul_f32 v[16:17], v[16:17], v[86:87]
	v_pk_mul_f32 v[12:13], v[12:13], v[90:91]
	v_pk_mul_f32 v[8:9], v[8:9], v[94:95]
	v_pk_mul_f32 v[4:5], v[4:5], v[188:189]
	v_pk_mul_f32 v[14:15], v[14:15], v[84:85]
	v_pk_mul_f32 v[10:11], v[10:11], v[88:89]
	v_pk_mul_f32 v[6:7], v[6:7], v[92:93]
	v_pk_mul_f32 v[2:3], v[2:3], v[186:187]

; #define SBAR() __builtin_amdgcn_sched_barrier(0)
; template <int OFF> DI s16x4 tr_read(int vb) { s16x4 r; asm volatile("ds_read_b64_tr_b16 %0, %1 offset:%2" : "=&v"(r) : "v"(vb), "i"(OFF) : "memory"); return r; }
; template <int D, int D0> DI void pv_one(f32x16& od, int vb, bf16x8 pa0, bf16x8 pa1, bf16x8 pa2, bf16x8 pa3) {
;     const s16x4 l0 = tr_read<v_rd_off<D>(D0, 0, 0)>(vb), h0 = tr_read<v_rd_off<D>(D0, 0, 1)>(vb), l1 = tr_read<v_rd_off<D>(D0, 1, 0)>(vb), h1 = tr_read<v_rd_off<D>(D0, 1, 1)>(vb);
;     const s16x4 l2 = tr_read<v_rd_off<D>(D0, 2, 0)>(vb), h2 = tr_read<v_rd_off<D>(D0, 2, 1)>(vb), l3 = tr_read<v_rd_off<D>(D0, 3, 0)>(vb), h3 = tr_read<v_rd_off<D>(D0, 3, 1)>(vb);
;     asm volatile("s_waitcnt lgkmcnt(0)" ::: "memory"); SBAR();
;     ...
;     od = __builtin_amdgcn_mfma_f32_32x32x16_bf16(pa0, PK(l0, h0), od, 0, 0, 0);
;     od = __builtin_amdgcn_mfma_f32_32x32x16_bf16(pa1, PK(l1, h1), od, 0, 0, 0);
;     od = __builtin_amdgcn_mfma_f32_32x32x16_bf16(pa2, PK(l2, h2), od, 0, 0, 0);
;     od = __builtin_amdgcn_mfma_f32_32x32x16_bf16(pa3, PK(l3, h3), od, 0, 0, 0);
;     ...
; }
; template <int D> DI void pv_all(f32x16* o, int vb, bf16x8 pa0, bf16x8 pa1, bf16x8 pa2, bf16x8 pa3) {
;     pv_one<D, 0>(o[0], vb, pa0, pa1, pa2, pa3); pv_one<D, 1>(o[1], vb, pa0, pa1, pa2, pa3);
;     if constexpr (D == 128) { pv_one<D, 2>(o[2], vb, pa0, pa1, pa2, pa3); pv_one<D, 3>(o[3], vb, pa0, pa1, pa2, pa3); }
; template <int D, bool PIPE, class Seq, class MaskF, class KX>
; DI void run_tiles(Core<D>& c, char* kv, float* ws, const bf16_t* Kg0, const bf16_t* Vg0, int pitch, const Seq& seq, const MaskF& mk, const KX& kx, int tid_, int lane_) {
;     ...
;             if (e1) { kx.apply(sk, t1, tid); stg_wrK<D>(sk, kv + (buf ^ 1) * KB, tid); stg_wrV<D>(sv, kv + 2 * KB + (buf ^ 1) * KB, tid); }
.Lpv_fast_win:
	s_waitcnt lgkmcnt(0)
	s_nop 0
	v_mfma_f32_32x32x16_bf16 v[50:65], v[66:69], v[84:87], v[50:65]
	ds_read_b64_tr_b16 v[84:85], v96 offset:0x200
	ds_read_b64_tr_b16 v[86:87], v96 offset:0xa00
	v_mfma_f32_32x32x16_bf16 v[50:65], v[70:73], v[88:91], v[50:65]
	ds_read_b64_tr_b16 v[88:89], v96 offset:0x1200
	ds_read_b64_tr_b16 v[90:91], v96 offset:0x1a00
	v_mfma_f32_32x32x16_bf16 v[50:65], v[74:77], v[92:95], v[50:65]
	ds_read_b64_tr_b16 v[92:93], v96 offset:0x2200
	ds_read_b64_tr_b16 v[94:95], v96 offset:0x2a00
	v_mfma_f32_32x32x16_bf16 v[50:65], v[78:81], v[186:189], v[50:65]
	ds_read_b64_tr_b16 v[186:187], v96 offset:0x3200
	ds_read_b64_tr_b16 v[188:189], v96 offset:0x3a00
	s_waitcnt lgkmcnt(0)
	v_mfma_f32_32x32x16_bf16 v[34:49], v[66:69], v[84:87], v[34:49]
	ds_read_b64_tr_b16 v[84:85], v96 offset:0x400
	ds_read_b64_tr_b16 v[86:87], v96 offset:0xc00
	v_mfma_f32_32x32x16_bf16 v[34:49], v[70:73], v[88:91], v[34:49]
	ds_read_b64_tr_b16 v[88:89], v96 offset:0x1400
	ds_read_b64_tr_b16 v[90:91], v96 offset:0x1c00
	v_mfma_f32_32x32x16_bf16 v[34:49], v[74:77], v[92:95], v[34:49]
	ds_read_b64_tr_b16 v[92:93], v96 offset:0x2400
	ds_read_b64_tr_b16 v[94:95], v96 offset:0x2c00
	v_mfma_f32_32x32x16_bf16 v[34:49], v[78:81], v[186:189], v[34:49]
	ds_read_b64_tr_b16 v[186:187], v96 offset:0x3400
	ds_read_b64_tr_b16 v[188:189], v96 offset:0x3c00
	s_waitcnt lgkmcnt(0)
	v_mfma_f32_32x32x16_bf16 v[18:33], v[66:69], v[84:87], v[18:33]
	ds_read_b64_tr_b16 v[84:85], v96 offset:0x600
	ds_read_b64_tr_b16 v[86:87], v96 offset:0xe00
	v_mfma_f32_32x32x16_bf16 v[18:33], v[70:73], v[88:91], v[18:33]
	ds_read_b64_tr_b16 v[88:89], v96 offset:0x1600
	ds_read_b64_tr_b16 v[90:91], v96 offset:0x1e00
	v_mfma_f32_32x32x16_bf16 v[18:33], v[74:77], v[92:95], v[18:33]
	ds_read_b64_tr_b16 v[92:93], v96 offset:0x2600
	ds_read_b64_tr_b16 v[94:95], v96 offset:0x2e00
	v_mfma_f32_32x32x16_bf16 v[18:33], v[78:81], v[186:189], v[18:33]
	ds_read_b64_tr_b16 v[186:187], v96 offset:0x3600
	ds_read_b64_tr_b16 v[188:189], v96 offset:0x3e00
	s_waitcnt lgkmcnt(0)
	v_mfma_f32_32x32x16_bf16 v[2:17], v[66:69], v[84:87], v[2:17]
	v_cndmask_b32_e64 v66, 0, 1, s[2:3]
	s_andn2_b64 vcc, exec, s[2:3]
	v_mfma_f32_32x32x16_bf16 v[2:17], v[70:73], v[88:91], v[2:17]
	v_mfma_f32_32x32x16_bf16 v[2:17], v[74:77], v[92:95], v[2:17]
	v_mfma_f32_32x32x16_bf16 v[2:17], v[78:81], v[186:189], v[2:17]
	s_cbranch_vccnz .LBB0_894
	s_xor_b32 s2, s93, 0x4000
	s_add_i32 s2, s2, 0
	v_add_u32_e32 v69, s2, v205
	s_mov_b32 s92, s88
	v_add_u32_e32 v67, s2, v213
	v_add_u32_e32 v68, s2, v212
	s_waitcnt vmcnt(3)
	ds_write_b128 v69, v[98:101]
	s_waitcnt vmcnt(2)
	ds_write_b128 v69, v[102:105] offset:8192
	s_waitcnt vmcnt(1)
	ds_write_b128 v68, v[106:109] offset:32768
	s_waitcnt vmcnt(0)
	ds_write_b128 v67, v[144:147] offset:32768

; #define PG8_STAGE(bufoff, gbase, voff) do { _Pragma("unroll") for (int _i = 0; _i < 2; ++_i) \
;         __builtin_amdgcn_global_load_lds((const unsigned*)((const char*)(gbase) + (voff)[_i]), (LAS unsigned*)(lds + (bufoff) + ldsw + _i * 8192), 16, 0, 0); } while (0)
; #define PG8_LDA(dst, b, h) do { _Pragma("unroll") for (int m = 0; m < 4; ++m) _Pragma("unroll") for (int k = 0; k < 2; ++k) dst[m][k] = *(const LAS bf16x8*)(lds + PG8_SA(b, h) + aoff + m * 2048 + k * 1024); } while (0)
; #define PG8_LDB(dst, b, h) do { _Pragma("unroll") for (int n = 0; n < 2; ++n) _Pragma("unroll") for (int k = 0; k < 2; ++k) dst[n][k] = *(const LAS bf16x8*)(lds + PG8_SB(b, h) + boff + n * 2048 + k * 1024); } while (0)
; #define PG8_WAIT_V(n) asm volatile("s_waitcnt vmcnt(" #n ")" ::: "memory")
; #define PG8_WAIT_L(n) asm volatile("s_waitcnt lgkmcnt(" #n ")" ::: "memory")
; #define PG8_BAR __builtin_amdgcn_s_barrier()
; template <class Epi, class Sched, int KC, bool ALIGN_EPI = false, bool SP2 = false, bool ATILED = false>
; __device__ __forceinline__ void gemm_phase(LAS unsigned char* lds, const Gemm g, const Sched& S, const Epi& E, int wave_s) {
;     ...
;         const bool has_next = S.next(ui + 1, nxt);
;         const char* nA = has_next ? (const char*)g.A + (size_t)nxt.pm * tstepA : cA; const char* nB = has_next ? (const char*)g.Bt + (size_t)nxt.pn * tstep : cB;
;         for (int t = 0; t < nt; t += 2) {
;             const bool last = (t == nt - 2);
;             const char* a1 = cA + PG8_AOFF(t + 1);
;             const char* a2 = last ? nA : cA + PG8_AOFF(t + 2); const char* b2 = last ? nB : cB + (size_t)(t + 2) * kstep;
;             const char* a3 = a2 + kstep; const char* b3 = b2 + kstep;
;             if (last && has_next) S.a_ready(nxt);
;             if constexpr (SP2) {
;             PG8_LDB(B0, 0, 0); PG8_LDB(B1, 0, 1); PG8_SCHED; PG8_LDA(At, 0, 0); PG8_STAGE(PG8_SA(1, 1), a1 + hstepA, voffA);
;             PG8_WAIT_V(8); PG8_WAIT_L(0); PG8_BAR; PG8_MMA(0, 0, At, B0); PG8_MMA(0, 1, At, B1); PG8_BAR; PG8_SCHED;
;     ...
; #pragma unroll
;         for (int a = 0; a < 2; ++a)
; #pragma unroll
;             for (int b = 0; b < 2; ++b)
; #pragma unroll
;                 for (int m = 0; m < 4; ++m)
; #pragma unroll
;                     for (int n = 0; n < 2; ++n) acc[a][b][m][n] = (f32x4){0.f, 0.f, 0.f, 0.f};
;         cur = nxt; cA = nA; cB = nB; ++ui;
.LBB0_1020:
	v_mov_b64_e32 v[2:3], 0x200
	s_ashr_i32 s9, s8, 31
	v_cmp_lt_i64_e32 vcc, s[10:11], v[2:3]
	s_lshl_b64 s[10:11], s[8:9], 20
	s_add_u32 s10, s27, s10
	s_addc_u32 s11, s28, s11
	s_and_b64 s[12:13], vcc, exec
	s_cselect_b32 s9, s11, s21
	s_cselect_b32 s15, s10, s20
	s_ashr_i32 s3, s2, 31
	s_lshl_b64 s[12:13], s[2:3], 20
	s_add_u32 s12, s29, s12
	s_addc_u32 s13, s30, s13
	s_and_b64 s[22:23], vcc, exec
	s_cselect_b32 s3, s13, s19
	s_cselect_b32 s17, s12, s18
	s_add_u32 s46, s18, 0x100
	s_addc_u32 s47, s19, 0
	s_add_u32 s18, s20, 0x80080
	v_mov_b32_e32 v2, 0
	s_addc_u32 s19, s21, 0
	s_mov_b32 s48, -2
	v_mov_b32_e32 v3, v2
	v_mov_b32_e32 v4, v2
	v_mov_b32_e32 v5, v2
	v_mov_b32_e32 v6, v2
	v_mov_b32_e32 v7, v2
	v_mov_b32_e32 v8, v2
	v_mov_b32_e32 v9, v2
	v_mov_b32_e32 v18, v2
	v_mov_b32_e32 v19, v2
	v_mov_b32_e32 v20, v2
	v_mov_b32_e32 v21, v2
	v_mov_b32_e32 v22, v2
	v_mov_b32_e32 v23, v2
	v_mov_b32_e32 v24, v2
	v_mov_b32_e32 v25, v2
	v_mov_b32_e32 v34, v2
	v_mov_b32_e32 v35, v2
	v_mov_b32_e32 v36, v2
	v_mov_b32_e32 v37, v2
	v_mov_b32_e32 v38, v2
	v_mov_b32_e32 v39, v2
	v_mov_b32_e32 v40, v2
	v_mov_b32_e32 v41, v2
	v_mov_b32_e32 v50, v2
	v_mov_b32_e32 v51, v2
	v_mov_b32_e32 v52, v2
	v_mov_b32_e32 v53, v2
	v_mov_b32_e32 v54, v2
	v_mov_b32_e32 v55, v2
	v_mov_b32_e32 v56, v2
	v_mov_b32_e32 v57, v2
	v_mov_b32_e32 v10, v2
	v_mov_b32_e32 v11, v2
	v_mov_b32_e32 v12, v2
	v_mov_b32_e32 v13, v2
	v_mov_b32_e32 v14, v2
	v_mov_b32_e32 v15, v2
	v_mov_b32_e32 v16, v2
	v_mov_b32_e32 v17, v2
	v_mov_b32_e32 v26, v2
	v_mov_b32_e32 v27, v2
	v_mov_b32_e32 v28, v2
	v_mov_b32_e32 v29, v2
	v_mov_b32_e32 v30, v2
	v_mov_b32_e32 v31, v2
	v_mov_b32_e32 v32, v2
	v_mov_b32_e32 v33, v2
	v_mov_b32_e32 v42, v2
	v_mov_b32_e32 v43, v2
	v_mov_b32_e32 v44, v2
	v_mov_b32_e32 v45, v2
	v_mov_b32_e32 v46, v2
	v_mov_b32_e32 v47, v2
	v_mov_b32_e32 v48, v2
	v_mov_b32_e32 v49, v2
	v_mov_b32_e32 v58, v2
	v_mov_b32_e32 v59, v2
	v_mov_b32_e32 v60, v2
	v_mov_b32_e32 v61, v2
	v_mov_b32_e32 v62, v2
	v_mov_b32_e32 v63, v2
	v_mov_b32_e32 v64, v2
	v_mov_b32_e32 v65, v2
	v_mov_b32_e32 v66, v2
	v_mov_b32_e32 v67, v2
	v_mov_b32_e32 v68, v2
	v_mov_b32_e32 v69, v2
	v_mov_b32_e32 v70, v2
	v_mov_b32_e32 v71, v2
	v_mov_b32_e32 v72, v2
	v_mov_b32_e32 v73, v2
	s_waitcnt vmcnt(0)
	v_mov_b32_e32 v82, v2
	v_mov_b32_e32 v83, v2
	v_mov_b32_e32 v84, v2
	v_mov_b32_e32 v85, v2
	v_mov_b32_e32 v86, v2
	v_mov_b32_e32 v87, v2
	v_mov_b32_e32 v88, v2
	v_mov_b32_e32 v89, v2
	v_mov_b32_e32 v98, v2
	v_mov_b32_e32 v99, v2
	v_mov_b32_e32 v100, v2
	v_mov_b32_e32 v101, v2
	v_mov_b32_e32 v102, v2
	v_mov_b32_e32 v103, v2
	v_mov_b32_e32 v104, v2
	v_mov_b32_e32 v105, v2
	v_mov_b32_e32 v114, v2
	v_mov_b32_e32 v115, v2
	v_mov_b32_e32 v116, v2
	v_mov_b32_e32 v117, v2
	v_mov_b32_e32 v118, v2
	v_mov_b32_e32 v119, v2
	v_mov_b32_e32 v120, v2
	v_mov_b32_e32 v121, v2
	v_mov_b32_e32 v74, v2
	v_mov_b32_e32 v75, v2
	v_mov_b32_e32 v76, v2
	v_mov_b32_e32 v77, v2
	v_mov_b32_e32 v78, v2
	v_mov_b32_e32 v79, v2
	v_mov_b32_e32 v80, v2
	v_mov_b32_e32 v81, v2
	v_mov_b32_e32 v90, v2
	v_mov_b32_e32 v91, v2
	v_mov_b32_e32 v92, v2
	v_mov_b32_e32 v93, v2
	v_mov_b32_e32 v94, v2
	v_mov_b32_e32 v95, v2
	v_mov_b32_e32 v96, v2
	v_mov_b32_e32 v97, v2
	v_mov_b32_e32 v106, v2
	v_mov_b32_e32 v107, v2
	v_mov_b32_e32 v108, v2
	v_mov_b32_e32 v109, v2
	v_mov_b32_e32 v110, v2
	v_mov_b32_e32 v111, v2
	v_mov_b32_e32 v112, v2
	v_mov_b32_e32 v113, v2
	v_mov_b32_e32 v122, v2
	v_mov_b32_e32 v123, v2
	v_mov_b32_e32 v124, v2
	v_mov_b32_e32 v125, v2
	v_mov_b32_e32 v126, v2
	v_mov_b32_e32 v127, v2
	v_mov_b32_e32 v128, v2
	v_mov_b32_e32 v129, v2
	s_add_u32 s20, s18, 0xfff80080
	s_addc_u32 s21, s19, -1
	s_add_i32 s49, 0, 0x10000
	s_cmp_eq_u32 s48, 28
	s_cselect_b32 s23, s9, s21
	s_cselect_b32 s22, s15, s20
	s_cselect_b32 s21, s3, s47
	s_cselect_b32 s20, s17, s46
	s_add_i32 s52, 0, 0x14000
	v_add_u32_e32 v142, s49, v229
	v_add_u32_e32 v158, s52, v229
	ds_read_b128 v[130:133], v142
	ds_read_b128 v[134:137], v142 offset:1024
	ds_read_b128 v[138:141], v142 offset:2048
	ds_read_b128 v[142:145], v142 offset:3072
	ds_read_b128 v[146:149], v158
	ds_read_b128 v[150:153], v158 offset:1024
	ds_read_b128 v[154:157], v158 offset:2048
	ds_read_b128 v[158:161], v158 offset:3072
	s_add_i32 m0, s34, 0xc000
	ds_read_b128 v[162:165], v230
	ds_read_b128 v[166:169], v230 offset:1024
	ds_read_b128 v[170:173], v230 offset:2048
	ds_read_b128 v[174:177], v230 offset:3072
	ds_read_b128 v[178:181], v230 offset:4096
	ds_read_b128 v[182:185], v230 offset:5120
	ds_read_b128 v[186:189], v230 offset:6144
	ds_read_b128 v[190:193], v230 offset:7168
	global_load_lds_dwordx4 v208, s[18:19]
	s_add_i32 m0, s34, 0xe000
	s_nop 0
	global_load_lds_dwordx4 v206, s[18:19]
	s_waitcnt vmcnt(32)
	s_waitcnt lgkmcnt(0)
	s_barrier
; #define PG8_STAGE(bufoff, gbase, voff) do { _Pragma("unroll") for (int _i = 0; _i < 2; ++_i) \
;         __builtin_amdgcn_global_load_lds((const unsigned*)((const char*)(gbase) + (voff)[_i]), (LAS unsigned*)(lds + (bufoff) + ldsw + _i * 8192), 16, 0, 0); } while (0)
; #define PG8_LDA(dst, b, h) do { _Pragma("unroll") for (int m = 0; m < 4; ++m) _Pragma("unroll") for (int k = 0; k < 2; ++k) dst[m][k] = *(const LAS bf16x8*)(lds + PG8_SA(b, h) + aoff + m * 2048 + k * 1024); } while (0)
; #define PG8_LDB(dst, b, h) do { _Pragma("unroll") for (int n = 0; n < 2; ++n) _Pragma("unroll") for (int k = 0; k < 2; ++k) dst[n][k] = *(const LAS bf16x8*)(lds + PG8_SB(b, h) + boff + n * 2048 + k * 1024); } while (0)
; #define PG8_MMA(ai, bj, At, Bt) do { __builtin_amdgcn_s_setprio(1); _Pragma("unroll") for (int m = 0; m < 4; ++m) _Pragma("unroll") for (int n = 0; n < 2; ++n) _Pragma("unroll") for (int k = 0; k < 2; ++k) \
;         acc[ai][bj][m][n] = __builtin_amdgcn_mfma_f32_16x16x32_bf16(Bt[n][k], At[m][k], acc[ai][bj][m][n], 0, 0, 0); __builtin_amdgcn_s_setprio(0); } while (0)
; #define PG8_WAIT_V(n) asm volatile("s_waitcnt vmcnt(" #n ")" ::: "memory")
; #define PG8_WAIT_L(n) asm volatile("s_waitcnt lgkmcnt(" #n ")" ::: "memory")
; #define PG8_BAR __builtin_amdgcn_s_barrier()
; #define PG8_SCHED __builtin_amdgcn_sched_barrier(0)
; template <class Epi, class Sched, int KC, bool ALIGN_EPI = false, bool SP2 = false, bool ATILED = false>
; __device__ __forceinline__ void gemm_phase(LAS unsigned char* lds, const Gemm g, const Sched& S, const Epi& E, int wave_s) {
;     ...
;             PG8_LDB(B0, 0, 0); PG8_LDB(B1, 0, 1); PG8_SCHED; PG8_LDA(At, 0, 0); PG8_STAGE(PG8_SA(1, 1), a1 + hstepA, voffA);
;             PG8_WAIT_V(8); PG8_WAIT_L(0); PG8_BAR; PG8_MMA(0, 0, At, B0); PG8_MMA(0, 1, At, B1); PG8_BAR; PG8_SCHED;
;             PG8_LDA(At, 0, 1); PG8_STAGE(PG8_SB(0, 0), b2, voffB); PG8_STAGE(PG8_SB(0, 1), b2 + hstepB, voffB); PG8_STAGE(PG8_SA(0, 0), a2, voffA);
;             PG8_WAIT_V(8); PG8_WAIT_L(0); PG8_BAR; PG8_MMA(1, 0, At, B0); PG8_MMA(1, 1, At, B1); PG8_BAR; PG8_SCHED;
	v_mfma_f32_16x16x32_bf16 v[126:129], v[130:133], v[162:165], v[126:129]
	v_mfma_f32_16x16x32_bf16 v[122:125], v[138:141], v[162:165], v[122:125]
	v_mfma_f32_16x16x32_bf16 v[110:113], v[130:133], v[170:173], v[110:113]
	v_mfma_f32_16x16x32_bf16 v[106:109], v[138:141], v[170:173], v[106:109]
	v_mfma_f32_16x16x32_bf16 v[94:97], v[130:133], v[178:181], v[94:97]
	v_mfma_f32_16x16x32_bf16 v[90:93], v[138:141], v[178:181], v[90:93]
	v_mfma_f32_16x16x32_bf16 v[78:81], v[130:133], v[186:189], v[78:81]
	v_mfma_f32_16x16x32_bf16 v[74:77], v[138:141], v[186:189], v[74:77]
	v_mfma_f32_16x16x32_bf16 v[126:129], v[134:137], v[166:169], v[126:129]
	v_mfma_f32_16x16x32_bf16 v[122:125], v[142:145], v[166:169], v[122:125]
	v_mfma_f32_16x16x32_bf16 v[110:113], v[134:137], v[174:177], v[110:113]
	v_mfma_f32_16x16x32_bf16 v[106:109], v[142:145], v[174:177], v[106:109]
	v_mfma_f32_16x16x32_bf16 v[94:97], v[134:137], v[182:185], v[94:97]
	v_mfma_f32_16x16x32_bf16 v[90:93], v[142:145], v[182:185], v[90:93]
	v_mfma_f32_16x16x32_bf16 v[78:81], v[134:137], v[190:193], v[78:81]
	v_mfma_f32_16x16x32_bf16 v[74:77], v[142:145], v[190:193], v[74:77]
	v_mfma_f32_16x16x32_bf16 v[118:121], v[146:149], v[162:165], v[118:121]
	v_mfma_f32_16x16x32_bf16 v[114:117], v[154:157], v[162:165], v[114:117]
	v_mfma_f32_16x16x32_bf16 v[102:105], v[146:149], v[170:173], v[102:105]
	v_mfma_f32_16x16x32_bf16 v[98:101], v[154:157], v[170:173], v[98:101]
	v_mfma_f32_16x16x32_bf16 v[86:89], v[146:149], v[178:181], v[86:89]
	v_mfma_f32_16x16x32_bf16 v[82:85], v[154:157], v[178:181], v[82:85]
	v_mfma_f32_16x16x32_bf16 v[70:73], v[146:149], v[186:189], v[70:73]
	v_mfma_f32_16x16x32_bf16 v[66:69], v[154:157], v[186:189], v[66:69]
	v_mfma_f32_16x16x32_bf16 v[118:121], v[150:153], v[166:169], v[118:121]
	v_mfma_f32_16x16x32_bf16 v[114:117], v[158:161], v[166:169], v[114:117]
	v_mfma_f32_16x16x32_bf16 v[102:105], v[150:153], v[174:177], v[102:105]
	v_mfma_f32_16x16x32_bf16 v[98:101], v[158:161], v[174:177], v[98:101]
	v_mfma_f32_16x16x32_bf16 v[86:89], v[150:153], v[182:185], v[86:89]
	v_mfma_f32_16x16x32_bf16 v[82:85], v[158:161], v[182:185], v[82:85]
	v_mfma_f32_16x16x32_bf16 v[70:73], v[150:153], v[190:193], v[70:73]
	v_mfma_f32_16x16x32_bf16 v[66:69], v[158:161], v[190:193], v[66:69]
	s_barrier
	s_add_u32 s100, s22, 0x80
	s_addc_u32 s101, s23, 0
	s_add_i32 s49, s49, s31
	s_mov_b32 m0, s49
	ds_read_b128 v[162:165], v230 offset:16384
	ds_read_b128 v[166:169], v230 offset:17408
	ds_read_b128 v[170:173], v230 offset:18432
	ds_read_b128 v[174:177], v230 offset:19456
	ds_read_b128 v[178:181], v230 offset:20480
	ds_read_b128 v[182:185], v230 offset:21504
	ds_read_b128 v[186:189], v230 offset:22528
	ds_read_b128 v[190:193], v230 offset:23552
	global_load_lds_dwordx4 v0, s[20:21]
	s_add_i32 m0, s49, 0x2000
	s_add_u32 s50, s20, 0x20000
	s_addc_u32 s51, s21, 0
	s_add_i32 s49, s52, s31
	global_load_lds_dwordx4 v202, s[20:21]
	s_mov_b32 m0, s49
	s_nop 0
	global_load_lds_dwordx4 v0, s[50:51]
	s_add_i32 m0, s49, 0x2000
	s_nop 0
	global_load_lds_dwordx4 v202, s[50:51]
	s_mov_b32 m0, s34
	s_nop 0
	global_load_lds_dwordx4 v198, s[22:23]
	s_mov_b32 m0, s35
	s_nop 0
	global_load_lds_dwordx4 v200, s[22:23]
	s_waitcnt vmcnt(32)
	s_waitcnt lgkmcnt(0)
	s_barrier
	v_mfma_f32_16x16x32_bf16 v[62:65], v[130:133], v[162:165], v[62:65]
	v_mfma_f32_16x16x32_bf16 v[58:61], v[138:141], v[162:165], v[58:61]
	v_mfma_f32_16x16x32_bf16 v[46:49], v[130:133], v[170:173], v[46:49]
	v_mfma_f32_16x16x32_bf16 v[42:45], v[138:141], v[170:173], v[42:45]
	v_mfma_f32_16x16x32_bf16 v[30:33], v[130:133], v[178:181], v[30:33]
	v_mfma_f32_16x16x32_bf16 v[26:29], v[138:141], v[178:181], v[26:29]
	v_mfma_f32_16x16x32_bf16 v[14:17], v[130:133], v[186:189], v[14:17]
	v_mfma_f32_16x16x32_bf16 v[10:13], v[138:141], v[186:189], v[10:13]
	v_mfma_f32_16x16x32_bf16 v[62:65], v[134:137], v[166:169], v[62:65]
	v_mfma_f32_16x16x32_bf16 v[58:61], v[142:145], v[166:169], v[58:61]
	v_mfma_f32_16x16x32_bf16 v[46:49], v[134:137], v[174:177], v[46:49]
	v_mfma_f32_16x16x32_bf16 v[42:45], v[142:145], v[174:177], v[42:45]
	v_mfma_f32_16x16x32_bf16 v[30:33], v[134:137], v[182:185], v[30:33]
	v_mfma_f32_16x16x32_bf16 v[26:29], v[142:145], v[182:185], v[26:29]
	v_mfma_f32_16x16x32_bf16 v[14:17], v[134:137], v[190:193], v[14:17]
	v_mfma_f32_16x16x32_bf16 v[10:13], v[142:145], v[190:193], v[10:13]
	v_mfma_f32_16x16x32_bf16 v[54:57], v[146:149], v[162:165], v[54:57]
	v_mfma_f32_16x16x32_bf16 v[50:53], v[154:157], v[162:165], v[50:53]
	v_mfma_f32_16x16x32_bf16 v[38:41], v[146:149], v[170:173], v[38:41]
	v_mfma_f32_16x16x32_bf16 v[34:37], v[154:157], v[170:173], v[34:37]
	v_mfma_f32_16x16x32_bf16 v[22:25], v[146:149], v[178:181], v[22:25]
	v_mfma_f32_16x16x32_bf16 v[18:21], v[154:157], v[178:181], v[18:21]
	v_mfma_f32_16x16x32_bf16 v[6:9], v[146:149], v[186:189], v[6:9]
	v_mfma_f32_16x16x32_bf16 v[2:5], v[154:157], v[186:189], v[2:5]
	v_mfma_f32_16x16x32_bf16 v[54:57], v[150:153], v[166:169], v[54:57]
	v_mfma_f32_16x16x32_bf16 v[50:53], v[158:161], v[166:169], v[50:53]
	v_mfma_f32_16x16x32_bf16 v[38:41], v[150:153], v[174:177], v[38:41]
	v_mfma_f32_16x16x32_bf16 v[34:37], v[158:161], v[174:177], v[34:37]
	v_mfma_f32_16x16x32_bf16 v[22:25], v[150:153], v[182:185], v[22:25]
	v_mfma_f32_16x16x32_bf16 v[18:21], v[158:161], v[182:185], v[18:21]
	v_mfma_f32_16x16x32_bf16 v[6:9], v[150:153], v[190:193], v[6:9]
	v_mfma_f32_16x16x32_bf16 v[2:5], v[158:161], v[190:193], v[2:5]
	s_barrier
; #define PG8_STAGE(bufoff, gbase, voff) do { _Pragma("unroll") for (int _i = 0; _i < 2; ++_i) \
;         __builtin_amdgcn_global_load_lds((const unsigned*)((const char*)(gbase) + (voff)[_i]), (LAS unsigned*)(lds + (bufoff) + ldsw + _i * 8192), 16, 0, 0); } while (0)
; #define PG8_LDA(dst, b, h) do { _Pragma("unroll") for (int m = 0; m < 4; ++m) _Pragma("unroll") for (int k = 0; k < 2; ++k) dst[m][k] = *(const LAS bf16x8*)(lds + PG8_SA(b, h) + aoff + m * 2048 + k * 1024); } while (0)
; #define PG8_LDB(dst, b, h) do { _Pragma("unroll") for (int n = 0; n < 2; ++n) _Pragma("unroll") for (int k = 0; k < 2; ++k) dst[n][k] = *(const LAS bf16x8*)(lds + PG8_SB(b, h) + boff + n * 2048 + k * 1024); } while (0)
; #define PG8_MMA(ai, bj, At, Bt) do { __builtin_amdgcn_s_setprio(1); _Pragma("unroll") for (int m = 0; m < 4; ++m) _Pragma("unroll") for (int n = 0; n < 2; ++n) _Pragma("unroll") for (int k = 0; k < 2; ++k) \
;         acc[ai][bj][m][n] = __builtin_amdgcn_mfma_f32_16x16x32_bf16(Bt[n][k], At[m][k], acc[ai][bj][m][n], 0, 0, 0); __builtin_amdgcn_s_setprio(0); } while (0)
; #define PG8_WAIT_V(n) asm volatile("s_waitcnt vmcnt(" #n ")" ::: "memory")
; #define PG8_WAIT_L(n) asm volatile("s_waitcnt lgkmcnt(" #n ")" ::: "memory")
; #define PG8_BAR __builtin_amdgcn_s_barrier()
; #define PG8_SCHED __builtin_amdgcn_sched_barrier(0)
; template <class Epi, class Sched, int KC, bool ALIGN_EPI = false, bool SP2 = false, bool ATILED = false>
; __device__ __forceinline__ void gemm_phase(LAS unsigned char* lds, const Gemm g, const Sched& S, const Epi& E, int wave_s) {
;     ...
;             PG8_LDB(B0, 1, 0); PG8_LDB(B1, 1, 1); PG8_SCHED; PG8_LDA(At, 1, 0); PG8_STAGE(PG8_SA(0, 1), a2 + hstepA, voffA);
;             PG8_WAIT_V(8); PG8_WAIT_L(0); PG8_BAR; PG8_MMA(0, 0, At, B0); PG8_MMA(0, 1, At, B1); PG8_BAR; PG8_SCHED;
;             PG8_LDA(At, 1, 1); PG8_STAGE(PG8_SB(1, 0), b3, voffB); PG8_STAGE(PG8_SB(1, 1), b3 + hstepB, voffB); PG8_STAGE(PG8_SA(1, 0), a3, voffA);
;             PG8_WAIT_V(8); PG8_WAIT_L(0); PG8_BAR; PG8_MMA(1, 0, At, B0); PG8_MMA(1, 1, At, B1); PG8_BAR; PG8_SCHED;
	s_add_i32 s49, 0, 0x18000
	s_add_i32 s50, 0, 0x1c000
	v_add_u32_e32 v142, s49, v229
	v_add_u32_e32 v158, s50, v229
	ds_read_b128 v[130:133], v142
	ds_read_b128 v[134:137], v142 offset:1024
	ds_read_b128 v[138:141], v142 offset:2048
	ds_read_b128 v[142:145], v142 offset:3072
	ds_read_b128 v[146:149], v158
	ds_read_b128 v[150:153], v158 offset:1024
	ds_read_b128 v[154:157], v158 offset:2048
	ds_read_b128 v[158:161], v158 offset:3072
	s_add_u32 s22, s22, 0x80000
	s_addc_u32 s23, s23, 0
	s_mov_b32 m0, s36
	ds_read_b128 v[162:165], v230 offset:32768
	ds_read_b128 v[166:169], v230 offset:33792
	ds_read_b128 v[170:173], v230 offset:34816
	ds_read_b128 v[174:177], v230 offset:35840
	ds_read_b128 v[178:181], v230 offset:36864
	ds_read_b128 v[182:185], v230 offset:37888
	ds_read_b128 v[186:189], v230 offset:38912
	ds_read_b128 v[190:193], v230 offset:39936
	global_load_lds_dwordx4 v198, s[22:23]
	s_mov_b32 m0, s37
	s_nop 0
	global_load_lds_dwordx4 v200, s[22:23]
	s_waitcnt vmcnt(8)
	s_waitcnt lgkmcnt(0)
	s_barrier
	v_mfma_f32_16x16x32_bf16 v[126:129], v[130:133], v[162:165], v[126:129]
	v_mfma_f32_16x16x32_bf16 v[122:125], v[138:141], v[162:165], v[122:125]
	v_mfma_f32_16x16x32_bf16 v[110:113], v[130:133], v[170:173], v[110:113]
	v_mfma_f32_16x16x32_bf16 v[106:109], v[138:141], v[170:173], v[106:109]
	v_mfma_f32_16x16x32_bf16 v[94:97], v[130:133], v[178:181], v[94:97]
	v_mfma_f32_16x16x32_bf16 v[90:93], v[138:141], v[178:181], v[90:93]
	v_mfma_f32_16x16x32_bf16 v[78:81], v[130:133], v[186:189], v[78:81]
	v_mfma_f32_16x16x32_bf16 v[74:77], v[138:141], v[186:189], v[74:77]
	v_mfma_f32_16x16x32_bf16 v[126:129], v[134:137], v[166:169], v[126:129]
	v_mfma_f32_16x16x32_bf16 v[122:125], v[142:145], v[166:169], v[122:125]
	v_mfma_f32_16x16x32_bf16 v[110:113], v[134:137], v[174:177], v[110:113]
	v_mfma_f32_16x16x32_bf16 v[106:109], v[142:145], v[174:177], v[106:109]
	v_mfma_f32_16x16x32_bf16 v[94:97], v[134:137], v[182:185], v[94:97]
	v_mfma_f32_16x16x32_bf16 v[90:93], v[142:145], v[182:185], v[90:93]
	v_mfma_f32_16x16x32_bf16 v[78:81], v[134:137], v[190:193], v[78:81]
	v_mfma_f32_16x16x32_bf16 v[74:77], v[142:145], v[190:193], v[74:77]
	v_mfma_f32_16x16x32_bf16 v[118:121], v[146:149], v[162:165], v[118:121]
	v_mfma_f32_16x16x32_bf16 v[114:117], v[154:157], v[162:165], v[114:117]
	v_mfma_f32_16x16x32_bf16 v[102:105], v[146:149], v[170:173], v[102:105]
	v_mfma_f32_16x16x32_bf16 v[98:101], v[154:157], v[170:173], v[98:101]
	v_mfma_f32_16x16x32_bf16 v[86:89], v[146:149], v[178:181], v[86:89]
	v_mfma_f32_16x16x32_bf16 v[82:85], v[154:157], v[178:181], v[82:85]
	v_mfma_f32_16x16x32_bf16 v[70:73], v[146:149], v[186:189], v[70:73]
	v_mfma_f32_16x16x32_bf16 v[66:69], v[154:157], v[186:189], v[66:69]
	v_mfma_f32_16x16x32_bf16 v[118:121], v[150:153], v[166:169], v[118:121]
	v_mfma_f32_16x16x32_bf16 v[114:117], v[158:161], v[166:169], v[114:117]
	v_mfma_f32_16x16x32_bf16 v[102:105], v[150:153], v[174:177], v[102:105]
	v_mfma_f32_16x16x32_bf16 v[98:101], v[158:161], v[174:177], v[98:101]
	v_mfma_f32_16x16x32_bf16 v[86:89], v[150:153], v[182:185], v[86:89]
	v_mfma_f32_16x16x32_bf16 v[82:85], v[158:161], v[182:185], v[82:85]
	v_mfma_f32_16x16x32_bf16 v[70:73], v[150:153], v[190:193], v[70:73]
	v_mfma_f32_16x16x32_bf16 v[66:69], v[158:161], v[190:193], v[66:69]
	s_barrier
	s_add_u32 s98, s20, 0x80
	s_addc_u32 s99, s21, 0
	s_add_i32 s22, s49, s31
	s_mov_b32 m0, s22
	ds_read_b128 v[162:165], v230 offset:49152
	ds_read_b128 v[166:169], v230 offset:50176
	ds_read_b128 v[170:173], v230 offset:51200
	ds_read_b128 v[174:177], v230 offset:52224
	ds_read_b128 v[178:181], v230 offset:53248
	ds_read_b128 v[182:185], v230 offset:54272
	ds_read_b128 v[186:189], v230 offset:55296
	ds_read_b128 v[190:193], v230 offset:56320
	global_load_lds_dwordx4 v0, s[98:99]
	s_add_i32 m0, s22, 0x2000
	s_add_u32 s20, s20, 0x20080
	s_addc_u32 s21, s21, 0
	s_add_i32 s22, s50, s31
	global_load_lds_dwordx4 v202, s[98:99]
	s_mov_b32 m0, s22
	s_nop 0
	global_load_lds_dwordx4 v0, s[20:21]
	s_add_i32 m0, s22, 0x2000
	s_nop 0
	global_load_lds_dwordx4 v202, s[20:21]
	s_mov_b32 m0, s41
	s_nop 0
	global_load_lds_dwordx4 v198, s[100:101]
	s_mov_b32 m0, s42
	s_nop 0
	global_load_lds_dwordx4 v200, s[100:101]
	s_waitcnt vmcnt(8)
	s_waitcnt lgkmcnt(0)
	s_barrier
	v_mfma_f32_16x16x32_bf16 v[62:65], v[130:133], v[162:165], v[62:65]
	v_mfma_f32_16x16x32_bf16 v[58:61], v[138:141], v[162:165], v[58:61]
	v_mfma_f32_16x16x32_bf16 v[46:49], v[130:133], v[170:173], v[46:49]
	v_mfma_f32_16x16x32_bf16 v[42:45], v[138:141], v[170:173], v[42:45]
	v_mfma_f32_16x16x32_bf16 v[30:33], v[130:133], v[178:181], v[30:33]
	v_mfma_f32_16x16x32_bf16 v[26:29], v[138:141], v[178:181], v[26:29]
	v_mfma_f32_16x16x32_bf16 v[14:17], v[130:133], v[186:189], v[14:17]
	v_mfma_f32_16x16x32_bf16 v[10:13], v[138:141], v[186:189], v[10:13]
	v_mfma_f32_16x16x32_bf16 v[62:65], v[134:137], v[166:169], v[62:65]
	v_mfma_f32_16x16x32_bf16 v[58:61], v[142:145], v[166:169], v[58:61]
	v_mfma_f32_16x16x32_bf16 v[46:49], v[134:137], v[174:177], v[46:49]
	v_mfma_f32_16x16x32_bf16 v[42:45], v[142:145], v[174:177], v[42:45]
	v_mfma_f32_16x16x32_bf16 v[30:33], v[134:137], v[182:185], v[30:33]
	v_mfma_f32_16x16x32_bf16 v[26:29], v[142:145], v[182:185], v[26:29]
	v_mfma_f32_16x16x32_bf16 v[14:17], v[134:137], v[190:193], v[14:17]
	v_mfma_f32_16x16x32_bf16 v[10:13], v[142:145], v[190:193], v[10:13]
	v_mfma_f32_16x16x32_bf16 v[54:57], v[146:149], v[162:165], v[54:57]
	v_mfma_f32_16x16x32_bf16 v[50:53], v[154:157], v[162:165], v[50:53]
	v_mfma_f32_16x16x32_bf16 v[38:41], v[146:149], v[170:173], v[38:41]
	v_mfma_f32_16x16x32_bf16 v[34:37], v[154:157], v[170:173], v[34:37]
	v_mfma_f32_16x16x32_bf16 v[22:25], v[146:149], v[178:181], v[22:25]
	v_mfma_f32_16x16x32_bf16 v[18:21], v[154:157], v[178:181], v[18:21]
	v_mfma_f32_16x16x32_bf16 v[6:9], v[146:149], v[186:189], v[6:9]
	v_mfma_f32_16x16x32_bf16 v[2:5], v[154:157], v[186:189], v[2:5]
	v_mfma_f32_16x16x32_bf16 v[54:57], v[150:153], v[166:169], v[54:57]
	v_mfma_f32_16x16x32_bf16 v[50:53], v[158:161], v[166:169], v[50:53]
	v_mfma_f32_16x16x32_bf16 v[38:41], v[150:153], v[174:177], v[38:41]
	v_mfma_f32_16x16x32_bf16 v[34:37], v[158:161], v[174:177], v[34:37]
	v_mfma_f32_16x16x32_bf16 v[22:25], v[150:153], v[182:185], v[22:25]
	v_mfma_f32_16x16x32_bf16 v[18:21], v[158:161], v[182:185], v[18:21]
	v_mfma_f32_16x16x32_bf16 v[6:9], v[150:153], v[190:193], v[6:9]
	v_mfma_f32_16x16x32_bf16 v[2:5], v[158:161], v[190:193], v[2:5]
	s_barrier
	s_add_i32 s48, s48, 2
	s_add_u32 s46, s46, 0x100
	s_addc_u32 s47, s47, 0
	s_add_u32 s18, s18, 0x100
	s_addc_u32 s19, s19, 0
	s_cmp_gt_u32 s48, 29
; #define PG8_STAGE(bufoff, gbase, voff) do { _Pragma("unroll") for (int _i = 0; _i < 2; ++_i) \
;         __builtin_amdgcn_global_load_lds((const unsigned*)((const char*)(gbase) + (voff)[_i]), (LAS unsigned*)(lds + (bufoff) + ldsw + _i * 8192), 16, 0, 0); } while (0)
; #define PG8_LDA(dst, b, h) do { _Pragma("unroll") for (int m = 0; m < 4; ++m) _Pragma("unroll") for (int k = 0; k < 2; ++k) dst[m][k] = *(const LAS bf16x8*)(lds + PG8_SA(b, h) + aoff + m * 2048 + k * 1024); } while (0)
; #define PG8_LDB(dst, b, h) do { _Pragma("unroll") for (int n = 0; n < 2; ++n) _Pragma("unroll") for (int k = 0; k < 2; ++k) dst[n][k] = *(const LAS bf16x8*)(lds + PG8_SB(b, h) + boff + n * 2048 + k * 1024); } while (0)
; #define PG8_MMA(ai, bj, At, Bt) do { __builtin_amdgcn_s_setprio(1); _Pragma("unroll") for (int m = 0; m < 4; ++m) _Pragma("unroll") for (int n = 0; n < 2; ++n) _Pragma("unroll") for (int k = 0; k < 2; ++k) \
;         acc[ai][bj][m][n] = __builtin_amdgcn_mfma_f32_16x16x32_bf16(Bt[n][k], At[m][k], acc[ai][bj][m][n], 0, 0, 0); __builtin_amdgcn_s_setprio(0); } while (0)
; #define PG8_WAIT_V(n) asm volatile("s_waitcnt vmcnt(" #n ")" ::: "memory")
; #define PG8_BAR __builtin_amdgcn_s_barrier()
; template <class Epi, class Sched, int KC, bool ALIGN_EPI = false, bool SP2 = false, bool ATILED = false>
; __device__ __forceinline__ void gemm_phase(LAS unsigned char* lds, const Gemm g, const Sched& S, const Epi& E, int wave_s) {
;     ...
;         for (int t = 0; t < nt; t += 2) {
;             const bool last = (t == nt - 2);
;             const char* a1 = cA + PG8_AOFF(t + 1);
;             const char* a2 = last ? nA : cA + PG8_AOFF(t + 2); const char* b2 = last ? nB : cB + (size_t)(t + 2) * kstep;
;             const char* a3 = a2 + kstep; const char* b3 = b2 + kstep;
;             if (last && has_next) S.a_ready(nxt);
;             if constexpr (SP2) {
;             PG8_LDB(B0, 0, 0); PG8_LDB(B1, 0, 1); PG8_SCHED; PG8_LDA(At, 0, 0); PG8_STAGE(PG8_SA(1, 1), a1 + hstepA, voffA);
;             PG8_WAIT_V(8); PG8_WAIT_L(0); PG8_BAR; PG8_MMA(0, 0, At, B0); PG8_MMA(0, 1, At, B1); PG8_BAR; PG8_SCHED;
;             PG8_LDA(At, 0, 1); PG8_STAGE(PG8_SB(0, 0), b2, voffB); PG8_STAGE(PG8_SB(0, 1), b2 + hstepB, voffB); PG8_STAGE(PG8_SA(0, 0), a2, voffA);
;             PG8_WAIT_V(8); PG8_WAIT_L(0); PG8_BAR; PG8_MMA(1, 0, At, B0); PG8_MMA(1, 1, At, B1); PG8_BAR; PG8_SCHED;
.LBB0_1021:
	s_add_u32 s20, s18, 0xfff80080
	s_addc_u32 s21, s19, -1
	s_add_i32 s49, 0, 0x10000
	s_cmp_eq_u32 s48, 28
	s_cselect_b32 s23, s9, s21
	s_cselect_b32 s22, s15, s20
	s_cselect_b32 s21, s3, s47
	s_cselect_b32 s20, s17, s46
	s_add_i32 s52, 0, 0x14000
	v_add_u32_e32 v142, s49, v229
	v_add_u32_e32 v158, s52, v229
	ds_read_b128 v[130:133], v142
	ds_read_b128 v[134:137], v142 offset:1024
	ds_read_b128 v[138:141], v142 offset:2048
	ds_read_b128 v[142:145], v142 offset:3072
	ds_read_b128 v[146:149], v158
	ds_read_b128 v[150:153], v158 offset:1024
	ds_read_b128 v[154:157], v158 offset:2048
	ds_read_b128 v[158:161], v158 offset:3072
	s_add_i32 m0, s34, 0xc000
	ds_read_b128 v[162:165], v230
	ds_read_b128 v[166:169], v230 offset:1024
	ds_read_b128 v[170:173], v230 offset:2048
	ds_read_b128 v[174:177], v230 offset:3072
	ds_read_b128 v[178:181], v230 offset:4096
	ds_read_b128 v[182:185], v230 offset:5120
	ds_read_b128 v[186:189], v230 offset:6144
	ds_read_b128 v[190:193], v230 offset:7168
	global_load_lds_dwordx4 v208, s[18:19]
	s_add_i32 m0, s34, 0xe000
	s_nop 0
	global_load_lds_dwordx4 v206, s[18:19]
	s_waitcnt vmcnt(8)
	s_waitcnt lgkmcnt(0)
	s_barrier
	v_mfma_f32_16x16x32_bf16 v[126:129], v[130:133], v[162:165], v[126:129]
	v_mfma_f32_16x16x32_bf16 v[122:125], v[138:141], v[162:165], v[122:125]
	v_mfma_f32_16x16x32_bf16 v[110:113], v[130:133], v[170:173], v[110:113]
	v_mfma_f32_16x16x32_bf16 v[106:109], v[138:141], v[170:173], v[106:109]
	v_mfma_f32_16x16x32_bf16 v[94:97], v[130:133], v[178:181], v[94:97]
	v_mfma_f32_16x16x32_bf16 v[90:93], v[138:141], v[178:181], v[90:93]
	v_mfma_f32_16x16x32_bf16 v[78:81], v[130:133], v[186:189], v[78:81]
	v_mfma_f32_16x16x32_bf16 v[74:77], v[138:141], v[186:189], v[74:77]
	v_mfma_f32_16x16x32_bf16 v[126:129], v[134:137], v[166:169], v[126:129]
	v_mfma_f32_16x16x32_bf16 v[122:125], v[142:145], v[166:169], v[122:125]
	v_mfma_f32_16x16x32_bf16 v[110:113], v[134:137], v[174:177], v[110:113]
	v_mfma_f32_16x16x32_bf16 v[106:109], v[142:145], v[174:177], v[106:109]
	v_mfma_f32_16x16x32_bf16 v[94:97], v[134:137], v[182:185], v[94:97]
	v_mfma_f32_16x16x32_bf16 v[90:93], v[142:145], v[182:185], v[90:93]
	v_mfma_f32_16x16x32_bf16 v[78:81], v[134:137], v[190:193], v[78:81]
	v_mfma_f32_16x16x32_bf16 v[74:77], v[142:145], v[190:193], v[74:77]
	v_mfma_f32_16x16x32_bf16 v[118:121], v[146:149], v[162:165], v[118:121]
	v_mfma_f32_16x16x32_bf16 v[114:117], v[154:157], v[162:165], v[114:117]
	v_mfma_f32_16x16x32_bf16 v[102:105], v[146:149], v[170:173], v[102:105]
	v_mfma_f32_16x16x32_bf16 v[98:101], v[154:157], v[170:173], v[98:101]
	v_mfma_f32_16x16x32_bf16 v[86:89], v[146:149], v[178:181], v[86:89]
	v_mfma_f32_16x16x32_bf16 v[82:85], v[154:157], v[178:181], v[82:85]
	v_mfma_f32_16x16x32_bf16 v[70:73], v[146:149], v[186:189], v[70:73]
	v_mfma_f32_16x16x32_bf16 v[66:69], v[154:157], v[186:189], v[66:69]
	v_mfma_f32_16x16x32_bf16 v[118:121], v[150:153], v[166:169], v[118:121]
	v_mfma_f32_16x16x32_bf16 v[114:117], v[158:161], v[166:169], v[114:117]
	v_mfma_f32_16x16x32_bf16 v[102:105], v[150:153], v[174:177], v[102:105]
	v_mfma_f32_16x16x32_bf16 v[98:101], v[158:161], v[174:177], v[98:101]
	v_mfma_f32_16x16x32_bf16 v[86:89], v[150:153], v[182:185], v[86:89]
	v_mfma_f32_16x16x32_bf16 v[82:85], v[158:161], v[182:185], v[82:85]
	v_mfma_f32_16x16x32_bf16 v[70:73], v[150:153], v[190:193], v[70:73]
	v_mfma_f32_16x16x32_bf16 v[66:69], v[158:161], v[190:193], v[66:69]
	s_barrier
	s_add_u32 s100, s22, 0x80
	s_addc_u32 s101, s23, 0
	s_add_i32 s49, s49, s31
	s_mov_b32 m0, s49
	ds_read_b128 v[162:165], v230 offset:16384
	ds_read_b128 v[166:169], v230 offset:17408
	ds_read_b128 v[170:173], v230 offset:18432
	ds_read_b128 v[174:177], v230 offset:19456
	ds_read_b128 v[178:181], v230 offset:20480
	ds_read_b128 v[182:185], v230 offset:21504
	ds_read_b128 v[186:189], v230 offset:22528
	ds_read_b128 v[190:193], v230 offset:23552
	global_load_lds_dwordx4 v0, s[20:21]
	s_add_i32 m0, s49, 0x2000
	s_add_u32 s50, s20, 0x20000
	s_addc_u32 s51, s21, 0
	s_add_i32 s49, s52, s31
	global_load_lds_dwordx4 v202, s[20:21]
	s_mov_b32 m0, s49
	s_nop 0
	global_load_lds_dwordx4 v0, s[50:51]
	s_add_i32 m0, s49, 0x2000
	s_nop 0
	global_load_lds_dwordx4 v202, s[50:51]
	s_mov_b32 m0, s34
	s_nop 0
	global_load_lds_dwordx4 v198, s[22:23]
	s_mov_b32 m0, s35
	s_nop 0
	global_load_lds_dwordx4 v200, s[22:23]
	s_waitcnt vmcnt(8)
	s_waitcnt lgkmcnt(0)
	s_barrier
	v_mfma_f32_16x16x32_bf16 v[62:65], v[130:133], v[162:165], v[62:65]
	v_mfma_f32_16x16x32_bf16 v[58:61], v[138:141], v[162:165], v[58:61]
	v_mfma_f32_16x16x32_bf16 v[46:49], v[130:133], v[170:173], v[46:49]
	v_mfma_f32_16x16x32_bf16 v[42:45], v[138:141], v[170:173], v[42:45]
	v_mfma_f32_16x16x32_bf16 v[30:33], v[130:133], v[178:181], v[30:33]
	v_mfma_f32_16x16x32_bf16 v[26:29], v[138:141], v[178:181], v[26:29]
	v_mfma_f32_16x16x32_bf16 v[14:17], v[130:133], v[186:189], v[14:17]
	v_mfma_f32_16x16x32_bf16 v[10:13], v[138:141], v[186:189], v[10:13]
	v_mfma_f32_16x16x32_bf16 v[62:65], v[134:137], v[166:169], v[62:65]
	v_mfma_f32_16x16x32_bf16 v[58:61], v[142:145], v[166:169], v[58:61]
	v_mfma_f32_16x16x32_bf16 v[46:49], v[134:137], v[174:177], v[46:49]
	v_mfma_f32_16x16x32_bf16 v[42:45], v[142:145], v[174:177], v[42:45]
	v_mfma_f32_16x16x32_bf16 v[30:33], v[134:137], v[182:185], v[30:33]
	v_mfma_f32_16x16x32_bf16 v[26:29], v[142:145], v[182:185], v[26:29]
	v_mfma_f32_16x16x32_bf16 v[14:17], v[134:137], v[190:193], v[14:17]
	v_mfma_f32_16x16x32_bf16 v[10:13], v[142:145], v[190:193], v[10:13]
	v_mfma_f32_16x16x32_bf16 v[54:57], v[146:149], v[162:165], v[54:57]
	v_mfma_f32_16x16x32_bf16 v[50:53], v[154:157], v[162:165], v[50:53]
	v_mfma_f32_16x16x32_bf16 v[38:41], v[146:149], v[170:173], v[38:41]
	v_mfma_f32_16x16x32_bf16 v[34:37], v[154:157], v[170:173], v[34:37]
	v_mfma_f32_16x16x32_bf16 v[22:25], v[146:149], v[178:181], v[22:25]
	v_mfma_f32_16x16x32_bf16 v[18:21], v[154:157], v[178:181], v[18:21]
	v_mfma_f32_16x16x32_bf16 v[6:9], v[146:149], v[186:189], v[6:9]
	v_mfma_f32_16x16x32_bf16 v[2:5], v[154:157], v[186:189], v[2:5]
	v_mfma_f32_16x16x32_bf16 v[54:57], v[150:153], v[166:169], v[54:57]
	v_mfma_f32_16x16x32_bf16 v[50:53], v[158:161], v[166:169], v[50:53]
	v_mfma_f32_16x16x32_bf16 v[38:41], v[150:153], v[174:177], v[38:41]
	v_mfma_f32_16x16x32_bf16 v[34:37], v[158:161], v[174:177], v[34:37]
	v_mfma_f32_16x16x32_bf16 v[22:25], v[150:153], v[182:185], v[22:25]
	v_mfma_f32_16x16x32_bf16 v[18:21], v[158:161], v[182:185], v[18:21]
	v_mfma_f32_16x16x32_bf16 v[6:9], v[150:153], v[190:193], v[6:9]
	v_mfma_f32_16x16x32_bf16 v[2:5], v[158:161], v[190:193], v[2:5]
	s_barrier
; #define PG8_STAGE(bufoff, gbase, voff) do { _Pragma("unroll") for (int _i = 0; _i < 2; ++_i) \
;         __builtin_amdgcn_global_load_lds((const unsigned*)((const char*)(gbase) + (voff)[_i]), (LAS unsigned*)(lds + (bufoff) + ldsw + _i * 8192), 16, 0, 0); } while (0)
; #define PG8_LDA(dst, b, h) do { _Pragma("unroll") for (int m = 0; m < 4; ++m) _Pragma("unroll") for (int k = 0; k < 2; ++k) dst[m][k] = *(const LAS bf16x8*)(lds + PG8_SA(b, h) + aoff + m * 2048 + k * 1024); } while (0)
; #define PG8_LDB(dst, b, h) do { _Pragma("unroll") for (int n = 0; n < 2; ++n) _Pragma("unroll") for (int k = 0; k < 2; ++k) dst[n][k] = *(const LAS bf16x8*)(lds + PG8_SB(b, h) + boff + n * 2048 + k * 1024); } while (0)
; #define PG8_MMA(ai, bj, At, Bt) do { __builtin_amdgcn_s_setprio(1); _Pragma("unroll") for (int m = 0; m < 4; ++m) _Pragma("unroll") for (int n = 0; n < 2; ++n) _Pragma("unroll") for (int k = 0; k < 2; ++k) \
;         acc[ai][bj][m][n] = __builtin_amdgcn_mfma_f32_16x16x32_bf16(Bt[n][k], At[m][k], acc[ai][bj][m][n], 0, 0, 0); __builtin_amdgcn_s_setprio(0); } while (0)
; #define PG8_WAIT_V(n) asm volatile("s_waitcnt vmcnt(" #n ")" ::: "memory")
; #define PG8_WAIT_L(n) asm volatile("s_waitcnt lgkmcnt(" #n ")" ::: "memory")
; #define PG8_BAR __builtin_amdgcn_s_barrier()
; #define PG8_SCHED __builtin_amdgcn_sched_barrier(0)
; template <class Epi, class Sched, int KC, bool ALIGN_EPI = false, bool SP2 = false, bool ATILED = false>
; __device__ __forceinline__ void gemm_phase(LAS unsigned char* lds, const Gemm g, const Sched& S, const Epi& E, int wave_s) {
;     ...
;             PG8_LDB(B0, 1, 0); PG8_LDB(B1, 1, 1); PG8_SCHED; PG8_LDA(At, 1, 0); PG8_STAGE(PG8_SA(0, 1), a2 + hstepA, voffA);
;             PG8_WAIT_V(8); PG8_WAIT_L(0); PG8_BAR; PG8_MMA(0, 0, At, B0); PG8_MMA(0, 1, At, B1); PG8_BAR; PG8_SCHED;
;             PG8_LDA(At, 1, 1); PG8_STAGE(PG8_SB(1, 0), b3, voffB); PG8_STAGE(PG8_SB(1, 1), b3 + hstepB, voffB); PG8_STAGE(PG8_SA(1, 0), a3, voffA);
;             PG8_WAIT_V(8); PG8_WAIT_L(0); PG8_BAR; PG8_MMA(1, 0, At, B0); PG8_MMA(1, 1, At, B1); PG8_BAR; PG8_SCHED;
	s_add_i32 s49, 0, 0x18000
	s_add_i32 s50, 0, 0x1c000
	v_add_u32_e32 v142, s49, v229
	v_add_u32_e32 v158, s50, v229
	ds_read_b128 v[130:133], v142
	ds_read_b128 v[134:137], v142 offset:1024
	ds_read_b128 v[138:141], v142 offset:2048
	ds_read_b128 v[142:145], v142 offset:3072
	ds_read_b128 v[146:149], v158
	ds_read_b128 v[150:153], v158 offset:1024
	ds_read_b128 v[154:157], v158 offset:2048
	ds_read_b128 v[158:161], v158 offset:3072
	s_add_u32 s22, s22, 0x80000
	s_addc_u32 s23, s23, 0
	s_mov_b32 m0, s36
	ds_read_b128 v[162:165], v230 offset:32768
	ds_read_b128 v[166:169], v230 offset:33792
	ds_read_b128 v[170:173], v230 offset:34816
	ds_read_b128 v[174:177], v230 offset:35840
	ds_read_b128 v[178:181], v230 offset:36864
	ds_read_b128 v[182:185], v230 offset:37888
	ds_read_b128 v[186:189], v230 offset:38912
	ds_read_b128 v[190:193], v230 offset:39936
	global_load_lds_dwordx4 v198, s[22:23]
	s_mov_b32 m0, s37
	s_nop 0
	global_load_lds_dwordx4 v200, s[22:23]
	s_waitcnt vmcnt(8)
	s_waitcnt lgkmcnt(0)
	s_barrier
	v_mfma_f32_16x16x32_bf16 v[126:129], v[130:133], v[162:165], v[126:129]
	v_mfma_f32_16x16x32_bf16 v[122:125], v[138:141], v[162:165], v[122:125]
	v_mfma_f32_16x16x32_bf16 v[110:113], v[130:133], v[170:173], v[110:113]
	v_mfma_f32_16x16x32_bf16 v[106:109], v[138:141], v[170:173], v[106:109]
	v_mfma_f32_16x16x32_bf16 v[94:97], v[130:133], v[178:181], v[94:97]
	v_mfma_f32_16x16x32_bf16 v[90:93], v[138:141], v[178:181], v[90:93]
	v_mfma_f32_16x16x32_bf16 v[78:81], v[130:133], v[186:189], v[78:81]
	v_mfma_f32_16x16x32_bf16 v[74:77], v[138:141], v[186:189], v[74:77]
	v_mfma_f32_16x16x32_bf16 v[126:129], v[134:137], v[166:169], v[126:129]
	v_mfma_f32_16x16x32_bf16 v[122:125], v[142:145], v[166:169], v[122:125]
	v_mfma_f32_16x16x32_bf16 v[110:113], v[134:137], v[174:177], v[110:113]
	v_mfma_f32_16x16x32_bf16 v[106:109], v[142:145], v[174:177], v[106:109]
	v_mfma_f32_16x16x32_bf16 v[94:97], v[134:137], v[182:185], v[94:97]
	v_mfma_f32_16x16x32_bf16 v[90:93], v[142:145], v[182:185], v[90:93]
	v_mfma_f32_16x16x32_bf16 v[78:81], v[134:137], v[190:193], v[78:81]
	v_mfma_f32_16x16x32_bf16 v[74:77], v[142:145], v[190:193], v[74:77]
	v_mfma_f32_16x16x32_bf16 v[118:121], v[146:149], v[162:165], v[118:121]
	v_mfma_f32_16x16x32_bf16 v[114:117], v[154:157], v[162:165], v[114:117]
	v_mfma_f32_16x16x32_bf16 v[102:105], v[146:149], v[170:173], v[102:105]
	v_mfma_f32_16x16x32_bf16 v[98:101], v[154:157], v[170:173], v[98:101]
	v_mfma_f32_16x16x32_bf16 v[86:89], v[146:149], v[178:181], v[86:89]
	v_mfma_f32_16x16x32_bf16 v[82:85], v[154:157], v[178:181], v[82:85]
	v_mfma_f32_16x16x32_bf16 v[70:73], v[146:149], v[186:189], v[70:73]
	v_mfma_f32_16x16x32_bf16 v[66:69], v[154:157], v[186:189], v[66:69]
	v_mfma_f32_16x16x32_bf16 v[118:121], v[150:153], v[166:169], v[118:121]
	v_mfma_f32_16x16x32_bf16 v[114:117], v[158:161], v[166:169], v[114:117]
	v_mfma_f32_16x16x32_bf16 v[102:105], v[150:153], v[174:177], v[102:105]
	v_mfma_f32_16x16x32_bf16 v[98:101], v[158:161], v[174:177], v[98:101]
	v_mfma_f32_16x16x32_bf16 v[86:89], v[150:153], v[182:185], v[86:89]
	v_mfma_f32_16x16x32_bf16 v[82:85], v[158:161], v[182:185], v[82:85]
	v_mfma_f32_16x16x32_bf16 v[70:73], v[150:153], v[190:193], v[70:73]
	v_mfma_f32_16x16x32_bf16 v[66:69], v[158:161], v[190:193], v[66:69]
	s_barrier
	s_add_u32 s98, s20, 0x80
	s_addc_u32 s99, s21, 0
	s_add_i32 s22, s49, s31
	s_mov_b32 m0, s22
	ds_read_b128 v[162:165], v230 offset:49152
	ds_read_b128 v[166:169], v230 offset:50176
	ds_read_b128 v[170:173], v230 offset:51200
	ds_read_b128 v[174:177], v230 offset:52224
	ds_read_b128 v[178:181], v230 offset:53248
	ds_read_b128 v[182:185], v230 offset:54272
	ds_read_b128 v[186:189], v230 offset:55296
	ds_read_b128 v[190:193], v230 offset:56320
	global_load_lds_dwordx4 v0, s[98:99]
	s_add_i32 m0, s22, 0x2000
	s_add_u32 s20, s20, 0x20080
	s_addc_u32 s21, s21, 0
	s_add_i32 s22, s50, s31
	global_load_lds_dwordx4 v202, s[98:99]
	s_mov_b32 m0, s22
	s_nop 0
	global_load_lds_dwordx4 v0, s[20:21]
	s_add_i32 m0, s22, 0x2000
	s_nop 0
	global_load_lds_dwordx4 v202, s[20:21]
	s_mov_b32 m0, s41
	s_nop 0
	global_load_lds_dwordx4 v198, s[100:101]
	s_mov_b32 m0, s42
	s_nop 0
	global_load_lds_dwordx4 v200, s[100:101]
	s_waitcnt vmcnt(8)
	s_waitcnt lgkmcnt(0)
	s_barrier
	v_mfma_f32_16x16x32_bf16 v[62:65], v[130:133], v[162:165], v[62:65]
	v_mfma_f32_16x16x32_bf16 v[58:61], v[138:141], v[162:165], v[58:61]
	v_mfma_f32_16x16x32_bf16 v[46:49], v[130:133], v[170:173], v[46:49]
	v_mfma_f32_16x16x32_bf16 v[42:45], v[138:141], v[170:173], v[42:45]
	v_mfma_f32_16x16x32_bf16 v[30:33], v[130:133], v[178:181], v[30:33]
	v_mfma_f32_16x16x32_bf16 v[26:29], v[138:141], v[178:181], v[26:29]
	v_mfma_f32_16x16x32_bf16 v[14:17], v[130:133], v[186:189], v[14:17]
	v_mfma_f32_16x16x32_bf16 v[10:13], v[138:141], v[186:189], v[10:13]
	v_mfma_f32_16x16x32_bf16 v[62:65], v[134:137], v[166:169], v[62:65]
	v_mfma_f32_16x16x32_bf16 v[58:61], v[142:145], v[166:169], v[58:61]
	v_mfma_f32_16x16x32_bf16 v[46:49], v[134:137], v[174:177], v[46:49]
	v_mfma_f32_16x16x32_bf16 v[42:45], v[142:145], v[174:177], v[42:45]
	v_mfma_f32_16x16x32_bf16 v[30:33], v[134:137], v[182:185], v[30:33]
	v_mfma_f32_16x16x32_bf16 v[26:29], v[142:145], v[182:185], v[26:29]
	v_mfma_f32_16x16x32_bf16 v[14:17], v[134:137], v[190:193], v[14:17]
	v_mfma_f32_16x16x32_bf16 v[10:13], v[142:145], v[190:193], v[10:13]
	v_mfma_f32_16x16x32_bf16 v[54:57], v[146:149], v[162:165], v[54:57]
	v_mfma_f32_16x16x32_bf16 v[50:53], v[154:157], v[162:165], v[50:53]
	v_mfma_f32_16x16x32_bf16 v[38:41], v[146:149], v[170:173], v[38:41]
	v_mfma_f32_16x16x32_bf16 v[34:37], v[154:157], v[170:173], v[34:37]
	v_mfma_f32_16x16x32_bf16 v[22:25], v[146:149], v[178:181], v[22:25]
	v_mfma_f32_16x16x32_bf16 v[18:21], v[154:157], v[178:181], v[18:21]
	v_mfma_f32_16x16x32_bf16 v[6:9], v[146:149], v[186:189], v[6:9]
	v_mfma_f32_16x16x32_bf16 v[2:5], v[154:157], v[186:189], v[2:5]
	v_mfma_f32_16x16x32_bf16 v[54:57], v[150:153], v[166:169], v[54:57]
	v_mfma_f32_16x16x32_bf16 v[50:53], v[158:161], v[166:169], v[50:53]
	v_mfma_f32_16x16x32_bf16 v[38:41], v[150:153], v[174:177], v[38:41]
	v_mfma_f32_16x16x32_bf16 v[34:37], v[158:161], v[174:177], v[34:37]
	v_mfma_f32_16x16x32_bf16 v[22:25], v[150:153], v[182:185], v[22:25]
	v_mfma_f32_16x16x32_bf16 v[18:21], v[158:161], v[182:185], v[18:21]
	v_mfma_f32_16x16x32_bf16 v[6:9], v[150:153], v[190:193], v[6:9]
	v_mfma_f32_16x16x32_bf16 v[2:5], v[158:161], v[190:193], v[2:5]
	s_barrier
; #define GAS __attribute__((address_space(1)))
; DI unsigned cvtpk(float lo, float hi) { unsigned r; asm volatile("v_cvt_pk_bf16_f32 %0, %1, %2" : "=v"(r) : "v"(lo), "v"(hi)); return r; }
;     DI void operator()(const f32x4 (&acc)[2][2][4][2], const Unit& u, int wr, int wc, int fr, int fq) const {
;         const int row0 = u.pm * BM + wr * 64 + fr, col0 = u.pn * BM + wc * 64 + 8 * fq;
;         const size_t hbase = (size_t)u.pn * ((size_t)M * 256) + wc * 64 + 8 * fq;
;         u32x4 H[2][4][2];
; #pragma unroll
;         for (int ai = 0; ai < 2; ++ai)
; #pragma unroll
;             for (int m = 0; m < 4; ++m)
; #pragma unroll
;                 for (int bj = 0; bj < 2; ++bj) H[ai][m][bj] = *(const GAS u32x4*)(hi + hbase + (size_t)(row0 + ai * HALF + m * 16) * 256 + bj * 32);
;         asm volatile("" ::: "memory");
; #pragma unroll
;         for (int ai = 0; ai < 2; ++ai) {
; #pragma unroll
;             for (int m = 0; m < 4; ++m) {
;                 const int r = row0 + ai * HALF + m * 16; const size_t off = (size_t)r * DM + col0; float ss = 0.f;
; #pragma unroll
;                 for (int bj = 0; bj < 2; ++bj) {
;                     const u32x4 h = H[ai][m][bj];
;                     const f32x4 a0 = acc[ai][bj][m][0], a1 = acc[ai][bj][m][1];
;                     float v[8];
;                     v[0] = bflo(h.x) + a0[0] * scale; v[1] = bfhi(h.x) + a0[1] * scale;
;                     v[2] = bflo(h.y) + a0[2] * scale; v[3] = bfhi(h.y) + a0[3] * scale;
;                     v[4] = bflo(h.z) + a1[0] * scale; v[5] = bfhi(h.z) + a1[1] * scale;
;                     v[6] = bflo(h.w) + a1[2] * scale; v[7] = bfhi(h.w) + a1[3] * scale;
; #pragma unroll
;                     for (int e = 0; e < 8; ++e) ss += v[e] * v[e];
;                     u32x4 nh;
;                     nh.x = cvtpk(v[0], v[1]); nh.y = cvtpk(v[2], v[3]); nh.z = cvtpk(v[4], v[5]); nh.w = cvtpk(v[6], v[7]);
;                     *(GAS u32x4*)(hi + hbase + (size_t)r * 256 + bj * 32) = nh;
;                     if (out) { *(GAS f32x4*)(out + off + bj * 32) = (f32x4){v[0], v[1], v[2], v[3]}; *(GAS f32x4*)(out + off + bj * 32 + 4) = (f32x4){v[4], v[5], v[6], v[7]}; }
;                 }
;                 ss = sum_xor32(sum_xor16(ss));
;                 if (fq == 0) ((GAS float*)rowss)[(size_t)(u.pn * 4 + wc) * M + r] = ss;
	s_add_i32 s48, s48, 2
	s_add_u32 s46, s46, 0x100
	s_addc_u32 s47, s47, 0
	s_add_u32 s18, s18, 0x100
	s_addc_u32 s19, s19, 0
	s_cmp_gt_u32 s48, 29
	s_cbranch_scc0 .LBB0_1021
	v_lshl_add_u32 v210, s16, 8, v228
	s_ashr_i32 s15, s14, 31
	s_lshl_b64 s[16:17], s[14:15], 23
	v_ashrrev_i32_e32 v211, 31, v210
	v_lshl_add_u64 v[130:131], v[204:205], 0, s[16:17]
	v_lshlrev_b64 v[132:133], 9, v[210:211]
	v_lshl_add_u64 v[226:227], v[130:131], 0, v[132:133]
	global_load_dwordx4 v[190:193], v[226:227], off
	global_load_dwordx4 v[186:189], v[226:227], off offset:64
	v_or_b32_e32 v132, 16, v210
	v_ashrrev_i32_e32 v133, 31, v132
	v_lshlrev_b64 v[132:133], 9, v[132:133]
	v_lshl_add_u64 v[224:225], v[130:131], 0, v[132:133]
	v_or_b32_e32 v132, 32, v210
	v_ashrrev_i32_e32 v133, 31, v132
	v_lshlrev_b64 v[132:133], 9, v[132:133]
	v_lshl_add_u64 v[222:223], v[130:131], 0, v[132:133]
	v_or_b32_e32 v132, 48, v210
	v_ashrrev_i32_e32 v133, 31, v132
	v_lshlrev_b64 v[132:133], 9, v[132:133]
	s_mov_b32 s3, 0x10000
	v_lshl_add_u64 v[220:221], v[130:131], 0, v[132:133]
	v_add_co_u32_e32 v130, vcc, s3, v226
	s_mov_b64 s[16:17], 0x10000
	s_nop 0
	v_addc_co_u32_e32 v131, vcc, 0, v227, vcc
	s_mov_b32 s3, 0x12000
	global_load_dwordx4 v[182:185], v[224:225], off
	global_load_dwordx4 v[178:181], v[224:225], off offset:64
	global_load_dwordx4 v[174:177], v[222:223], off
	global_load_dwordx4 v[170:173], v[222:223], off offset:64
	global_load_dwordx4 v[166:169], v[220:221], off
	global_load_dwordx4 v[162:165], v[220:221], off offset:64
	v_lshl_add_u64 v[218:219], v[226:227], 0, s[16:17]
	global_load_dwordx4 v[158:161], v[130:131], off
	global_load_dwordx4 v[150:153], v[218:219], off offset:64
	v_add_co_u32_e32 v130, vcc, s3, v226
	s_mov_b64 s[16:17], 0x12000
	s_nop 0
	v_addc_co_u32_e32 v131, vcc, 0, v227, vcc
	s_mov_b32 s3, 0x14000
	v_lshl_add_u64 v[216:217], v[226:227], 0, s[16:17]
	global_load_dwordx4 v[154:157], v[130:131], off
	global_load_dwordx4 v[146:149], v[216:217], off offset:64
	v_add_co_u32_e32 v130, vcc, s3, v226
	s_mov_b64 s[16:17], 0x14000
	s_nop 0
	v_addc_co_u32_e32 v131, vcc, 0, v227, vcc
	s_mov_b32 s3, 0x16000
	v_lshl_add_u64 v[214:215], v[226:227], 0, s[16:17]
	global_load_dwordx4 v[142:145], v[130:131], off
	global_load_dwordx4 v[134:137], v[214:215], off offset:64
	v_add_co_u32_e32 v130, vcc, s3, v226
	s_mov_b64 s[16:17], 0x16000
	s_nop 0
	v_addc_co_u32_e32 v131, vcc, 0, v227, vcc
	v_lshl_add_u64 v[212:213], v[226:227], 0, s[16:17]
	global_load_dwordx4 v[138:141], v[130:131], off
	s_nop 0
	global_load_dwordx4 v[130:133], v[212:213], off offset:64
	s_lshl_b32 s3, s14, 2
	s_or_b32 s14, s3, s40
	s_ashr_i32 s15, s14, 31
	s_lshl_b64 s[14:15], s[14:15], 16
	s_waitcnt vmcnt(0)
	v_lshlrev_b32_e32 v194, 16, v190
	v_and_b32_e32 v190, 0xffff0000, v190
	v_add_f32_e32 v127, v127, v190
	v_lshlrev_b32_e32 v190, 16, v191
	v_add_f32_e32 v128, v128, v190
	v_and_b32_e32 v190, 0xffff0000, v191
	v_add_f32_e32 v129, v129, v190
	v_lshlrev_b32_e32 v190, 16, v192
	v_add_f32_e32 v190, v122, v190
	v_and_b32_e32 v122, 0xffff0000, v192
	v_add_f32_e32 v191, v123, v122
	v_lshlrev_b32_e32 v122, 16, v193
	v_add_f32_e32 v126, v126, v194
	v_add_f32_e32 v192, v124, v122
	v_and_b32_e32 v122, 0xffff0000, v193
	v_mul_f32_e32 v193, v127, v127
	v_fmac_f32_e32 v193, v126, v126
	v_fmac_f32_e32 v193, v128, v128
	v_fmac_f32_e32 v193, v129, v129
	v_fmac_f32_e32 v193, v190, v190
	v_fmac_f32_e32 v193, v191, v191
	v_add_f32_e32 v125, v125, v122
	v_fmac_f32_e32 v193, v192, v192
	v_cvt_pk_bf16_f32 v122, v126, v127
	v_fmac_f32_e32 v193, v125, v125
	v_cvt_pk_bf16_f32 v123, v128, v129
	v_cvt_pk_bf16_f32 v124, v190, v191
	v_cvt_pk_bf16_f32 v125, v192, v125
	global_store_dwordx4 v[226:227], v[122:125], off
	s_nop 1
	v_lshlrev_b32_e32 v122, 16, v186
	v_add_f32_e32 v118, v118, v122
	v_and_b32_e32 v122, 0xffff0000, v186
	v_add_f32_e32 v119, v119, v122
	v_lshlrev_b32_e32 v122, 16, v187
	v_fmac_f32_e32 v193, v118, v118
	v_add_f32_e32 v120, v120, v122
	v_and_b32_e32 v122, 0xffff0000, v187
	v_fmac_f32_e32 v193, v119, v119
	v_add_f32_e32 v121, v121, v122
	v_lshlrev_b32_e32 v122, 16, v188
	v_fmac_f32_e32 v193, v120, v120
	v_add_f32_e32 v122, v114, v122
	v_and_b32_e32 v114, 0xffff0000, v188
	v_fmac_f32_e32 v193, v121, v121
	v_add_f32_e32 v123, v115, v114
	v_lshlrev_b32_e32 v114, 16, v189
	v_fmac_f32_e32 v193, v122, v122
	v_add_f32_e32 v124, v116, v114
	v_and_b32_e32 v114, 0xffff0000, v189
	v_fmac_f32_e32 v193, v123, v123
	v_add_f32_e32 v117, v117, v114
	v_fmac_f32_e32 v193, v124, v124
	v_fmac_f32_e32 v193, v117, v117
	v_cvt_pk_bf16_f32 v114, v118, v119
	v_cvt_pk_bf16_f32 v115, v120, v121
	v_cvt_pk_bf16_f32 v116, v122, v123
	v_cvt_pk_bf16_f32 v117, v124, v117
	global_store_dwordx4 v[226:227], v[114:117], off offset:64
	s_nop 1
	v_mov_b32_e32 v114, v193
	s_nop 1
	v_permlane16_swap_b32_e32 v193, v114
	v_add_f32_e32 v114, v193, v114
	v_mov_b32_e32 v115, v114
	s_nop 1
	v_permlane32_swap_b32_e32 v114, v115
	s_and_saveexec_b64 s[16:17], s[4:5]
	s_cbranch_execz .LBB0_1024
	s_add_u32 s18, s38, s14
	s_addc_u32 s19, s39, s15
	v_lshl_add_u64 v[116:117], v[210:211], 2, s[18:19]
	v_add_f32_e32 v114, v114, v115
	global_store_dword v[116:117], v114, off
